# K-loops: removed the redundant mid-block s_setprio 0 / s_setprio 1 pair between the two 16-MFMA groups (28 sites, priority stays raised across the 32-MFMA block), on top of v12
# baseline (speedup 1.0000x reference)
.LBB0_131:
	s_add_u32 s60, s57, 0xffffff80
	s_addc_u32 s61, s58, -1
	s_cmp_eq_u32 s59, 60
	s_cselect_b32 s36, s17, s57
	s_cselect_b32 s37, s7, s58
	s_cselect_b32 s39, s21, s56
	s_cselect_b32 s38, s33, s55
	s_add_u32 s30, s36, 0x80
	s_addc_u32 s31, s37, 0
	s_add_u32 s34, s38, 0x80
	s_addc_u32 s35, s39, 0
	s_add_i32 s62, 0, 0x10000
	s_add_i32 s63, 0, 0x14000
	v_add_u32_e32 v152, s62, v1
	v_add_u32_e32 v168, s63, v1
	ds_read_b128 v[140:143], v152
	ds_read_b128 v[144:147], v152 offset:1024
	ds_read_b128 v[148:151], v152 offset:2048
	ds_read_b128 v[152:155], v152 offset:3072
	ds_read_b128 v[156:159], v168
	ds_read_b128 v[160:163], v168 offset:1024
	ds_read_b128 v[164:167], v168 offset:2048
	ds_read_b128 v[168:171], v168 offset:3072
	s_add_u32 s60, s60, 0x100000
	s_addc_u32 s61, s61, 0
	v_lshl_add_u64 v[204:205], s[60:61], 0, v[2:3]
	s_add_i32 m0, s29, 0xc000
	ds_read_b128 v[172:175], v5
	ds_read_b128 v[176:179], v5 offset:1024
	ds_read_b128 v[180:183], v5 offset:2048
	ds_read_b128 v[184:187], v5 offset:3072
	ds_read_b128 v[188:191], v5 offset:4096
	ds_read_b128 v[192:195], v5 offset:5120
	ds_read_b128 v[196:199], v5 offset:6144
	ds_read_b128 v[200:203], v5 offset:7168
	global_load_lds_dwordx4 v[204:205], off
	v_lshl_add_u64 v[204:205], s[60:61], 0, v[136:137]
	s_add_i32 m0, s29, 0xe000
	s_nop 0
	global_load_lds_dwordx4 v[204:205], off
	s_waitcnt vmcnt(8)
	s_waitcnt lgkmcnt(0)
	s_barrier
	s_setprio 1
	s_waitcnt lgkmcnt(0)
	v_mfma_f32_16x16x32_bf16 v[130:133], v[140:143], v[172:175], v[130:133]
	v_mfma_f32_16x16x32_bf16 v[126:129], v[148:151], v[172:175], v[126:129]
	v_mfma_f32_16x16x32_bf16 v[114:117], v[140:143], v[180:183], v[114:117]
	v_mfma_f32_16x16x32_bf16 v[110:113], v[148:151], v[180:183], v[110:113]
	v_mfma_f32_16x16x32_bf16 v[98:101], v[140:143], v[188:191], v[98:101]
	v_mfma_f32_16x16x32_bf16 v[94:97], v[148:151], v[188:191], v[94:97]
	v_mfma_f32_16x16x32_bf16 v[82:85], v[140:143], v[196:199], v[82:85]
	v_mfma_f32_16x16x32_bf16 v[78:81], v[148:151], v[196:199], v[78:81]
	v_mfma_f32_16x16x32_bf16 v[130:133], v[144:147], v[176:179], v[130:133]
	v_mfma_f32_16x16x32_bf16 v[126:129], v[152:155], v[176:179], v[126:129]
	v_mfma_f32_16x16x32_bf16 v[114:117], v[144:147], v[184:187], v[114:117]
	v_mfma_f32_16x16x32_bf16 v[110:113], v[152:155], v[184:187], v[110:113]
	v_mfma_f32_16x16x32_bf16 v[98:101], v[144:147], v[192:195], v[98:101]
	v_mfma_f32_16x16x32_bf16 v[94:97], v[152:155], v[192:195], v[94:97]
	v_mfma_f32_16x16x32_bf16 v[82:85], v[144:147], v[200:203], v[82:85]
	v_mfma_f32_16x16x32_bf16 v[78:81], v[152:155], v[200:203], v[78:81]
	v_mfma_f32_16x16x32_bf16 v[122:125], v[156:159], v[172:175], v[122:125]
	v_mfma_f32_16x16x32_bf16 v[118:121], v[164:167], v[172:175], v[118:121]
	v_mfma_f32_16x16x32_bf16 v[106:109], v[156:159], v[180:183], v[106:109]
	v_mfma_f32_16x16x32_bf16 v[102:105], v[164:167], v[180:183], v[102:105]
	v_mfma_f32_16x16x32_bf16 v[90:93], v[156:159], v[188:191], v[90:93]
	v_mfma_f32_16x16x32_bf16 v[86:89], v[164:167], v[188:191], v[86:89]
	v_mfma_f32_16x16x32_bf16 v[74:77], v[156:159], v[196:199], v[74:77]
	v_mfma_f32_16x16x32_bf16 v[70:73], v[164:167], v[196:199], v[70:73]
	v_mfma_f32_16x16x32_bf16 v[122:125], v[160:163], v[176:179], v[122:125]
	v_mfma_f32_16x16x32_bf16 v[118:121], v[168:171], v[176:179], v[118:121]
	v_mfma_f32_16x16x32_bf16 v[106:109], v[160:163], v[184:187], v[106:109]
	v_mfma_f32_16x16x32_bf16 v[102:105], v[168:171], v[184:187], v[102:105]
	v_mfma_f32_16x16x32_bf16 v[90:93], v[160:163], v[192:195], v[90:93]
	v_mfma_f32_16x16x32_bf16 v[86:89], v[168:171], v[192:195], v[86:89]
	v_mfma_f32_16x16x32_bf16 v[74:77], v[160:163], v[200:203], v[74:77]
	v_mfma_f32_16x16x32_bf16 v[70:73], v[168:171], v[200:203], v[70:73]
	s_setprio 0
	s_barrier
	s_add_i32 s60, s62, s42
	v_lshl_add_u64 v[204:205], s[38:39], 0, v[134:135]
	s_mov_b32 m0, s60
	ds_read_b128 v[172:175], v5 offset:16384
	ds_read_b128 v[176:179], v5 offset:17408
	ds_read_b128 v[180:183], v5 offset:18432
	ds_read_b128 v[184:187], v5 offset:19456
	ds_read_b128 v[188:191], v5 offset:20480
	ds_read_b128 v[192:195], v5 offset:21504
	ds_read_b128 v[196:199], v5 offset:22528
	ds_read_b128 v[200:203], v5 offset:23552
	global_load_lds_dwordx4 v[204:205], off
	s_add_i32 m0, s60, 0x2000
	v_lshl_add_u64 v[204:205], s[38:39], 0, v[138:139]
	s_add_u32 s38, s38, 0x100000
	s_addc_u32 s39, s39, 0
	s_add_i32 s60, s63, s42
	global_load_lds_dwordx4 v[204:205], off
	v_lshl_add_u64 v[204:205], s[38:39], 0, v[134:135]
	s_mov_b32 m0, s60
	s_nop 0
	global_load_lds_dwordx4 v[204:205], off
	v_lshl_add_u64 v[204:205], s[38:39], 0, v[138:139]
	s_add_i32 m0, s60, 0x2000
	s_nop 0
	global_load_lds_dwordx4 v[204:205], off
	v_lshl_add_u64 v[204:205], s[36:37], 0, v[2:3]
	s_mov_b32 m0, s29
	s_nop 0
	global_load_lds_dwordx4 v[204:205], off
	v_lshl_add_u64 v[204:205], s[36:37], 0, v[136:137]
	s_mov_b32 m0, s43
	s_nop 0
	global_load_lds_dwordx4 v[204:205], off
	s_waitcnt vmcnt(8)
	s_waitcnt lgkmcnt(0)
	s_barrier
	s_setprio 1
	s_waitcnt lgkmcnt(0)
	v_mfma_f32_16x16x32_bf16 v[66:69], v[140:143], v[172:175], v[66:69]
	v_mfma_f32_16x16x32_bf16 v[62:65], v[148:151], v[172:175], v[62:65]
	v_mfma_f32_16x16x32_bf16 v[50:53], v[140:143], v[180:183], v[50:53]
	v_mfma_f32_16x16x32_bf16 v[46:49], v[148:151], v[180:183], v[46:49]
	v_mfma_f32_16x16x32_bf16 v[34:37], v[140:143], v[188:191], v[34:37]
	v_mfma_f32_16x16x32_bf16 v[30:33], v[148:151], v[188:191], v[30:33]
	v_mfma_f32_16x16x32_bf16 v[18:21], v[140:143], v[196:199], v[18:21]
	v_mfma_f32_16x16x32_bf16 v[14:17], v[148:151], v[196:199], v[14:17]
	v_mfma_f32_16x16x32_bf16 v[66:69], v[144:147], v[176:179], v[66:69]
	v_mfma_f32_16x16x32_bf16 v[62:65], v[152:155], v[176:179], v[62:65]
	v_mfma_f32_16x16x32_bf16 v[50:53], v[144:147], v[184:187], v[50:53]
	v_mfma_f32_16x16x32_bf16 v[46:49], v[152:155], v[184:187], v[46:49]
	v_mfma_f32_16x16x32_bf16 v[34:37], v[144:147], v[192:195], v[34:37]
	v_mfma_f32_16x16x32_bf16 v[30:33], v[152:155], v[192:195], v[30:33]
	v_mfma_f32_16x16x32_bf16 v[18:21], v[144:147], v[200:203], v[18:21]
	v_mfma_f32_16x16x32_bf16 v[14:17], v[152:155], v[200:203], v[14:17]
	v_mfma_f32_16x16x32_bf16 v[58:61], v[156:159], v[172:175], v[58:61]
	v_mfma_f32_16x16x32_bf16 v[54:57], v[164:167], v[172:175], v[54:57]
	v_mfma_f32_16x16x32_bf16 v[42:45], v[156:159], v[180:183], v[42:45]
	v_mfma_f32_16x16x32_bf16 v[38:41], v[164:167], v[180:183], v[38:41]
	v_mfma_f32_16x16x32_bf16 v[26:29], v[156:159], v[188:191], v[26:29]
	v_mfma_f32_16x16x32_bf16 v[22:25], v[164:167], v[188:191], v[22:25]
	v_mfma_f32_16x16x32_bf16 v[10:13], v[156:159], v[196:199], v[10:13]
	v_mfma_f32_16x16x32_bf16 v[6:9], v[164:167], v[196:199], v[6:9]
	v_mfma_f32_16x16x32_bf16 v[58:61], v[160:163], v[176:179], v[58:61]
	v_mfma_f32_16x16x32_bf16 v[54:57], v[168:171], v[176:179], v[54:57]
	v_mfma_f32_16x16x32_bf16 v[42:45], v[160:163], v[184:187], v[42:45]
	v_mfma_f32_16x16x32_bf16 v[38:41], v[168:171], v[184:187], v[38:41]
	v_mfma_f32_16x16x32_bf16 v[26:29], v[160:163], v[192:195], v[26:29]
	v_mfma_f32_16x16x32_bf16 v[22:25], v[168:171], v[192:195], v[22:25]
	v_mfma_f32_16x16x32_bf16 v[10:13], v[160:163], v[200:203], v[10:13]
	v_mfma_f32_16x16x32_bf16 v[6:9], v[168:171], v[200:203], v[6:9]
	s_setprio 0
	s_barrier
	s_add_i32 s38, 0, 0x18000
	s_add_i32 s39, 0, 0x1c000
	v_add_u32_e32 v152, s38, v1
	v_add_u32_e32 v168, s39, v1
	ds_read_b128 v[140:143], v152
	ds_read_b128 v[144:147], v152 offset:1024
	ds_read_b128 v[148:151], v152 offset:2048
	ds_read_b128 v[152:155], v152 offset:3072
	ds_read_b128 v[156:159], v168
	ds_read_b128 v[160:163], v168 offset:1024
	ds_read_b128 v[164:167], v168 offset:2048
	ds_read_b128 v[168:171], v168 offset:3072
	s_add_u32 s36, s36, 0x100000
	s_addc_u32 s37, s37, 0
	s_mov_b32 m0, s48
	v_lshl_add_u64 v[204:205], s[36:37], 0, v[2:3]
	ds_read_b128 v[172:175], v5 offset:32768
	ds_read_b128 v[176:179], v5 offset:33792
	ds_read_b128 v[180:183], v5 offset:34816
	ds_read_b128 v[184:187], v5 offset:35840
	ds_read_b128 v[188:191], v5 offset:36864
	ds_read_b128 v[192:195], v5 offset:37888
	ds_read_b128 v[196:199], v5 offset:38912
	ds_read_b128 v[200:203], v5 offset:39936
	global_load_lds_dwordx4 v[204:205], off
	v_lshl_add_u64 v[204:205], s[36:37], 0, v[136:137]
	s_mov_b32 m0, s49
	s_nop 0
	global_load_lds_dwordx4 v[204:205], off
	s_waitcnt vmcnt(8)
	s_waitcnt lgkmcnt(0)
	s_barrier
	s_setprio 1
	s_waitcnt lgkmcnt(0)
	v_mfma_f32_16x16x32_bf16 v[130:133], v[140:143], v[172:175], v[130:133]
	v_mfma_f32_16x16x32_bf16 v[126:129], v[148:151], v[172:175], v[126:129]
	v_mfma_f32_16x16x32_bf16 v[114:117], v[140:143], v[180:183], v[114:117]
	v_mfma_f32_16x16x32_bf16 v[110:113], v[148:151], v[180:183], v[110:113]
	v_mfma_f32_16x16x32_bf16 v[98:101], v[140:143], v[188:191], v[98:101]
	v_mfma_f32_16x16x32_bf16 v[94:97], v[148:151], v[188:191], v[94:97]
	v_mfma_f32_16x16x32_bf16 v[82:85], v[140:143], v[196:199], v[82:85]
	v_mfma_f32_16x16x32_bf16 v[78:81], v[148:151], v[196:199], v[78:81]
	v_mfma_f32_16x16x32_bf16 v[130:133], v[144:147], v[176:179], v[130:133]
	v_mfma_f32_16x16x32_bf16 v[126:129], v[152:155], v[176:179], v[126:129]
	v_mfma_f32_16x16x32_bf16 v[114:117], v[144:147], v[184:187], v[114:117]
	v_mfma_f32_16x16x32_bf16 v[110:113], v[152:155], v[184:187], v[110:113]
	v_mfma_f32_16x16x32_bf16 v[98:101], v[144:147], v[192:195], v[98:101]
	v_mfma_f32_16x16x32_bf16 v[94:97], v[152:155], v[192:195], v[94:97]
	v_mfma_f32_16x16x32_bf16 v[82:85], v[144:147], v[200:203], v[82:85]
	v_mfma_f32_16x16x32_bf16 v[78:81], v[152:155], v[200:203], v[78:81]
	v_mfma_f32_16x16x32_bf16 v[122:125], v[156:159], v[172:175], v[122:125]
	v_mfma_f32_16x16x32_bf16 v[118:121], v[164:167], v[172:175], v[118:121]
	v_mfma_f32_16x16x32_bf16 v[106:109], v[156:159], v[180:183], v[106:109]
	v_mfma_f32_16x16x32_bf16 v[102:105], v[164:167], v[180:183], v[102:105]
	v_mfma_f32_16x16x32_bf16 v[90:93], v[156:159], v[188:191], v[90:93]
	v_mfma_f32_16x16x32_bf16 v[86:89], v[164:167], v[188:191], v[86:89]
	v_mfma_f32_16x16x32_bf16 v[74:77], v[156:159], v[196:199], v[74:77]
	v_mfma_f32_16x16x32_bf16 v[70:73], v[164:167], v[196:199], v[70:73]
	v_mfma_f32_16x16x32_bf16 v[122:125], v[160:163], v[176:179], v[122:125]
	v_mfma_f32_16x16x32_bf16 v[118:121], v[168:171], v[176:179], v[118:121]
	v_mfma_f32_16x16x32_bf16 v[106:109], v[160:163], v[184:187], v[106:109]
	v_mfma_f32_16x16x32_bf16 v[102:105], v[168:171], v[184:187], v[102:105]
	v_mfma_f32_16x16x32_bf16 v[90:93], v[160:163], v[192:195], v[90:93]
	v_mfma_f32_16x16x32_bf16 v[86:89], v[168:171], v[192:195], v[86:89]
	v_mfma_f32_16x16x32_bf16 v[74:77], v[160:163], v[200:203], v[74:77]
	v_mfma_f32_16x16x32_bf16 v[70:73], v[168:171], v[200:203], v[70:73]
	s_setprio 0
	s_barrier
	s_add_i32 s36, s38, s42
	v_lshl_add_u64 v[204:205], s[34:35], 0, v[134:135]
	s_mov_b32 m0, s36
	ds_read_b128 v[172:175], v5 offset:49152
	ds_read_b128 v[176:179], v5 offset:50176
	ds_read_b128 v[180:183], v5 offset:51200
	ds_read_b128 v[184:187], v5 offset:52224
	ds_read_b128 v[188:191], v5 offset:53248
	ds_read_b128 v[192:195], v5 offset:54272
	ds_read_b128 v[196:199], v5 offset:55296
	ds_read_b128 v[200:203], v5 offset:56320
	global_load_lds_dwordx4 v[204:205], off
	s_add_i32 m0, s36, 0x2000
	v_lshl_add_u64 v[204:205], s[34:35], 0, v[138:139]
	s_add_u32 s34, s34, 0x100000
	s_addc_u32 s35, s35, 0
	s_add_i32 s36, s39, s42
	global_load_lds_dwordx4 v[204:205], off
	v_lshl_add_u64 v[204:205], s[34:35], 0, v[134:135]
	s_mov_b32 m0, s36
	s_nop 0
	global_load_lds_dwordx4 v[204:205], off
	v_lshl_add_u64 v[204:205], s[34:35], 0, v[138:139]
	s_add_i32 m0, s36, 0x2000
	s_nop 0
	global_load_lds_dwordx4 v[204:205], off
	v_lshl_add_u64 v[204:205], s[30:31], 0, v[2:3]
	s_mov_b32 m0, s52
	s_nop 0
	global_load_lds_dwordx4 v[204:205], off
	v_lshl_add_u64 v[204:205], s[30:31], 0, v[136:137]
	s_mov_b32 m0, s53
	s_nop 0
	global_load_lds_dwordx4 v[204:205], off
	s_waitcnt vmcnt(8)
	s_waitcnt lgkmcnt(0)
	s_barrier
	s_setprio 1
	s_waitcnt lgkmcnt(0)
	v_mfma_f32_16x16x32_bf16 v[66:69], v[140:143], v[172:175], v[66:69]
	v_mfma_f32_16x16x32_bf16 v[62:65], v[148:151], v[172:175], v[62:65]
	v_mfma_f32_16x16x32_bf16 v[50:53], v[140:143], v[180:183], v[50:53]
	v_mfma_f32_16x16x32_bf16 v[46:49], v[148:151], v[180:183], v[46:49]
	v_mfma_f32_16x16x32_bf16 v[34:37], v[140:143], v[188:191], v[34:37]
	v_mfma_f32_16x16x32_bf16 v[30:33], v[148:151], v[188:191], v[30:33]
	v_mfma_f32_16x16x32_bf16 v[18:21], v[140:143], v[196:199], v[18:21]
	v_mfma_f32_16x16x32_bf16 v[14:17], v[148:151], v[196:199], v[14:17]
	v_mfma_f32_16x16x32_bf16 v[66:69], v[144:147], v[176:179], v[66:69]
	v_mfma_f32_16x16x32_bf16 v[62:65], v[152:155], v[176:179], v[62:65]
	v_mfma_f32_16x16x32_bf16 v[50:53], v[144:147], v[184:187], v[50:53]
	v_mfma_f32_16x16x32_bf16 v[46:49], v[152:155], v[184:187], v[46:49]
	v_mfma_f32_16x16x32_bf16 v[34:37], v[144:147], v[192:195], v[34:37]
	v_mfma_f32_16x16x32_bf16 v[30:33], v[152:155], v[192:195], v[30:33]
	v_mfma_f32_16x16x32_bf16 v[18:21], v[144:147], v[200:203], v[18:21]
	v_mfma_f32_16x16x32_bf16 v[14:17], v[152:155], v[200:203], v[14:17]
	v_mfma_f32_16x16x32_bf16 v[58:61], v[156:159], v[172:175], v[58:61]
	v_mfma_f32_16x16x32_bf16 v[54:57], v[164:167], v[172:175], v[54:57]
	v_mfma_f32_16x16x32_bf16 v[42:45], v[156:159], v[180:183], v[42:45]
	v_mfma_f32_16x16x32_bf16 v[38:41], v[164:167], v[180:183], v[38:41]
	v_mfma_f32_16x16x32_bf16 v[26:29], v[156:159], v[188:191], v[26:29]
	v_mfma_f32_16x16x32_bf16 v[22:25], v[164:167], v[188:191], v[22:25]
	v_mfma_f32_16x16x32_bf16 v[10:13], v[156:159], v[196:199], v[10:13]
	v_mfma_f32_16x16x32_bf16 v[6:9], v[164:167], v[196:199], v[6:9]
	v_mfma_f32_16x16x32_bf16 v[58:61], v[160:163], v[176:179], v[58:61]
	v_mfma_f32_16x16x32_bf16 v[54:57], v[168:171], v[176:179], v[54:57]
	v_mfma_f32_16x16x32_bf16 v[42:45], v[160:163], v[184:187], v[42:45]
	v_mfma_f32_16x16x32_bf16 v[38:41], v[168:171], v[184:187], v[38:41]
	v_mfma_f32_16x16x32_bf16 v[26:29], v[160:163], v[192:195], v[26:29]
	v_mfma_f32_16x16x32_bf16 v[22:25], v[168:171], v[192:195], v[22:25]
	v_mfma_f32_16x16x32_bf16 v[10:13], v[160:163], v[200:203], v[10:13]
	v_mfma_f32_16x16x32_bf16 v[6:9], v[168:171], v[200:203], v[6:9]
	s_setprio 0
	s_barrier
	s_add_i32 s59, s59, 2
	s_add_u32 s55, s55, 0x100
	s_addc_u32 s56, s56, 0
	s_add_u32 s57, s57, 0x100
	s_addc_u32 s58, s58, 0
	s_cmp_gt_u32 s59, 61
	s_cbranch_scc0 .LBB0_131
	s_and_b64 vcc, exec, s[8:9]
	s_cbranch_vccz .LBB0_134
	s_barrier

.LBB0_251:
	s_add_u32 s56, s52, 0xffffff80
	s_addc_u32 s57, s53, -1
	s_cmp_eq_u32 s54, 60
	s_cselect_b32 s28, s2, s52
	s_cselect_b32 s29, s1, s53
	s_cselect_b32 s31, s11, s33
	s_cselect_b32 s30, s15, s19
	s_add_u32 s24, s28, 0x80
	s_addc_u32 s25, s29, 0
	s_add_u32 s26, s30, 0x80
	s_addc_u32 s27, s31, 0
	s_add_i32 s55, 0, 0x10000
	s_add_i32 s58, 0, 0x14000
	v_add_u32_e32 v152, s55, v1
	v_add_u32_e32 v168, s58, v1
	ds_read_b128 v[140:143], v152
	ds_read_b128 v[144:147], v152 offset:1024
	ds_read_b128 v[148:151], v152 offset:2048
	ds_read_b128 v[152:155], v152 offset:3072
	ds_read_b128 v[156:159], v168
	ds_read_b128 v[160:163], v168 offset:1024
	ds_read_b128 v[164:167], v168 offset:2048
	ds_read_b128 v[168:171], v168 offset:3072
	s_add_u32 s56, s56, 0x100000
	s_addc_u32 s57, s57, 0
	v_lshl_add_u64 v[204:205], s[56:57], 0, v[138:139]
	s_add_i32 m0, s23, 0xc000
	ds_read_b128 v[172:175], v5
	ds_read_b128 v[176:179], v5 offset:1024
	ds_read_b128 v[180:183], v5 offset:2048
	ds_read_b128 v[184:187], v5 offset:3072
	ds_read_b128 v[188:191], v5 offset:4096
	ds_read_b128 v[192:195], v5 offset:5120
	ds_read_b128 v[196:199], v5 offset:6144
	ds_read_b128 v[200:203], v5 offset:7168
	global_load_lds_dwordx4 v[204:205], off
	v_lshl_add_u64 v[204:205], s[56:57], 0, v[134:135]
	s_add_i32 m0, s23, 0xe000
	s_nop 0
	global_load_lds_dwordx4 v[204:205], off
	s_waitcnt vmcnt(8)
	s_waitcnt lgkmcnt(0)
	s_barrier
	s_setprio 1
	s_waitcnt lgkmcnt(0)
	v_mfma_f32_16x16x32_bf16 v[6:9], v[140:143], v[172:175], v[6:9]
	v_mfma_f32_16x16x32_bf16 v[10:13], v[148:151], v[172:175], v[10:13]
	v_mfma_f32_16x16x32_bf16 v[22:25], v[140:143], v[180:183], v[22:25]
	v_mfma_f32_16x16x32_bf16 v[26:29], v[148:151], v[180:183], v[26:29]
	v_mfma_f32_16x16x32_bf16 v[38:41], v[140:143], v[188:191], v[38:41]
	v_mfma_f32_16x16x32_bf16 v[42:45], v[148:151], v[188:191], v[42:45]
	v_mfma_f32_16x16x32_bf16 v[54:57], v[140:143], v[196:199], v[54:57]
	v_mfma_f32_16x16x32_bf16 v[58:61], v[148:151], v[196:199], v[58:61]
	v_mfma_f32_16x16x32_bf16 v[6:9], v[144:147], v[176:179], v[6:9]
	v_mfma_f32_16x16x32_bf16 v[10:13], v[152:155], v[176:179], v[10:13]
	v_mfma_f32_16x16x32_bf16 v[22:25], v[144:147], v[184:187], v[22:25]
	v_mfma_f32_16x16x32_bf16 v[26:29], v[152:155], v[184:187], v[26:29]
	v_mfma_f32_16x16x32_bf16 v[38:41], v[144:147], v[192:195], v[38:41]
	v_mfma_f32_16x16x32_bf16 v[42:45], v[152:155], v[192:195], v[42:45]
	v_mfma_f32_16x16x32_bf16 v[54:57], v[144:147], v[200:203], v[54:57]
	v_mfma_f32_16x16x32_bf16 v[58:61], v[152:155], v[200:203], v[58:61]
	v_mfma_f32_16x16x32_bf16 v[14:17], v[156:159], v[172:175], v[14:17]
	v_mfma_f32_16x16x32_bf16 v[18:21], v[164:167], v[172:175], v[18:21]
	v_mfma_f32_16x16x32_bf16 v[30:33], v[156:159], v[180:183], v[30:33]
	v_mfma_f32_16x16x32_bf16 v[34:37], v[164:167], v[180:183], v[34:37]
	v_mfma_f32_16x16x32_bf16 v[46:49], v[156:159], v[188:191], v[46:49]
	v_mfma_f32_16x16x32_bf16 v[50:53], v[164:167], v[188:191], v[50:53]
	v_mfma_f32_16x16x32_bf16 v[62:65], v[156:159], v[196:199], v[62:65]
	v_mfma_f32_16x16x32_bf16 v[66:69], v[164:167], v[196:199], v[66:69]
	v_mfma_f32_16x16x32_bf16 v[14:17], v[160:163], v[176:179], v[14:17]
	v_mfma_f32_16x16x32_bf16 v[18:21], v[168:171], v[176:179], v[18:21]
	v_mfma_f32_16x16x32_bf16 v[30:33], v[160:163], v[184:187], v[30:33]
	v_mfma_f32_16x16x32_bf16 v[34:37], v[168:171], v[184:187], v[34:37]
	v_mfma_f32_16x16x32_bf16 v[46:49], v[160:163], v[192:195], v[46:49]
	v_mfma_f32_16x16x32_bf16 v[50:53], v[168:171], v[192:195], v[50:53]
	v_mfma_f32_16x16x32_bf16 v[62:65], v[160:163], v[200:203], v[62:65]
	v_mfma_f32_16x16x32_bf16 v[66:69], v[168:171], v[200:203], v[66:69]
	s_setprio 0
	s_barrier
	s_add_i32 s55, s55, s37
	v_lshl_add_u64 v[204:205], s[30:31], 0, v[136:137]
	s_mov_b32 m0, s55
	ds_read_b128 v[172:175], v5 offset:16384
	ds_read_b128 v[176:179], v5 offset:17408
	ds_read_b128 v[180:183], v5 offset:18432
	ds_read_b128 v[184:187], v5 offset:19456
	ds_read_b128 v[188:191], v5 offset:20480
	ds_read_b128 v[192:195], v5 offset:21504
	ds_read_b128 v[196:199], v5 offset:22528
	ds_read_b128 v[200:203], v5 offset:23552
	global_load_lds_dwordx4 v[204:205], off
	s_add_i32 m0, s55, 0x2000
	v_lshl_add_u64 v[204:205], s[30:31], 0, v[2:3]
	s_add_u32 s30, s30, 0x100000
	s_addc_u32 s31, s31, 0
	s_add_i32 s55, s58, s37
	global_load_lds_dwordx4 v[204:205], off
	v_lshl_add_u64 v[204:205], s[30:31], 0, v[136:137]
	s_mov_b32 m0, s55
	s_nop 0
	global_load_lds_dwordx4 v[204:205], off
	v_lshl_add_u64 v[204:205], s[30:31], 0, v[2:3]
	s_add_i32 m0, s55, 0x2000
	s_nop 0
	global_load_lds_dwordx4 v[204:205], off
	v_lshl_add_u64 v[204:205], s[28:29], 0, v[138:139]
	s_mov_b32 m0, s23
	s_nop 0
	global_load_lds_dwordx4 v[204:205], off
	v_lshl_add_u64 v[204:205], s[28:29], 0, v[134:135]
	s_mov_b32 m0, s40
	s_nop 0
	global_load_lds_dwordx4 v[204:205], off
	s_waitcnt vmcnt(8)
	s_waitcnt lgkmcnt(0)
	s_barrier
	s_setprio 1
	s_waitcnt lgkmcnt(0)
	v_mfma_f32_16x16x32_bf16 v[70:73], v[140:143], v[172:175], v[70:73]
	v_mfma_f32_16x16x32_bf16 v[74:77], v[148:151], v[172:175], v[74:77]
	v_mfma_f32_16x16x32_bf16 v[86:89], v[140:143], v[180:183], v[86:89]
	v_mfma_f32_16x16x32_bf16 v[90:93], v[148:151], v[180:183], v[90:93]
	v_mfma_f32_16x16x32_bf16 v[102:105], v[140:143], v[188:191], v[102:105]
	v_mfma_f32_16x16x32_bf16 v[106:109], v[148:151], v[188:191], v[106:109]
	v_mfma_f32_16x16x32_bf16 v[130:133], v[140:143], v[196:199], v[130:133]
	v_mfma_f32_16x16x32_bf16 v[126:129], v[148:151], v[196:199], v[126:129]
	v_mfma_f32_16x16x32_bf16 v[70:73], v[144:147], v[176:179], v[70:73]
	v_mfma_f32_16x16x32_bf16 v[74:77], v[152:155], v[176:179], v[74:77]
	v_mfma_f32_16x16x32_bf16 v[86:89], v[144:147], v[184:187], v[86:89]
	v_mfma_f32_16x16x32_bf16 v[90:93], v[152:155], v[184:187], v[90:93]
	v_mfma_f32_16x16x32_bf16 v[102:105], v[144:147], v[192:195], v[102:105]
	v_mfma_f32_16x16x32_bf16 v[106:109], v[152:155], v[192:195], v[106:109]
	v_mfma_f32_16x16x32_bf16 v[130:133], v[144:147], v[200:203], v[130:133]
	v_mfma_f32_16x16x32_bf16 v[126:129], v[152:155], v[200:203], v[126:129]
	v_mfma_f32_16x16x32_bf16 v[78:81], v[156:159], v[172:175], v[78:81]
	v_mfma_f32_16x16x32_bf16 v[82:85], v[164:167], v[172:175], v[82:85]
	v_mfma_f32_16x16x32_bf16 v[94:97], v[156:159], v[180:183], v[94:97]
	v_mfma_f32_16x16x32_bf16 v[98:101], v[164:167], v[180:183], v[98:101]
	v_mfma_f32_16x16x32_bf16 v[110:113], v[156:159], v[188:191], v[110:113]
	v_mfma_f32_16x16x32_bf16 v[114:117], v[164:167], v[188:191], v[114:117]
	v_mfma_f32_16x16x32_bf16 v[122:125], v[156:159], v[196:199], v[122:125]
	v_mfma_f32_16x16x32_bf16 v[118:121], v[164:167], v[196:199], v[118:121]
	v_mfma_f32_16x16x32_bf16 v[78:81], v[160:163], v[176:179], v[78:81]
	v_mfma_f32_16x16x32_bf16 v[82:85], v[168:171], v[176:179], v[82:85]
	v_mfma_f32_16x16x32_bf16 v[94:97], v[160:163], v[184:187], v[94:97]
	v_mfma_f32_16x16x32_bf16 v[98:101], v[168:171], v[184:187], v[98:101]
	v_mfma_f32_16x16x32_bf16 v[110:113], v[160:163], v[192:195], v[110:113]
	v_mfma_f32_16x16x32_bf16 v[114:117], v[168:171], v[192:195], v[114:117]
	v_mfma_f32_16x16x32_bf16 v[122:125], v[160:163], v[200:203], v[122:125]
	v_mfma_f32_16x16x32_bf16 v[118:121], v[168:171], v[200:203], v[118:121]
	s_setprio 0
	s_barrier
	s_add_i32 s30, 0, 0x18000
	s_add_i32 s31, 0, 0x1c000
	v_add_u32_e32 v152, s30, v1
	v_add_u32_e32 v168, s31, v1
	ds_read_b128 v[140:143], v152
	ds_read_b128 v[144:147], v152 offset:1024
	ds_read_b128 v[148:151], v152 offset:2048
	ds_read_b128 v[152:155], v152 offset:3072
	ds_read_b128 v[156:159], v168
	ds_read_b128 v[160:163], v168 offset:1024
	ds_read_b128 v[164:167], v168 offset:2048
	ds_read_b128 v[168:171], v168 offset:3072
	s_add_u32 s28, s28, 0x100000
	s_addc_u32 s29, s29, 0
	s_mov_b32 m0, s41
	v_lshl_add_u64 v[204:205], s[28:29], 0, v[138:139]
	ds_read_b128 v[172:175], v5 offset:32768
	ds_read_b128 v[176:179], v5 offset:33792
	ds_read_b128 v[180:183], v5 offset:34816
	ds_read_b128 v[184:187], v5 offset:35840
	ds_read_b128 v[188:191], v5 offset:36864
	ds_read_b128 v[192:195], v5 offset:37888
	ds_read_b128 v[196:199], v5 offset:38912
	ds_read_b128 v[200:203], v5 offset:39936
	global_load_lds_dwordx4 v[204:205], off
	v_lshl_add_u64 v[204:205], s[28:29], 0, v[134:135]
	s_mov_b32 m0, s42
	s_nop 0
	global_load_lds_dwordx4 v[204:205], off
	s_waitcnt vmcnt(8)
	s_waitcnt lgkmcnt(0)
	s_barrier
	s_setprio 1
	s_waitcnt lgkmcnt(0)
	v_mfma_f32_16x16x32_bf16 v[6:9], v[140:143], v[172:175], v[6:9]
	v_mfma_f32_16x16x32_bf16 v[10:13], v[148:151], v[172:175], v[10:13]
	v_mfma_f32_16x16x32_bf16 v[22:25], v[140:143], v[180:183], v[22:25]
	v_mfma_f32_16x16x32_bf16 v[26:29], v[148:151], v[180:183], v[26:29]
	v_mfma_f32_16x16x32_bf16 v[38:41], v[140:143], v[188:191], v[38:41]
	v_mfma_f32_16x16x32_bf16 v[42:45], v[148:151], v[188:191], v[42:45]
	v_mfma_f32_16x16x32_bf16 v[54:57], v[140:143], v[196:199], v[54:57]
	v_mfma_f32_16x16x32_bf16 v[58:61], v[148:151], v[196:199], v[58:61]
	v_mfma_f32_16x16x32_bf16 v[6:9], v[144:147], v[176:179], v[6:9]
	v_mfma_f32_16x16x32_bf16 v[10:13], v[152:155], v[176:179], v[10:13]
	v_mfma_f32_16x16x32_bf16 v[22:25], v[144:147], v[184:187], v[22:25]
	v_mfma_f32_16x16x32_bf16 v[26:29], v[152:155], v[184:187], v[26:29]
	v_mfma_f32_16x16x32_bf16 v[38:41], v[144:147], v[192:195], v[38:41]
	v_mfma_f32_16x16x32_bf16 v[42:45], v[152:155], v[192:195], v[42:45]
	v_mfma_f32_16x16x32_bf16 v[54:57], v[144:147], v[200:203], v[54:57]
	v_mfma_f32_16x16x32_bf16 v[58:61], v[152:155], v[200:203], v[58:61]
	v_mfma_f32_16x16x32_bf16 v[14:17], v[156:159], v[172:175], v[14:17]
	v_mfma_f32_16x16x32_bf16 v[18:21], v[164:167], v[172:175], v[18:21]
	v_mfma_f32_16x16x32_bf16 v[30:33], v[156:159], v[180:183], v[30:33]
	v_mfma_f32_16x16x32_bf16 v[34:37], v[164:167], v[180:183], v[34:37]
	v_mfma_f32_16x16x32_bf16 v[46:49], v[156:159], v[188:191], v[46:49]
	v_mfma_f32_16x16x32_bf16 v[50:53], v[164:167], v[188:191], v[50:53]
	v_mfma_f32_16x16x32_bf16 v[62:65], v[156:159], v[196:199], v[62:65]
	v_mfma_f32_16x16x32_bf16 v[66:69], v[164:167], v[196:199], v[66:69]
	v_mfma_f32_16x16x32_bf16 v[14:17], v[160:163], v[176:179], v[14:17]
	v_mfma_f32_16x16x32_bf16 v[18:21], v[168:171], v[176:179], v[18:21]
	v_mfma_f32_16x16x32_bf16 v[30:33], v[160:163], v[184:187], v[30:33]
	v_mfma_f32_16x16x32_bf16 v[34:37], v[168:171], v[184:187], v[34:37]
	v_mfma_f32_16x16x32_bf16 v[46:49], v[160:163], v[192:195], v[46:49]
	v_mfma_f32_16x16x32_bf16 v[50:53], v[168:171], v[192:195], v[50:53]
	v_mfma_f32_16x16x32_bf16 v[62:65], v[160:163], v[200:203], v[62:65]
	v_mfma_f32_16x16x32_bf16 v[66:69], v[168:171], v[200:203], v[66:69]
	s_setprio 0
	s_barrier
	s_add_i32 s28, s30, s37
	v_lshl_add_u64 v[204:205], s[26:27], 0, v[136:137]
	s_mov_b32 m0, s28
	ds_read_b128 v[172:175], v5 offset:49152
	ds_read_b128 v[176:179], v5 offset:50176
	ds_read_b128 v[180:183], v5 offset:51200
	ds_read_b128 v[184:187], v5 offset:52224
	ds_read_b128 v[188:191], v5 offset:53248
	ds_read_b128 v[192:195], v5 offset:54272
	ds_read_b128 v[196:199], v5 offset:55296
	ds_read_b128 v[200:203], v5 offset:56320
	global_load_lds_dwordx4 v[204:205], off
	s_add_i32 m0, s28, 0x2000
	v_lshl_add_u64 v[204:205], s[26:27], 0, v[2:3]
	s_add_u32 s26, s26, 0x100000
	s_addc_u32 s27, s27, 0
	s_add_i32 s28, s31, s37
	global_load_lds_dwordx4 v[204:205], off
	v_lshl_add_u64 v[204:205], s[26:27], 0, v[136:137]
	s_mov_b32 m0, s28
	s_nop 0
	global_load_lds_dwordx4 v[204:205], off
	v_lshl_add_u64 v[204:205], s[26:27], 0, v[2:3]
	s_add_i32 m0, s28, 0x2000
	s_nop 0
	global_load_lds_dwordx4 v[204:205], off
	v_lshl_add_u64 v[204:205], s[24:25], 0, v[138:139]
	s_mov_b32 m0, s49
	s_nop 0
	global_load_lds_dwordx4 v[204:205], off
	v_lshl_add_u64 v[204:205], s[24:25], 0, v[134:135]
	s_mov_b32 m0, s50
	s_nop 0
	global_load_lds_dwordx4 v[204:205], off
	s_waitcnt vmcnt(8)
	s_waitcnt lgkmcnt(0)
	s_barrier
	s_setprio 1
	s_waitcnt lgkmcnt(0)
	v_mfma_f32_16x16x32_bf16 v[70:73], v[140:143], v[172:175], v[70:73]
	v_mfma_f32_16x16x32_bf16 v[74:77], v[148:151], v[172:175], v[74:77]
	v_mfma_f32_16x16x32_bf16 v[86:89], v[140:143], v[180:183], v[86:89]
	v_mfma_f32_16x16x32_bf16 v[90:93], v[148:151], v[180:183], v[90:93]
	v_mfma_f32_16x16x32_bf16 v[102:105], v[140:143], v[188:191], v[102:105]
	v_mfma_f32_16x16x32_bf16 v[106:109], v[148:151], v[188:191], v[106:109]
	v_mfma_f32_16x16x32_bf16 v[130:133], v[140:143], v[196:199], v[130:133]
	v_mfma_f32_16x16x32_bf16 v[126:129], v[148:151], v[196:199], v[126:129]
	v_mfma_f32_16x16x32_bf16 v[70:73], v[144:147], v[176:179], v[70:73]
	v_mfma_f32_16x16x32_bf16 v[74:77], v[152:155], v[176:179], v[74:77]
	v_mfma_f32_16x16x32_bf16 v[86:89], v[144:147], v[184:187], v[86:89]
	v_mfma_f32_16x16x32_bf16 v[90:93], v[152:155], v[184:187], v[90:93]
	v_mfma_f32_16x16x32_bf16 v[102:105], v[144:147], v[192:195], v[102:105]
	v_mfma_f32_16x16x32_bf16 v[106:109], v[152:155], v[192:195], v[106:109]
	v_mfma_f32_16x16x32_bf16 v[130:133], v[144:147], v[200:203], v[130:133]
	v_mfma_f32_16x16x32_bf16 v[126:129], v[152:155], v[200:203], v[126:129]
	v_mfma_f32_16x16x32_bf16 v[78:81], v[156:159], v[172:175], v[78:81]
	v_mfma_f32_16x16x32_bf16 v[82:85], v[164:167], v[172:175], v[82:85]
	v_mfma_f32_16x16x32_bf16 v[94:97], v[156:159], v[180:183], v[94:97]
	v_mfma_f32_16x16x32_bf16 v[98:101], v[164:167], v[180:183], v[98:101]
	v_mfma_f32_16x16x32_bf16 v[110:113], v[156:159], v[188:191], v[110:113]
	v_mfma_f32_16x16x32_bf16 v[114:117], v[164:167], v[188:191], v[114:117]
	v_mfma_f32_16x16x32_bf16 v[122:125], v[156:159], v[196:199], v[122:125]
	v_mfma_f32_16x16x32_bf16 v[118:121], v[164:167], v[196:199], v[118:121]
	v_mfma_f32_16x16x32_bf16 v[78:81], v[160:163], v[176:179], v[78:81]
	v_mfma_f32_16x16x32_bf16 v[82:85], v[168:171], v[176:179], v[82:85]
	v_mfma_f32_16x16x32_bf16 v[94:97], v[160:163], v[184:187], v[94:97]
	v_mfma_f32_16x16x32_bf16 v[98:101], v[168:171], v[184:187], v[98:101]
	v_mfma_f32_16x16x32_bf16 v[110:113], v[160:163], v[192:195], v[110:113]
	v_mfma_f32_16x16x32_bf16 v[114:117], v[168:171], v[192:195], v[114:117]
	v_mfma_f32_16x16x32_bf16 v[122:125], v[160:163], v[200:203], v[122:125]
	v_mfma_f32_16x16x32_bf16 v[118:121], v[168:171], v[200:203], v[118:121]
	s_setprio 0
	s_barrier
	s_add_i32 s54, s54, 2
	s_add_u32 s19, s19, 0x100
	s_addc_u32 s33, s33, 0
	s_add_u32 s52, s52, 0x100
	s_addc_u32 s53, s53, 0
	s_cmp_gt_u32 s54, 61
	s_cbranch_scc0 .LBB0_251
	v_mov_b32_e32 v141, v0
	s_lshl_b32 s1, s0, 8
	s_mov_b64 s[24:25], s[84:85]
	s_add_i32 s1, s1, s43
	v_and_or_b32 v140, v141, 15, s1
	v_lshrrev_b32_e32 v141, 1, v141
	s_add_u32 s26, s24, s6
	v_and_or_b32 v148, v141, 24, s48
	s_addc_u32 s27, s25, s7
	v_ashrrev_i32_e32 v141, 31, v140
	v_lshl_add_u64 v[142:143], v[140:141], 2, s[26:27]
	s_mov_b64 s[26:27], 0x10000
	v_lshl_add_u64 v[144:145], v[142:143], 0, s[26:27]
	v_add_co_u32_e32 v142, vcc, s91, v142
	global_load_dword v146, v[144:145], off offset:512
	s_nop 0
	v_addc_co_u32_e32 v143, vcc, 0, v143, vcc
	global_load_dword v142, v[142:143], off
	s_cmp_lt_i32 s22, 8
	s_mov_b64 s[26:27], -1
	global_load_dword v205, v[144:145], off offset:64
	global_load_dword v204, v[144:145], off offset:128
	global_load_dword v203, v[144:145], off offset:192
	global_load_dword v202, v[144:145], off offset:576
	global_load_dword v201, v[144:145], off offset:640
	global_load_dword v200, v[144:145], off offset:704
	s_waitcnt vmcnt(0)
	v_fmamk_f32 v146, v146, 0x39800000, v246
	v_mul_f32_e32 v147, 0x4b800000, v146
	v_fmamk_f32 v142, v142, 0x39800000, v246
	v_cmp_gt_f32_e32 vcc, s95, v142
	v_mul_f32_e32 v143, 0x4b800000, v142
	s_nop 0
	v_cndmask_b32_e32 v142, v142, v143, vcc
	v_rsq_f32_e32 v142, v142
	s_nop 0
	v_mul_f32_e32 v143, 0x45800000, v142
	v_cndmask_b32_e32 v142, v142, v143, vcc
	v_pk_mul_f32 v[8:9], v[8:9], v[142:143] op_sel_hi:[1,0]
	v_pk_mul_f32 v[6:7], v[6:7], v[142:143] op_sel_hi:[1,0]
	v_pk_mul_f32 v[12:13], v[12:13], v[142:143] op_sel_hi:[1,0]
	v_pk_mul_f32 v[10:11], v[10:11], v[142:143] op_sel_hi:[1,0]
	v_pk_mul_f32 v[16:17], v[16:17], v[142:143] op_sel_hi:[1,0]
	v_pk_mul_f32 v[14:15], v[14:15], v[142:143] op_sel_hi:[1,0]
	v_pk_mul_f32 v[20:21], v[20:21], v[142:143] op_sel_hi:[1,0]
	v_pk_mul_f32 v[18:19], v[18:19], v[142:143] op_sel_hi:[1,0]
	s_waitcnt vmcnt(0)
	v_fmamk_f32 v142, v205, 0x39800000, v246
	v_cmp_gt_f32_e32 vcc, s95, v142
	v_mul_f32_e32 v143, 0x4b800000, v142
	s_nop 0
	v_cndmask_b32_e32 v142, v142, v143, vcc
	v_rsq_f32_e32 v142, v142
	s_nop 0
	v_mul_f32_e32 v143, 0x45800000, v142
	v_cndmask_b32_e32 v142, v142, v143, vcc
	v_pk_mul_f32 v[24:25], v[24:25], v[142:143] op_sel_hi:[1,0]
	v_pk_mul_f32 v[22:23], v[22:23], v[142:143] op_sel_hi:[1,0]
	v_pk_mul_f32 v[28:29], v[28:29], v[142:143] op_sel_hi:[1,0]
	v_pk_mul_f32 v[26:27], v[26:27], v[142:143] op_sel_hi:[1,0]
	v_pk_mul_f32 v[32:33], v[32:33], v[142:143] op_sel_hi:[1,0]
	v_pk_mul_f32 v[30:31], v[30:31], v[142:143] op_sel_hi:[1,0]
	v_pk_mul_f32 v[36:37], v[36:37], v[142:143] op_sel_hi:[1,0]
	v_pk_mul_f32 v[34:35], v[34:35], v[142:143] op_sel_hi:[1,0]
	s_waitcnt vmcnt(0)
	v_fmamk_f32 v142, v204, 0x39800000, v246
	v_cmp_gt_f32_e32 vcc, s95, v142
	v_mul_f32_e32 v143, 0x4b800000, v142
	s_nop 0
	v_cndmask_b32_e32 v142, v142, v143, vcc
	v_rsq_f32_e32 v142, v142
	s_nop 0
	v_mul_f32_e32 v143, 0x45800000, v142
	v_cndmask_b32_e32 v142, v142, v143, vcc
	v_pk_mul_f32 v[40:41], v[40:41], v[142:143] op_sel_hi:[1,0]
	v_pk_mul_f32 v[38:39], v[38:39], v[142:143] op_sel_hi:[1,0]
	v_pk_mul_f32 v[44:45], v[44:45], v[142:143] op_sel_hi:[1,0]
	v_pk_mul_f32 v[42:43], v[42:43], v[142:143] op_sel_hi:[1,0]
	v_pk_mul_f32 v[48:49], v[48:49], v[142:143] op_sel_hi:[1,0]
	v_pk_mul_f32 v[46:47], v[46:47], v[142:143] op_sel_hi:[1,0]
	v_pk_mul_f32 v[52:53], v[52:53], v[142:143] op_sel_hi:[1,0]
	v_pk_mul_f32 v[50:51], v[50:51], v[142:143] op_sel_hi:[1,0]
	s_waitcnt vmcnt(0)
	v_fmamk_f32 v142, v203, 0x39800000, v246
	v_cmp_gt_f32_e32 vcc, s95, v142
	v_mul_f32_e32 v143, 0x4b800000, v142
	s_nop 0
	v_cndmask_b32_e32 v142, v142, v143, vcc
	v_rsq_f32_e32 v142, v142
	s_nop 0
	v_mul_f32_e32 v143, 0x45800000, v142
	v_cndmask_b32_e32 v142, v142, v143, vcc
	v_cmp_gt_f32_e32 vcc, s95, v146
	v_pk_mul_f32 v[56:57], v[56:57], v[142:143] op_sel_hi:[1,0]
	v_pk_mul_f32 v[54:55], v[54:55], v[142:143] op_sel_hi:[1,0]
	v_cndmask_b32_e32 v146, v146, v147, vcc
	v_rsq_f32_e32 v146, v146
	v_pk_mul_f32 v[60:61], v[60:61], v[142:143] op_sel_hi:[1,0]
	v_pk_mul_f32 v[58:59], v[58:59], v[142:143] op_sel_hi:[1,0]
	v_pk_mul_f32 v[64:65], v[64:65], v[142:143] op_sel_hi:[1,0]
	v_mul_f32_e32 v147, 0x45800000, v146
	v_cndmask_b32_e32 v146, v146, v147, vcc
	v_pk_mul_f32 v[72:73], v[72:73], v[146:147] op_sel_hi:[1,0]
	v_pk_mul_f32 v[70:71], v[70:71], v[146:147] op_sel_hi:[1,0]
	v_pk_mul_f32 v[76:77], v[76:77], v[146:147] op_sel_hi:[1,0]
	v_pk_mul_f32 v[74:75], v[74:75], v[146:147] op_sel_hi:[1,0]
	v_pk_mul_f32 v[80:81], v[80:81], v[146:147] op_sel_hi:[1,0]
	v_pk_mul_f32 v[78:79], v[78:79], v[146:147] op_sel_hi:[1,0]
	v_pk_mul_f32 v[84:85], v[84:85], v[146:147] op_sel_hi:[1,0]
	v_pk_mul_f32 v[82:83], v[82:83], v[146:147] op_sel_hi:[1,0]
	v_pk_mul_f32 v[62:63], v[62:63], v[142:143] op_sel_hi:[1,0]
	v_pk_mul_f32 v[68:69], v[68:69], v[142:143] op_sel_hi:[1,0]
	v_pk_mul_f32 v[66:67], v[66:67], v[142:143] op_sel_hi:[1,0]
	v_add_u32_e32 v142, 0x80, v140
	v_ashrrev_i32_e32 v143, 31, v142
	s_waitcnt vmcnt(0)
	v_fmamk_f32 v146, v202, 0x39800000, v246
	v_cmp_gt_f32_e32 vcc, s95, v146
	v_mul_f32_e32 v147, 0x4b800000, v146
	s_nop 0
	v_cndmask_b32_e32 v146, v146, v147, vcc
	v_rsq_f32_e32 v146, v146
	s_nop 0
	v_mul_f32_e32 v147, 0x45800000, v146
	v_cndmask_b32_e32 v146, v146, v147, vcc
	v_pk_mul_f32 v[88:89], v[88:89], v[146:147] op_sel_hi:[1,0]
	v_pk_mul_f32 v[86:87], v[86:87], v[146:147] op_sel_hi:[1,0]
	v_pk_mul_f32 v[92:93], v[92:93], v[146:147] op_sel_hi:[1,0]
	v_pk_mul_f32 v[90:91], v[90:91], v[146:147] op_sel_hi:[1,0]
	v_pk_mul_f32 v[96:97], v[96:97], v[146:147] op_sel_hi:[1,0]
	v_pk_mul_f32 v[94:95], v[94:95], v[146:147] op_sel_hi:[1,0]
	v_pk_mul_f32 v[100:101], v[100:101], v[146:147] op_sel_hi:[1,0]
	v_pk_mul_f32 v[98:99], v[98:99], v[146:147] op_sel_hi:[1,0]
	s_waitcnt vmcnt(0)
	v_fmamk_f32 v146, v201, 0x39800000, v246
	v_cmp_gt_f32_e32 vcc, s95, v146
	v_mul_f32_e32 v147, 0x4b800000, v146
	s_waitcnt vmcnt(0)
	v_fmamk_f32 v144, v200, 0x39800000, v246
	v_cndmask_b32_e32 v146, v146, v147, vcc
	v_rsq_f32_e32 v146, v146
	v_mul_f32_e32 v145, 0x4b800000, v144
	v_mul_f32_e32 v147, 0x45800000, v146
	v_cndmask_b32_e32 v146, v146, v147, vcc
	v_cmp_gt_f32_e32 vcc, s95, v144
	v_pk_mul_f32 v[104:105], v[104:105], v[146:147] op_sel_hi:[1,0]
	v_pk_mul_f32 v[102:103], v[102:103], v[146:147] op_sel_hi:[1,0]
	v_cndmask_b32_e32 v144, v144, v145, vcc
	v_rsq_f32_e32 v144, v144
	v_pk_mul_f32 v[108:109], v[108:109], v[146:147] op_sel_hi:[1,0]
	v_pk_mul_f32 v[106:107], v[106:107], v[146:147] op_sel_hi:[1,0]
	v_pk_mul_f32 v[112:113], v[112:113], v[146:147] op_sel_hi:[1,0]
	v_mul_f32_e32 v145, 0x45800000, v144
	v_cndmask_b32_e32 v144, v144, v145, vcc
	v_pk_mul_f32 v[110:111], v[110:111], v[146:147] op_sel_hi:[1,0]
	v_pk_mul_f32 v[116:117], v[116:117], v[146:147] op_sel_hi:[1,0]
	v_pk_mul_f32 v[114:115], v[114:115], v[146:147] op_sel_hi:[1,0]
	v_pk_mul_f32 v[132:133], v[132:133], v[144:145] op_sel_hi:[1,0]
	v_pk_mul_f32 v[130:131], v[130:131], v[144:145] op_sel_hi:[1,0]
	v_pk_mul_f32 v[128:129], v[128:129], v[144:145] op_sel_hi:[1,0]
	v_pk_mul_f32 v[126:127], v[126:127], v[144:145] op_sel_hi:[1,0]
	v_pk_mul_f32 v[124:125], v[124:125], v[144:145] op_sel_hi:[1,0]
	v_pk_mul_f32 v[122:123], v[122:123], v[144:145] op_sel_hi:[1,0]
	v_pk_mul_f32 v[120:121], v[120:121], v[144:145] op_sel_hi:[1,0]
	v_pk_mul_f32 v[118:119], v[118:119], v[144:145] op_sel_hi:[1,0]
	s_cbranch_scc1 .LBB0_254
	v_mul_f32_e32 v145, 0xbfb8aa3b, v7
	v_mul_f32_e32 v146, 0xbfb8aa3b, v8
	v_exp_f32_e32 v145, v145
	v_exp_f32_e32 v146, v146
	v_mul_f32_e32 v144, 0xbfb8aa3b, v6
	v_exp_f32_e32 v144, v144
	v_add_f32_e32 v145, 1.0, v145
	v_add_f32_e32 v146, 1.0, v146
	v_rcp_f32_e32 v145, v145
	v_rcp_f32_e32 v149, v146
	v_add_f32_e32 v144, 1.0, v144
	v_mul_f32_e32 v146, 0xbfb8aa3b, v9
	v_mul_f32_e32 v147, v7, v145
	v_mul_f32_e32 v195, v8, v149
	v_mul_f32_e32 v145, 0xbfb8aa3b, v10
	v_mul_f32_e32 v149, 0xbfb8aa3b, v11
	v_rcp_f32_e32 v144, v144
	v_exp_f32_e32 v150, v146
	v_exp_f32_e32 v145, v145
	v_exp_f32_e32 v149, v149
	v_mul_f32_e32 v146, v6, v144
	v_add_f32_e32 v144, 1.0, v150
	v_add_f32_e32 v145, 1.0, v145
	v_add_f32_e32 v149, 1.0, v149
	v_mul_f32_e32 v150, 0xbfb8aa3b, v12
	v_rcp_f32_e32 v144, v144
	v_rcp_f32_e32 v145, v145
	v_rcp_f32_e32 v149, v149
	v_exp_f32_e32 v150, v150
	v_mul_f32_e32 v209, v9, v144
	v_mul_f32_e32 v144, v10, v145
	v_mul_f32_e32 v145, v11, v149
	v_add_f32_e32 v149, 1.0, v150
	v_mul_f32_e32 v150, 0xbfb8aa3b, v13
	v_exp_f32_e32 v150, v150
	v_mul_f32_e32 v151, 0xbfb8aa3b, v14
	v_exp_f32_e32 v151, v151
	v_mul_f32_e32 v240, 0xbfb8aa3b, v99
	v_add_f32_e32 v150, 1.0, v150
	v_rcp_f32_e32 v150, v150
	v_add_f32_e32 v151, 1.0, v151
	v_rcp_f32_e32 v151, v151
	v_exp_f32_e32 v240, v240
	v_mul_f32_e32 v206, v13, v150
	v_mul_f32_e32 v150, 0xbfb8aa3b, v16
	v_mul_f32_e32 v194, v14, v151
	v_exp_f32_e32 v150, v150
	v_mul_f32_e32 v151, 0xbfb8aa3b, v17
	v_exp_f32_e32 v151, v151
	v_mul_f32_e32 v152, 0xbfb8aa3b, v15
	v_rcp_f32_e32 v149, v149
	v_exp_f32_e32 v152, v152
	v_add_f32_e32 v150, 1.0, v150
	v_rcp_f32_e32 v150, v150
	v_add_f32_e32 v151, 1.0, v151
	v_add_f32_e32 v242, 1.0, v240
	v_cvt_pk_bf16_f32 v240, v146, v147
	v_mul_f32_e32 v146, 0xbfb8aa3b, v100
	v_rcp_f32_e32 v151, v151
	v_exp_f32_e32 v146, v146
	v_mul_f32_e32 v147, 0xbfb8aa3b, v101
	v_exp_f32_e32 v147, v147
	v_mul_f32_e32 v205, v12, v149
	v_add_f32_e32 v149, 1.0, v152
	v_mul_f32_e32 v152, 0xbfb8aa3b, v18
	s_lshl_b32 s1, s22, 8
	v_rcp_f32_e32 v149, v149
	v_exp_f32_e32 v152, v152
	v_mul_f32_e32 v203, v16, v150
	v_mul_f32_e32 v150, 0xbfb8aa3b, v19
	v_cvt_pk_bf16_f32 v241, v195, v209
	v_rcp_f32_e32 v195, v242
	s_addk_i32 s1, 0xf800
	v_cvt_pk_bf16_f32 v242, v144, v145
	v_cvt_pk_bf16_f32 v243, v205, v206
	v_mul_f32_e32 v205, 0xbfb8aa3b, v102
	v_mul_f32_e32 v204, v17, v151
	v_exp_f32_e32 v150, v150
	v_mul_f32_e32 v151, 0xbfb8aa3b, v20
	v_add_f32_e32 v146, 1.0, v146
	v_or_b32_e32 v144, s1, v148
	v_mov_b32_e32 v145, v4
	v_exp_f32_e32 v205, v205
	v_exp_f32_e32 v151, v151
	v_rcp_f32_e32 v209, v146
	v_add_f32_e32 v146, 1.0, v147
	v_lshl_add_u64 v[144:145], v[144:145], 1, s[24:25]
	s_mov_b64 s[26:27], 0x1b480000
	v_rcp_f32_e32 v244, v146
	v_lshl_add_u64 v[146:147], v[144:145], 0, s[26:27]
	v_lshlrev_b64 v[144:145], 13, v[140:141]
	v_mul_f32_e32 v202, v15, v149
	v_add_f32_e32 v149, 1.0, v152
	v_lshl_add_u64 v[144:145], v[146:147], 0, v[144:145]
	v_rcp_f32_e32 v149, v149
	v_add_f32_e32 v150, 1.0, v150
	global_store_dwordx4 v[144:145], v[240:243], off nt
	v_add_f32_e32 v205, 1.0, v205
	v_rcp_f32_e32 v150, v150
	v_mul_f32_e32 v240, 0xbfb8aa3b, v103
	v_add_f32_e32 v151, 1.0, v151
	v_exp_f32_e32 v240, v240
	v_cvt_pk_bf16_f32 v202, v194, v202
	v_cvt_pk_bf16_f32 v203, v203, v204
	v_rcp_f32_e32 v204, v205
	v_rcp_f32_e32 v151, v151
	v_mul_f32_e32 v152, 0xbfb8aa3b, v21
	v_mul_f32_e32 v200, v18, v149
	v_exp_f32_e32 v152, v152
	v_mul_f32_e32 v201, v19, v150
	v_add_f32_e32 v205, 1.0, v240
	v_mul_f32_e32 v240, 0xbfb8aa3b, v105
	v_mul_f32_e32 v241, v102, v204
	v_cvt_pk_bf16_f32 v204, v200, v201
	v_mul_f32_e32 v200, 0xbfb8aa3b, v106
	v_mul_f32_e32 v192, v20, v151
	v_mul_f32_e32 v151, 0xbfb8aa3b, v23
	v_rcp_f32_e32 v205, v205
	v_exp_f32_e32 v240, v240
	v_exp_f32_e32 v200, v200
	v_exp_f32_e32 v151, v151
	v_mul_f32_e32 v150, 0xbfb8aa3b, v22
	v_add_f32_e32 v149, 1.0, v152
	v_exp_f32_e32 v150, v150
	v_rcp_f32_e32 v149, v149
	v_mul_f32_e32 v242, v103, v205
	v_add_f32_e32 v205, 1.0, v240
	v_mul_f32_e32 v201, 0xbfb8aa3b, v107
	v_add_f32_e32 v200, 1.0, v200
	v_add_f32_e32 v151, 1.0, v151
	v_exp_f32_e32 v201, v201
	v_rcp_f32_e32 v240, v205
	v_rcp_f32_e32 v200, v200
	v_rcp_f32_e32 v151, v151
	v_add_f32_e32 v150, 1.0, v150
	v_rcp_f32_e32 v150, v150
	v_mul_f32_e32 v197, v21, v149
	v_mul_f32_e32 v152, 0xbfb8aa3b, v24
	v_add_f32_e32 v201, 1.0, v201
	v_cvt_pk_bf16_f32 v205, v192, v197
	v_mul_f32_e32 v197, v105, v240
	v_mul_f32_e32 v240, v106, v200
	v_mul_f32_e32 v200, 0xbfb8aa3b, v109
	v_exp_f32_e32 v152, v152
	v_mul_f32_e32 v181, v23, v151
	v_mul_f32_e32 v151, 0xbfb8aa3b, v26
	v_rcp_f32_e32 v201, v201
	v_exp_f32_e32 v200, v200
	v_exp_f32_e32 v151, v151
	v_mul_f32_e32 v179, v22, v150
	v_mul_f32_e32 v150, 0xbfb8aa3b, v25
	v_exp_f32_e32 v150, v150
	v_add_f32_e32 v149, 1.0, v152
	v_mul_f32_e32 v152, 0xbfb8aa3b, v27
	v_mul_f32_e32 v243, v107, v201
	v_mul_f32_e32 v201, 0xbfb8aa3b, v110
	v_add_f32_e32 v200, 1.0, v200
	v_rcp_f32_e32 v149, v149
	v_add_f32_e32 v151, 1.0, v151
	v_exp_f32_e32 v152, v152
	v_exp_f32_e32 v201, v201
	v_rcp_f32_e32 v200, v200
	v_rcp_f32_e32 v151, v151
	v_add_f32_e32 v150, 1.0, v150
	v_rcp_f32_e32 v150, v150
	global_store_dwordx4 v[144:145], v[202:205], off offset:256 nt
	v_mul_f32_e32 v188, v24, v149
	v_add_f32_e32 v149, 1.0, v152
	v_mul_f32_e32 v202, 0xbfb8aa3b, v111
	v_add_f32_e32 v201, 1.0, v201
	v_exp_f32_e32 v202, v202
	v_mul_f32_e32 v204, v109, v200
	v_cvt_pk_bf16_f32 v200, v179, v181
	v_mul_f32_e32 v181, 0xbfb8aa3b, v113
	v_mul_f32_e32 v178, v26, v151
	v_mul_f32_e32 v151, 0xbfb8aa3b, v29
	v_rcp_f32_e32 v149, v149
	v_rcp_f32_e32 v201, v201
	v_exp_f32_e32 v181, v181
	v_exp_f32_e32 v151, v151
	v_mul_f32_e32 v179, 0xbfb8aa3b, v112
	v_mul_f32_e32 v189, v25, v150
	v_mul_f32_e32 v150, 0xbfb8aa3b, v28
	v_exp_f32_e32 v179, v179
	v_exp_f32_e32 v150, v150
	v_add_f32_e32 v202, 1.0, v202
	v_mul_f32_e32 v187, v27, v149
	v_mul_f32_e32 v205, v110, v201
	v_cvt_pk_bf16_f32 v201, v188, v189
	v_rcp_f32_e32 v188, v202
	v_add_f32_e32 v181, 1.0, v181
	v_cvt_pk_bf16_f32 v202, v178, v187
	v_mul_f32_e32 v178, 0xbfb8aa3b, v114
	v_add_f32_e32 v151, 1.0, v151
	v_rcp_f32_e32 v181, v181
	v_exp_f32_e32 v178, v178
	v_rcp_f32_e32 v151, v151
	v_add_f32_e32 v179, 1.0, v179
	v_add_f32_e32 v150, 1.0, v150
	v_rcp_f32_e32 v179, v179
	v_rcp_f32_e32 v150, v150
	v_mul_f32_e32 v245, v113, v181
	v_add_f32_e32 v181, 1.0, v178
	v_mul_f32_e32 v178, 0xbfb8aa3b, v115
	v_mul_f32_e32 v182, v29, v151
	v_mul_f32_e32 v151, 0xbfb8aa3b, v32
	v_exp_f32_e32 v248, v178
	v_or_b32_e32 v178, 16, v140
	v_exp_f32_e32 v151, v151
	v_mul_f32_e32 v206, v100, v209
	v_mul_f32_e32 v209, v101, v244
	v_mul_f32_e32 v244, v112, v179
	v_ashrrev_i32_e32 v179, 31, v178
	v_mul_f32_e32 v152, 0xbfb8aa3b, v30
	v_mul_f32_e32 v180, v28, v150
	v_mul_f32_e32 v150, 0xbfb8aa3b, v31
	v_lshlrev_b64 v[178:179], 13, v[178:179]
	v_exp_f32_e32 v152, v152
	v_exp_f32_e32 v150, v150
	v_mul_f32_e32 v187, v111, v188
	v_lshl_add_u64 v[188:189], v[146:147], 0, v[178:179]
	v_mul_f32_e32 v178, 0xbfb8aa3b, v116
	v_exp_f32_e32 v178, v178
	v_add_f32_e32 v151, 1.0, v151
	v_rcp_f32_e32 v151, v151
	v_add_f32_e32 v149, 1.0, v152
	v_add_f32_e32 v150, 1.0, v150
	v_rcp_f32_e32 v149, v149
	v_rcp_f32_e32 v150, v150
	v_add_f32_e32 v178, 1.0, v178
	v_rcp_f32_e32 v178, v178
	v_mul_f32_e32 v173, v32, v151
	v_mul_f32_e32 v151, 0xbfb8aa3b, v35
	v_exp_f32_e32 v151, v151
	v_mul_f32_e32 v152, 0xbfb8aa3b, v33
	v_mul_f32_e32 v170, v30, v149
	v_mul_f32_e32 v172, v31, v150
	v_mul_f32_e32 v150, 0xbfb8aa3b, v34
	v_exp_f32_e32 v152, v152
	v_exp_f32_e32 v150, v150
	v_cvt_pk_bf16_f32 v203, v180, v182
	global_store_dwordx4 v[188:189], v[200:203], off nt
	v_add_f32_e32 v151, 1.0, v151
	v_rcp_f32_e32 v151, v151
	v_mul_f32_e32 v201, v116, v178
	v_cvt_pk_bf16_f32 v178, v170, v172
	v_mul_f32_e32 v170, 0xbfb8aa3b, v130
	v_exp_f32_e32 v170, v170
	v_add_f32_e32 v149, 1.0, v152
	v_add_f32_e32 v150, 1.0, v150
	v_rcp_f32_e32 v149, v149
	v_rcp_f32_e32 v150, v150
	v_add_f32_e32 v170, 1.0, v170
	v_rcp_f32_e32 v179, v181
	v_rcp_f32_e32 v170, v170
	v_mul_f32_e32 v152, 0xbfb8aa3b, v36
	v_mul_f32_e32 v169, v35, v151
	v_mul_f32_e32 v151, 0xbfb8aa3b, v38
	v_exp_f32_e32 v152, v152
	v_exp_f32_e32 v151, v151
	v_add_f32_e32 v180, 1.0, v248
	v_mul_f32_e32 v181, 0xbfb8aa3b, v117
	v_mul_f32_e32 v183, v33, v149
	v_mul_f32_e32 v168, v34, v150
	v_mul_f32_e32 v150, 0xbfb8aa3b, v37
	v_rcp_f32_e32 v180, v180
	v_exp_f32_e32 v181, v181
	v_exp_f32_e32 v150, v150
	v_mul_f32_e32 v182, v114, v179
	v_cvt_pk_bf16_f32 v179, v173, v183
	v_mul_f32_e32 v183, v130, v170
	v_mul_f32_e32 v170, 0xbfb8aa3b, v126
	v_exp_f32_e32 v170, v170
	v_add_f32_e32 v149, 1.0, v152
	v_add_f32_e32 v151, 1.0, v151
	v_rcp_f32_e32 v149, v149
	v_rcp_f32_e32 v151, v151
	v_mul_f32_e32 v200, v115, v180
	v_add_f32_e32 v180, 1.0, v181
	v_add_f32_e32 v150, 1.0, v150
	v_rcp_f32_e32 v173, v180
	v_cvt_pk_bf16_f32 v180, v168, v169
	v_mul_f32_e32 v168, 0xbfb8aa3b, v132
	v_mul_f32_e32 v169, 0xbfb8aa3b, v133
	v_rcp_f32_e32 v150, v150
	v_exp_f32_e32 v168, v168
	v_exp_f32_e32 v169, v169
	v_add_f32_e32 v170, 1.0, v170
	v_rcp_f32_e32 v170, v170
	v_mul_f32_e32 v171, v36, v149
	v_mul_f32_e32 v149, v38, v151
	v_mul_f32_e32 v151, 0xbfb8aa3b, v40
	v_mul_f32_e32 v152, 0xbfb8aa3b, v39
	v_exp_f32_e32 v151, v151
	v_exp_f32_e32 v152, v152
	v_mul_f32_e32 v174, v37, v150
	v_add_f32_e32 v168, 1.0, v168
	v_cvt_pk_bf16_f32 v181, v171, v174
	v_add_f32_e32 v169, 1.0, v169
	v_mul_f32_e32 v171, 0xbfb8aa3b, v127
	v_rcp_f32_e32 v168, v168
	v_rcp_f32_e32 v169, v169
	v_exp_f32_e32 v171, v171
	v_mul_f32_e32 v203, v126, v170
	v_mul_f32_e32 v170, 0xbfb8aa3b, v129
	v_exp_f32_e32 v170, v170
	v_add_f32_e32 v151, 1.0, v151
	v_add_f32_e32 v150, 1.0, v152
	v_mul_f32_e32 v152, 0xbfb8aa3b, v41
	v_rcp_f32_e32 v151, v151
	v_exp_f32_e32 v152, v152
	v_mul_f32_e32 v174, v132, v168
	v_mul_f32_e32 v202, v133, v169
	v_add_f32_e32 v168, 1.0, v171
	v_mul_f32_e32 v169, 0xbfb8aa3b, v128
	v_exp_f32_e32 v169, v169
	v_rcp_f32_e32 v168, v168
	v_add_f32_e32 v170, 1.0, v170
	v_mul_f32_e32 v171, 0xbfb8aa3b, v122
	v_rcp_f32_e32 v170, v170
	v_exp_f32_e32 v171, v171
	v_mul_f32_e32 v153, 0xbfb8aa3b, v42
	v_mul_f32_e32 v154, v40, v151
	v_mul_f32_e32 v151, 0xbfb8aa3b, v43
	v_rcp_f32_e32 v150, v150
	v_add_f32_e32 v152, 1.0, v152
	v_exp_f32_e32 v156, v153
	v_exp_f32_e32 v151, v151
	v_rcp_f32_e32 v152, v152
	global_store_dwordx4 v[188:189], v[178:181], off offset:256 nt
	v_add_f32_e32 v169, 1.0, v169
	v_rcp_f32_e32 v169, v169
	v_mul_f32_e32 v178, v127, v168
	v_mul_f32_e32 v168, 0xbfb8aa3b, v123
	v_mul_f32_e32 v180, v129, v170
	v_add_f32_e32 v170, 1.0, v171
	v_exp_f32_e32 v171, v168
	v_mul_f32_e32 v153, v39, v150
	v_add_f32_e32 v150, 1.0, v156
	v_add_f32_e32 v151, 1.0, v151
	v_mul_f32_e32 v156, 0xbfb8aa3b, v45
	v_mul_f32_e32 v155, v41, v152
	v_mul_f32_e32 v152, 0xbfb8aa3b, v44
	v_rcp_f32_e32 v150, v150
	v_rcp_f32_e32 v151, v151
	v_exp_f32_e32 v158, v156
	v_exp_f32_e32 v152, v152
	v_mul_f32_e32 v179, v128, v169
	v_cvt_pk_bf16_f32 v168, v149, v153
	v_cvt_pk_bf16_f32 v169, v154, v155
	v_add_f32_e32 v154, 1.0, v171
	v_mul_f32_e32 v155, 0xbfb8aa3b, v125
	v_rcp_f32_e32 v153, v170
	v_rcp_f32_e32 v154, v154
	v_exp_f32_e32 v155, v155
	v_mul_f32_e32 v156, v42, v150
	v_mul_f32_e32 v157, v43, v151
	v_add_f32_e32 v150, 1.0, v158
	v_mul_f32_e32 v151, 0xbfb8aa3b, v46
	v_mul_f32_e32 v158, 0xbfb8aa3b, v47
	v_add_f32_e32 v152, 1.0, v152
	v_exp_f32_e32 v151, v151
	v_exp_f32_e32 v158, v158
	v_rcp_f32_e32 v152, v152
	v_mul_f32_e32 v185, 0xbfb8aa3b, v61
	v_mul_f32_e32 v181, v122, v153
	v_mul_f32_e32 v188, v123, v154
	v_add_f32_e32 v153, 1.0, v155
	v_mul_f32_e32 v154, 0xbfb8aa3b, v118
	v_rcp_f32_e32 v150, v150
	v_exp_f32_e32 v185, v185
	v_mul_f32_e32 v186, 0xbfb8aa3b, v62
	v_rcp_f32_e32 v153, v153
	v_exp_f32_e32 v154, v154
	v_mul_f32_e32 v184, 0xbfb8aa3b, v60
	v_exp_f32_e32 v186, v186
	v_add_f32_e32 v151, 1.0, v151
	v_add_f32_e32 v158, 1.0, v158
	v_mul_f32_e32 v159, 0xbfb8aa3b, v48
	v_exp_f32_e32 v184, v184
	v_mul_f32_e32 v210, 0xbfb8aa3b, v71
	v_mul_f32_e32 v155, 0xbfb8aa3b, v119
	v_mul_f32_e32 v152, v44, v152
	v_rcp_f32_e32 v151, v151
	v_rcp_f32_e32 v158, v158
	v_exp_f32_e32 v159, v159
	v_mul_f32_e32 v207, 0xbfb8aa3b, v69
	v_mul_f32_e32 v208, 0xbfb8aa3b, v70
	v_exp_f32_e32 v210, v210
	v_mul_f32_e32 v226, 0xbfb8aa3b, v85
	v_exp_f32_e32 v155, v155
	v_mul_f32_e32 v161, v45, v150
	v_add_f32_e32 v185, 1.0, v185
	v_exp_f32_e32 v207, v207
	v_exp_f32_e32 v208, v208
	v_exp_f32_e32 v226, v226
	v_mul_f32_e32 v227, 0xbfb8aa3b, v86
	v_cvt_pk_bf16_f32 v170, v156, v157
	v_mul_f32_e32 v156, v125, v153
	v_add_f32_e32 v153, 1.0, v154
	v_cvt_pk_bf16_f32 v171, v152, v161
	v_or_b32_e32 v152, 32, v140
	v_rcp_f32_e32 v190, v185
	v_add_f32_e32 v185, 1.0, v186
	v_mul_f32_e32 v225, 0xbfb8aa3b, v84
	v_exp_f32_e32 v227, v227
	v_mul_f32_e32 v236, 0xbfb8aa3b, v95
	v_rcp_f32_e32 v157, v153
	v_ashrrev_i32_e32 v153, 31, v152
	v_add_f32_e32 v184, 1.0, v184
	v_rcp_f32_e32 v191, v185
	v_mul_f32_e32 v185, 0xbfb8aa3b, v63
	v_exp_f32_e32 v225, v225
	v_mul_f32_e32 v234, 0xbfb8aa3b, v93
	v_mul_f32_e32 v235, 0xbfb8aa3b, v94
	v_exp_f32_e32 v236, v236
	v_lshlrev_b64 v[152:153], 13, v[152:153]
	v_mul_f32_e32 v150, v46, v151
	v_mul_f32_e32 v151, v47, v158
	v_add_f32_e32 v158, 1.0, v159
	v_mul_f32_e32 v159, 0xbfb8aa3b, v49
	v_mul_f32_e32 v160, 0xbfb8aa3b, v50
	v_mul_f32_e32 v162, 0xbfb8aa3b, v51
	v_mul_f32_e32 v163, 0xbfb8aa3b, v52
	v_mul_f32_e32 v164, 0xbfb8aa3b, v53
	v_rcp_f32_e32 v184, v184
	v_exp_f32_e32 v193, v185
	v_add_f32_e32 v210, 1.0, v210
	v_exp_f32_e32 v234, v234
	v_exp_f32_e32 v235, v235
	v_add_f32_e32 v189, 1.0, v155
	v_lshl_add_u64 v[154:155], v[146:147], 0, v[152:153]
	v_mul_f32_e32 v152, 0xbfb8aa3b, v120
	v_mul_f32_e32 v153, 0xbfb8aa3b, v121
	v_exp_f32_e32 v159, v159
	v_exp_f32_e32 v160, v160
	v_exp_f32_e32 v162, v162
	v_exp_f32_e32 v163, v163
	v_exp_f32_e32 v164, v164
	v_add_f32_e32 v207, 1.0, v207
	v_add_f32_e32 v208, 1.0, v208
	v_rcp_f32_e32 v211, v210
	v_mul_f32_e32 v210, 0xbfb8aa3b, v72
	v_add_f32_e32 v226, 1.0, v226
	v_exp_f32_e32 v152, v152
	v_exp_f32_e32 v153, v153
	v_rcp_f32_e32 v207, v207
	v_rcp_f32_e32 v208, v208
	v_exp_f32_e32 v212, v210
	v_rcp_f32_e32 v228, v226
	v_add_f32_e32 v226, 1.0, v227
	v_mul_f32_e32 v165, 0xbfb8aa3b, v54
	v_mul_f32_e32 v166, 0xbfb8aa3b, v55
	v_mul_f32_e32 v167, 0xbfb8aa3b, v56
	v_mul_f32_e32 v175, 0xbfb8aa3b, v57
	v_add_f32_e32 v225, 1.0, v225
	v_rcp_f32_e32 v229, v226
	v_mul_f32_e32 v226, 0xbfb8aa3b, v87
	v_add_f32_e32 v236, 1.0, v236
	v_exp_f32_e32 v165, v165
	v_exp_f32_e32 v166, v166
	v_exp_f32_e32 v167, v167
	v_exp_f32_e32 v175, v175
	v_mul_f32_e32 v176, 0xbfb8aa3b, v58
	v_mul_f32_e32 v177, 0xbfb8aa3b, v59
	v_mul_f32_e32 v185, v60, v184
	v_mul_f32_e32 v186, v61, v190
	v_mul_f32_e32 v184, v62, v191
	v_add_f32_e32 v190, 1.0, v193
	v_mul_f32_e32 v191, 0xbfb8aa3b, v64
	v_mul_f32_e32 v193, 0xbfb8aa3b, v65
	v_rcp_f32_e32 v225, v225
	v_exp_f32_e32 v230, v226
	v_add_f32_e32 v234, 1.0, v234
	v_add_f32_e32 v235, 1.0, v235
	v_rcp_f32_e32 v237, v236
	v_mul_f32_e32 v236, 0xbfb8aa3b, v96
	v_add_f32_e32 v159, 1.0, v159
	v_add_f32_e32 v160, 1.0, v160
	v_add_f32_e32 v162, 1.0, v162
	v_add_f32_e32 v163, 1.0, v163
	v_add_f32_e32 v164, 1.0, v164
	v_exp_f32_e32 v176, v176
	v_exp_f32_e32 v177, v177
	v_exp_f32_e32 v191, v191
	v_exp_f32_e32 v193, v193
	v_mul_f32_e32 v196, 0xbfb8aa3b, v66
	v_mul_f32_e32 v198, 0xbfb8aa3b, v67
	v_mul_f32_e32 v199, 0xbfb8aa3b, v68
	v_rcp_f32_e32 v234, v234
	v_rcp_f32_e32 v235, v235
	v_exp_f32_e32 v238, v236
	v_add_f32_e32 v152, 1.0, v152
	v_add_f32_e32 v153, 1.0, v153
	v_rcp_f32_e32 v158, v158
	v_rcp_f32_e32 v159, v159
	v_rcp_f32_e32 v160, v160
	v_rcp_f32_e32 v162, v162
	v_rcp_f32_e32 v163, v163
	v_rcp_f32_e32 v164, v164
	v_exp_f32_e32 v196, v196
	v_exp_f32_e32 v198, v198
	v_exp_f32_e32 v199, v199
	v_mul_f32_e32 v210, v69, v207
	v_mul_f32_e32 v207, v70, v208
	v_mul_f32_e32 v208, v71, v211
	v_add_f32_e32 v211, 1.0, v212
	v_mul_f32_e32 v212, 0xbfb8aa3b, v73
	v_mul_f32_e32 v213, 0xbfb8aa3b, v74
	v_mul_f32_e32 v216, 0xbfb8aa3b, v75
	v_mul_f32_e32 v217, 0xbfb8aa3b, v76
	v_mul_f32_e32 v218, 0xbfb8aa3b, v77
	v_rcp_f32_e32 v152, v152
	v_rcp_f32_e32 v153, v153
	v_exp_f32_e32 v212, v212
	v_exp_f32_e32 v213, v213
	v_exp_f32_e32 v216, v216
	v_exp_f32_e32 v217, v217
	v_exp_f32_e32 v218, v218
	v_mul_f32_e32 v219, 0xbfb8aa3b, v78
	v_mul_f32_e32 v220, 0xbfb8aa3b, v79
	v_mul_f32_e32 v221, 0xbfb8aa3b, v80
	v_mul_f32_e32 v222, 0xbfb8aa3b, v81
	v_mul_f32_e32 v223, 0xbfb8aa3b, v82
	v_mul_f32_e32 v224, 0xbfb8aa3b, v83
	v_add_f32_e32 v165, 1.0, v165
	v_add_f32_e32 v166, 1.0, v166
	v_add_f32_e32 v167, 1.0, v167
	v_add_f32_e32 v175, 1.0, v175
	v_exp_f32_e32 v219, v219
	v_exp_f32_e32 v220, v220
	v_exp_f32_e32 v221, v221
	v_exp_f32_e32 v222, v222
	v_exp_f32_e32 v223, v223
	v_exp_f32_e32 v224, v224
	v_mul_f32_e32 v226, v84, v225
	v_mul_f32_e32 v227, v85, v228
	v_mul_f32_e32 v225, v86, v229
	v_add_f32_e32 v228, 1.0, v230
	v_mul_f32_e32 v229, 0xbfb8aa3b, v88
	v_mul_f32_e32 v230, 0xbfb8aa3b, v89
	v_mul_f32_e32 v231, 0xbfb8aa3b, v90
	v_mul_f32_e32 v232, 0xbfb8aa3b, v91
	v_mul_f32_e32 v233, 0xbfb8aa3b, v92
	v_rcp_f32_e32 v165, v165
	v_rcp_f32_e32 v166, v166
	v_rcp_f32_e32 v167, v167
	v_rcp_f32_e32 v175, v175
	v_add_f32_e32 v176, 1.0, v176
	v_add_f32_e32 v177, 1.0, v177
	v_add_f32_e32 v191, 1.0, v191
	v_add_f32_e32 v193, 1.0, v193
	v_exp_f32_e32 v229, v229
	v_exp_f32_e32 v230, v230
	v_exp_f32_e32 v231, v231
	v_exp_f32_e32 v232, v232
	v_exp_f32_e32 v233, v233
	v_mul_f32_e32 v236, v93, v234
	v_mul_f32_e32 v234, v94, v235
	v_mul_f32_e32 v235, v95, v237
	v_add_f32_e32 v237, 1.0, v238
	v_mul_f32_e32 v238, 0xbfb8aa3b, v97
	v_mul_f32_e32 v239, 0xbfb8aa3b, v98
	global_store_dwordx4 v[154:155], v[168:171], off nt
	v_cvt_pk_bf16_f32 v150, v150, v151
	v_mul_f32_e32 v158, v48, v158
	v_mul_f32_e32 v159, v49, v159
	v_mul_f32_e32 v160, v50, v160
	v_mul_f32_e32 v162, v51, v162
	v_mul_f32_e32 v163, v52, v163
	v_mul_f32_e32 v164, v53, v164
	v_rcp_f32_e32 v176, v176
	v_rcp_f32_e32 v177, v177
	v_rcp_f32_e32 v190, v190
	v_rcp_f32_e32 v191, v191
	v_rcp_f32_e32 v193, v193
	v_add_f32_e32 v196, 1.0, v196
	v_add_f32_e32 v198, 1.0, v198
	v_add_f32_e32 v199, 1.0, v199
	v_exp_f32_e32 v238, v238
	v_exp_f32_e32 v239, v239
	v_mul_f32_e32 v194, 0xbfb8aa3b, v104
	v_mul_f32_e32 v192, 0xbfb8aa3b, v108
	v_mul_f32_e32 v168, v120, v152
	v_mul_f32_e32 v169, v121, v153
	v_cvt_pk_bf16_f32 v151, v158, v159
	v_cvt_pk_bf16_f32 v152, v160, v162
	v_cvt_pk_bf16_f32 v153, v163, v164
	global_store_dwordx4 v[154:155], v[150:153], off offset:256 nt
	v_rcp_f32_e32 v196, v196
	v_rcp_f32_e32 v198, v198
	v_or_b32_e32 v150, 48, v140
	v_rcp_f32_e32 v199, v199
	v_add_f32_e32 v212, 1.0, v212
	v_add_f32_e32 v213, 1.0, v213
	v_add_f32_e32 v216, 1.0, v216
	v_add_f32_e32 v217, 1.0, v217
	v_add_f32_e32 v218, 1.0, v218
	v_exp_f32_e32 v194, v194
	v_exp_f32_e32 v192, v192
	v_ashrrev_i32_e32 v151, 31, v150
	v_rcp_f32_e32 v211, v211
	v_rcp_f32_e32 v212, v212
	v_rcp_f32_e32 v213, v213
	v_rcp_f32_e32 v216, v216
	v_rcp_f32_e32 v217, v217
	v_rcp_f32_e32 v218, v218
	v_add_f32_e32 v219, 1.0, v219
	v_add_f32_e32 v220, 1.0, v220
	v_add_f32_e32 v221, 1.0, v221
	v_add_f32_e32 v222, 1.0, v222
	v_add_f32_e32 v223, 1.0, v223
	v_add_f32_e32 v224, 1.0, v224
	v_mul_f32_e32 v172, 0xbfb8aa3b, v131
	v_mul_f32_e32 v149, 0xbfb8aa3b, v124
	v_lshlrev_b64 v[150:151], 13, v[150:151]
	v_mul_f32_e32 v165, v54, v165
	v_mul_f32_e32 v166, v55, v166
	v_mul_f32_e32 v167, v56, v167
	v_mul_f32_e32 v175, v57, v175
	v_rcp_f32_e32 v219, v219
	v_rcp_f32_e32 v220, v220
	v_rcp_f32_e32 v221, v221
	v_rcp_f32_e32 v222, v222
	v_rcp_f32_e32 v223, v223
	v_rcp_f32_e32 v224, v224
	v_add_f32_e32 v229, 1.0, v229
	v_add_f32_e32 v230, 1.0, v230
	v_add_f32_e32 v231, 1.0, v231
	v_add_f32_e32 v232, 1.0, v232
	v_add_f32_e32 v233, 1.0, v233
	v_exp_f32_e32 v172, v172
	v_exp_f32_e32 v149, v149
	v_lshl_add_u64 v[154:155], v[146:147], 0, v[150:151]
	v_cvt_pk_bf16_f32 v150, v165, v166
	v_cvt_pk_bf16_f32 v151, v167, v175
	v_mul_f32_e32 v176, v58, v176
	v_mul_f32_e32 v177, v59, v177
	v_mul_f32_e32 v190, v63, v190
	v_mul_f32_e32 v191, v64, v191
	v_mul_f32_e32 v193, v65, v193
	v_rcp_f32_e32 v228, v228
	v_rcp_f32_e32 v229, v229
	v_rcp_f32_e32 v230, v230
	v_rcp_f32_e32 v231, v231
	v_rcp_f32_e32 v232, v232
	v_rcp_f32_e32 v233, v233
	v_add_f32_e32 v238, 1.0, v238
	v_add_f32_e32 v239, 1.0, v239
	v_cvt_pk_bf16_f32 v152, v176, v177
	v_cvt_pk_bf16_f32 v153, v185, v186
	global_store_dwordx4 v[154:155], v[150:153], off nt
	v_mul_f32_e32 v196, v66, v196
	v_mul_f32_e32 v198, v67, v198
	v_cvt_pk_bf16_f32 v150, v184, v190
	v_cvt_pk_bf16_f32 v151, v191, v193
	v_mul_f32_e32 v199, v68, v199
	v_rcp_f32_e32 v237, v237
	v_rcp_f32_e32 v238, v238
	v_rcp_f32_e32 v239, v239
	v_add_f32_e32 v194, 1.0, v194
	v_add_f32_e32 v192, 1.0, v192
	v_cvt_pk_bf16_f32 v152, v196, v198
	v_cvt_pk_bf16_f32 v153, v199, v210
	global_store_dwordx4 v[154:155], v[150:153], off offset:256 nt
	v_mul_f32_e32 v211, v72, v211
	v_mul_f32_e32 v212, v73, v212
	v_lshlrev_b64 v[150:151], 13, v[142:143]
	v_mul_f32_e32 v213, v74, v213
	v_mul_f32_e32 v216, v75, v216
	v_mul_f32_e32 v217, v76, v217
	v_mul_f32_e32 v218, v77, v218
	v_rcp_f32_e32 v194, v194
	v_rcp_f32_e32 v192, v192
	v_lshl_add_u64 v[146:147], v[146:147], 0, v[150:151]
	v_cvt_pk_bf16_f32 v150, v207, v208
	v_cvt_pk_bf16_f32 v151, v211, v212
	v_cvt_pk_bf16_f32 v152, v213, v216
	v_cvt_pk_bf16_f32 v153, v217, v218
	v_add_co_u32_e32 v154, vcc, s72, v144
	v_mul_f32_e32 v219, v78, v219
	v_mul_f32_e32 v220, v79, v220
	v_mul_f32_e32 v221, v80, v221
	v_mul_f32_e32 v222, v81, v222
	v_mul_f32_e32 v223, v82, v223
	v_mul_f32_e32 v224, v83, v224
	v_add_f32_e32 v172, 1.0, v172
	v_add_f32_e32 v149, 1.0, v149
	global_store_dwordx4 v[146:147], v[150:153], off nt
	s_mov_b64 s[26:27], 0x120000
	v_addc_co_u32_e32 v155, vcc, 0, v145, vcc
	v_cvt_pk_bf16_f32 v150, v219, v220
	v_cvt_pk_bf16_f32 v151, v221, v222
	v_cvt_pk_bf16_f32 v152, v223, v224
	v_cvt_pk_bf16_f32 v153, v226, v227
	global_store_dwordx4 v[146:147], v[150:153], off offset:256 nt
	v_mul_f32_e32 v228, v87, v228
	v_mul_f32_e32 v229, v88, v229
	v_mul_f32_e32 v230, v89, v230
	v_mul_f32_e32 v231, v90, v231
	v_mul_f32_e32 v232, v91, v232
	v_mul_f32_e32 v233, v92, v233
	v_rcp_f32_e32 v172, v172
	v_rcp_f32_e32 v149, v149
	v_rcp_f32_e32 v161, v189
	v_lshl_add_u64 v[146:147], v[144:145], 0, s[26:27]
	v_cvt_pk_bf16_f32 v150, v225, v228
	v_cvt_pk_bf16_f32 v151, v229, v230
	v_cvt_pk_bf16_f32 v152, v231, v232
	v_cvt_pk_bf16_f32 v153, v233, v236
	global_store_dwordx4 v[154:155], v[150:153], off nt
	s_mov_b64 s[26:27], 0x140000
	v_add_co_u32_e32 v154, vcc, s73, v144
	v_mul_f32_e32 v237, v96, v237
	v_mul_f32_e32 v238, v97, v238
	v_mul_f32_e32 v239, v98, v239
	v_mul_f32_e32 v195, v99, v195
	v_cvt_pk_bf16_f32 v150, v234, v235
	v_cvt_pk_bf16_f32 v151, v237, v238
	v_cvt_pk_bf16_f32 v152, v239, v195
	v_cvt_pk_bf16_f32 v153, v206, v209
	global_store_dwordx4 v[146:147], v[150:153], off offset:256 nt
	v_lshl_add_u64 v[146:147], v[144:145], 0, s[26:27]
	v_addc_co_u32_e32 v155, vcc, 0, v145, vcc
	s_mov_b64 s[26:27], 0x160000
	v_mul_f32_e32 v194, v104, v194
	v_mul_f32_e32 v192, v108, v192
	v_cvt_pk_bf16_f32 v150, v241, v242
	v_cvt_pk_bf16_f32 v151, v194, v197
	v_cvt_pk_bf16_f32 v152, v240, v243
	v_cvt_pk_bf16_f32 v153, v192, v204
	global_store_dwordx4 v[154:155], v[150:153], off nt
	v_lshl_add_u64 v[154:155], v[144:145], 0, s[26:27]
	v_add_co_u32_e32 v144, vcc, 0x160000, v144
	v_mul_f32_e32 v173, v117, v173
	v_cvt_pk_bf16_f32 v150, v205, v187
	v_cvt_pk_bf16_f32 v151, v244, v245
	v_cvt_pk_bf16_f32 v152, v182, v200
	v_cvt_pk_bf16_f32 v153, v201, v173
	global_store_dwordx4 v[146:147], v[150:153], off offset:256 nt
	v_addc_co_u32_e32 v145, vcc, 0, v145, vcc
	v_mul_f32_e32 v172, v131, v172
	v_mul_f32_e32 v149, v124, v149
	v_mul_f32_e32 v157, v118, v157
	v_mul_f32_e32 v161, v119, v161
	v_cvt_pk_bf16_f32 v150, v183, v172
	v_cvt_pk_bf16_f32 v151, v174, v202
	v_cvt_pk_bf16_f32 v152, v203, v178
	v_cvt_pk_bf16_f32 v153, v179, v180
	global_store_dwordx4 v[144:145], v[150:153], off nt
	v_cvt_pk_bf16_f32 v144, v181, v188
	v_cvt_pk_bf16_f32 v145, v149, v156
	v_cvt_pk_bf16_f32 v146, v157, v161
	v_cvt_pk_bf16_f32 v147, v168, v169
	global_store_dwordx4 v[154:155], v[144:147], off offset:256 nt
	s_mov_b64 s[26:27], 0

.LBB0_346:
	s_add_u32 s54, s33, 0xffffff80
	s_addc_u32 s55, s52, -1
	s_cmp_eq_u32 s53, 60
	s_cselect_b32 s28, s2, s33
	s_cselect_b32 s29, s1, s52
	s_cselect_b32 s31, s11, s23
	s_cselect_b32 s30, s15, s19
	s_add_u32 s24, s28, 0x80
	s_addc_u32 s25, s29, 0
	s_add_u32 s26, s30, 0x80
	s_addc_u32 s27, s31, 0
	s_add_i32 s56, 0, 0x10000
	s_add_i32 s57, 0, 0x14000
	v_add_u32_e32 v152, s56, v1
	v_add_u32_e32 v168, s57, v1
	ds_read_b128 v[140:143], v152
	ds_read_b128 v[144:147], v152 offset:1024
	ds_read_b128 v[148:151], v152 offset:2048
	ds_read_b128 v[152:155], v152 offset:3072
	ds_read_b128 v[156:159], v168
	ds_read_b128 v[160:163], v168 offset:1024
	ds_read_b128 v[164:167], v168 offset:2048
	ds_read_b128 v[168:171], v168 offset:3072
	s_add_u32 s54, s54, 0x100000
	s_addc_u32 s55, s55, 0
	v_lshl_add_u64 v[204:205], s[54:55], 0, v[2:3]
	s_add_i32 m0, s41, 0xc000
	ds_read_b128 v[172:175], v5
	ds_read_b128 v[176:179], v5 offset:1024
	ds_read_b128 v[180:183], v5 offset:2048
	ds_read_b128 v[184:187], v5 offset:3072
	ds_read_b128 v[188:191], v5 offset:4096
	ds_read_b128 v[192:195], v5 offset:5120
	ds_read_b128 v[196:199], v5 offset:6144
	ds_read_b128 v[200:203], v5 offset:7168
	global_load_lds_dwordx4 v[204:205], off
	v_lshl_add_u64 v[204:205], s[54:55], 0, v[136:137]
	s_add_i32 m0, s41, 0xe000
	s_nop 0
	global_load_lds_dwordx4 v[204:205], off
	s_waitcnt vmcnt(8)
	s_waitcnt lgkmcnt(0)
	s_barrier
	s_setprio 1
	s_waitcnt lgkmcnt(0)
	v_mfma_f32_16x16x32_bf16 v[130:133], v[140:143], v[172:175], v[130:133]
	v_mfma_f32_16x16x32_bf16 v[126:129], v[148:151], v[172:175], v[126:129]
	v_mfma_f32_16x16x32_bf16 v[114:117], v[140:143], v[180:183], v[114:117]
	v_mfma_f32_16x16x32_bf16 v[110:113], v[148:151], v[180:183], v[110:113]
	v_mfma_f32_16x16x32_bf16 v[98:101], v[140:143], v[188:191], v[98:101]
	v_mfma_f32_16x16x32_bf16 v[94:97], v[148:151], v[188:191], v[94:97]
	v_mfma_f32_16x16x32_bf16 v[82:85], v[140:143], v[196:199], v[82:85]
	v_mfma_f32_16x16x32_bf16 v[78:81], v[148:151], v[196:199], v[78:81]
	v_mfma_f32_16x16x32_bf16 v[130:133], v[144:147], v[176:179], v[130:133]
	v_mfma_f32_16x16x32_bf16 v[126:129], v[152:155], v[176:179], v[126:129]
	v_mfma_f32_16x16x32_bf16 v[114:117], v[144:147], v[184:187], v[114:117]
	v_mfma_f32_16x16x32_bf16 v[110:113], v[152:155], v[184:187], v[110:113]
	v_mfma_f32_16x16x32_bf16 v[98:101], v[144:147], v[192:195], v[98:101]
	v_mfma_f32_16x16x32_bf16 v[94:97], v[152:155], v[192:195], v[94:97]
	v_mfma_f32_16x16x32_bf16 v[82:85], v[144:147], v[200:203], v[82:85]
	v_mfma_f32_16x16x32_bf16 v[78:81], v[152:155], v[200:203], v[78:81]
	v_mfma_f32_16x16x32_bf16 v[122:125], v[156:159], v[172:175], v[122:125]
	v_mfma_f32_16x16x32_bf16 v[118:121], v[164:167], v[172:175], v[118:121]
	v_mfma_f32_16x16x32_bf16 v[106:109], v[156:159], v[180:183], v[106:109]
	v_mfma_f32_16x16x32_bf16 v[102:105], v[164:167], v[180:183], v[102:105]
	v_mfma_f32_16x16x32_bf16 v[90:93], v[156:159], v[188:191], v[90:93]
	v_mfma_f32_16x16x32_bf16 v[86:89], v[164:167], v[188:191], v[86:89]
	v_mfma_f32_16x16x32_bf16 v[74:77], v[156:159], v[196:199], v[74:77]
	v_mfma_f32_16x16x32_bf16 v[70:73], v[164:167], v[196:199], v[70:73]
	v_mfma_f32_16x16x32_bf16 v[122:125], v[160:163], v[176:179], v[122:125]
	v_mfma_f32_16x16x32_bf16 v[118:121], v[168:171], v[176:179], v[118:121]
	v_mfma_f32_16x16x32_bf16 v[106:109], v[160:163], v[184:187], v[106:109]
	v_mfma_f32_16x16x32_bf16 v[102:105], v[168:171], v[184:187], v[102:105]
	v_mfma_f32_16x16x32_bf16 v[90:93], v[160:163], v[192:195], v[90:93]
	v_mfma_f32_16x16x32_bf16 v[86:89], v[168:171], v[192:195], v[86:89]
	v_mfma_f32_16x16x32_bf16 v[74:77], v[160:163], v[200:203], v[74:77]
	v_mfma_f32_16x16x32_bf16 v[70:73], v[168:171], v[200:203], v[70:73]
	s_setprio 0
	s_barrier
	s_add_i32 s54, s56, s38
	v_lshl_add_u64 v[204:205], s[30:31], 0, v[134:135]
	s_mov_b32 m0, s54
	ds_read_b128 v[172:175], v5 offset:16384
	ds_read_b128 v[176:179], v5 offset:17408
	ds_read_b128 v[180:183], v5 offset:18432
	ds_read_b128 v[184:187], v5 offset:19456
	ds_read_b128 v[188:191], v5 offset:20480
	ds_read_b128 v[192:195], v5 offset:21504
	ds_read_b128 v[196:199], v5 offset:22528
	ds_read_b128 v[200:203], v5 offset:23552
	global_load_lds_dwordx4 v[204:205], off
	s_add_i32 m0, s54, 0x2000
	v_lshl_add_u64 v[204:205], s[30:31], 0, v[138:139]
	s_add_u32 s30, s30, 0x100000
	s_addc_u32 s31, s31, 0
	s_add_i32 s54, s57, s38
	global_load_lds_dwordx4 v[204:205], off
	v_lshl_add_u64 v[204:205], s[30:31], 0, v[134:135]
	s_mov_b32 m0, s54
	s_nop 0
	global_load_lds_dwordx4 v[204:205], off
	v_lshl_add_u64 v[204:205], s[30:31], 0, v[138:139]
	s_add_i32 m0, s54, 0x2000
	s_nop 0
	global_load_lds_dwordx4 v[204:205], off
	v_lshl_add_u64 v[204:205], s[28:29], 0, v[2:3]
	s_mov_b32 m0, s41
	s_nop 0
	global_load_lds_dwordx4 v[204:205], off
	v_lshl_add_u64 v[204:205], s[28:29], 0, v[136:137]
	s_mov_b32 m0, s3
	s_nop 0
	global_load_lds_dwordx4 v[204:205], off
	s_waitcnt vmcnt(8)
	s_waitcnt lgkmcnt(0)
	s_barrier
	s_setprio 1
	s_waitcnt lgkmcnt(0)
	v_mfma_f32_16x16x32_bf16 v[66:69], v[140:143], v[172:175], v[66:69]
	v_mfma_f32_16x16x32_bf16 v[62:65], v[148:151], v[172:175], v[62:65]
	v_mfma_f32_16x16x32_bf16 v[50:53], v[140:143], v[180:183], v[50:53]
	v_mfma_f32_16x16x32_bf16 v[46:49], v[148:151], v[180:183], v[46:49]
	v_mfma_f32_16x16x32_bf16 v[34:37], v[140:143], v[188:191], v[34:37]
	v_mfma_f32_16x16x32_bf16 v[30:33], v[148:151], v[188:191], v[30:33]
	v_mfma_f32_16x16x32_bf16 v[18:21], v[140:143], v[196:199], v[18:21]
	v_mfma_f32_16x16x32_bf16 v[14:17], v[148:151], v[196:199], v[14:17]
	v_mfma_f32_16x16x32_bf16 v[66:69], v[144:147], v[176:179], v[66:69]
	v_mfma_f32_16x16x32_bf16 v[62:65], v[152:155], v[176:179], v[62:65]
	v_mfma_f32_16x16x32_bf16 v[50:53], v[144:147], v[184:187], v[50:53]
	v_mfma_f32_16x16x32_bf16 v[46:49], v[152:155], v[184:187], v[46:49]
	v_mfma_f32_16x16x32_bf16 v[34:37], v[144:147], v[192:195], v[34:37]
	v_mfma_f32_16x16x32_bf16 v[30:33], v[152:155], v[192:195], v[30:33]
	v_mfma_f32_16x16x32_bf16 v[18:21], v[144:147], v[200:203], v[18:21]
	v_mfma_f32_16x16x32_bf16 v[14:17], v[152:155], v[200:203], v[14:17]
	v_mfma_f32_16x16x32_bf16 v[58:61], v[156:159], v[172:175], v[58:61]
	v_mfma_f32_16x16x32_bf16 v[54:57], v[164:167], v[172:175], v[54:57]
	v_mfma_f32_16x16x32_bf16 v[42:45], v[156:159], v[180:183], v[42:45]
	v_mfma_f32_16x16x32_bf16 v[38:41], v[164:167], v[180:183], v[38:41]
	v_mfma_f32_16x16x32_bf16 v[26:29], v[156:159], v[188:191], v[26:29]
	v_mfma_f32_16x16x32_bf16 v[22:25], v[164:167], v[188:191], v[22:25]
	v_mfma_f32_16x16x32_bf16 v[10:13], v[156:159], v[196:199], v[10:13]
	v_mfma_f32_16x16x32_bf16 v[6:9], v[164:167], v[196:199], v[6:9]
	v_mfma_f32_16x16x32_bf16 v[58:61], v[160:163], v[176:179], v[58:61]
	v_mfma_f32_16x16x32_bf16 v[54:57], v[168:171], v[176:179], v[54:57]
	v_mfma_f32_16x16x32_bf16 v[42:45], v[160:163], v[184:187], v[42:45]
	v_mfma_f32_16x16x32_bf16 v[38:41], v[168:171], v[184:187], v[38:41]
	v_mfma_f32_16x16x32_bf16 v[26:29], v[160:163], v[192:195], v[26:29]
	v_mfma_f32_16x16x32_bf16 v[22:25], v[168:171], v[192:195], v[22:25]
	v_mfma_f32_16x16x32_bf16 v[10:13], v[160:163], v[200:203], v[10:13]
	v_mfma_f32_16x16x32_bf16 v[6:9], v[168:171], v[200:203], v[6:9]
	s_setprio 0
	s_barrier
	s_add_i32 s30, 0, 0x18000
	s_add_i32 s31, 0, 0x1c000
	v_add_u32_e32 v152, s30, v1
	v_add_u32_e32 v168, s31, v1
	ds_read_b128 v[140:143], v152
	ds_read_b128 v[144:147], v152 offset:1024
	ds_read_b128 v[148:151], v152 offset:2048
	ds_read_b128 v[152:155], v152 offset:3072
	ds_read_b128 v[156:159], v168
	ds_read_b128 v[160:163], v168 offset:1024
	ds_read_b128 v[164:167], v168 offset:2048
	ds_read_b128 v[168:171], v168 offset:3072
	s_add_u32 s28, s28, 0x100000
	s_addc_u32 s29, s29, 0
	s_mov_b32 m0, s43
	v_lshl_add_u64 v[204:205], s[28:29], 0, v[2:3]
	ds_read_b128 v[172:175], v5 offset:32768
	ds_read_b128 v[176:179], v5 offset:33792
	ds_read_b128 v[180:183], v5 offset:34816
	ds_read_b128 v[184:187], v5 offset:35840
	ds_read_b128 v[188:191], v5 offset:36864
	ds_read_b128 v[192:195], v5 offset:37888
	ds_read_b128 v[196:199], v5 offset:38912
	ds_read_b128 v[200:203], v5 offset:39936
	global_load_lds_dwordx4 v[204:205], off
	v_lshl_add_u64 v[204:205], s[28:29], 0, v[136:137]
	s_mov_b32 m0, s46
	s_nop 0
	global_load_lds_dwordx4 v[204:205], off
	s_waitcnt vmcnt(8)
	s_waitcnt lgkmcnt(0)
	s_barrier
	s_setprio 1
	s_waitcnt lgkmcnt(0)
	v_mfma_f32_16x16x32_bf16 v[130:133], v[140:143], v[172:175], v[130:133]
	v_mfma_f32_16x16x32_bf16 v[126:129], v[148:151], v[172:175], v[126:129]
	v_mfma_f32_16x16x32_bf16 v[114:117], v[140:143], v[180:183], v[114:117]
	v_mfma_f32_16x16x32_bf16 v[110:113], v[148:151], v[180:183], v[110:113]
	v_mfma_f32_16x16x32_bf16 v[98:101], v[140:143], v[188:191], v[98:101]
	v_mfma_f32_16x16x32_bf16 v[94:97], v[148:151], v[188:191], v[94:97]
	v_mfma_f32_16x16x32_bf16 v[82:85], v[140:143], v[196:199], v[82:85]
	v_mfma_f32_16x16x32_bf16 v[78:81], v[148:151], v[196:199], v[78:81]
	v_mfma_f32_16x16x32_bf16 v[130:133], v[144:147], v[176:179], v[130:133]
	v_mfma_f32_16x16x32_bf16 v[126:129], v[152:155], v[176:179], v[126:129]
	v_mfma_f32_16x16x32_bf16 v[114:117], v[144:147], v[184:187], v[114:117]
	v_mfma_f32_16x16x32_bf16 v[110:113], v[152:155], v[184:187], v[110:113]
	v_mfma_f32_16x16x32_bf16 v[98:101], v[144:147], v[192:195], v[98:101]
	v_mfma_f32_16x16x32_bf16 v[94:97], v[152:155], v[192:195], v[94:97]
	v_mfma_f32_16x16x32_bf16 v[82:85], v[144:147], v[200:203], v[82:85]
	v_mfma_f32_16x16x32_bf16 v[78:81], v[152:155], v[200:203], v[78:81]
	v_mfma_f32_16x16x32_bf16 v[122:125], v[156:159], v[172:175], v[122:125]
	v_mfma_f32_16x16x32_bf16 v[118:121], v[164:167], v[172:175], v[118:121]
	v_mfma_f32_16x16x32_bf16 v[106:109], v[156:159], v[180:183], v[106:109]
	v_mfma_f32_16x16x32_bf16 v[102:105], v[164:167], v[180:183], v[102:105]
	v_mfma_f32_16x16x32_bf16 v[90:93], v[156:159], v[188:191], v[90:93]
	v_mfma_f32_16x16x32_bf16 v[86:89], v[164:167], v[188:191], v[86:89]
	v_mfma_f32_16x16x32_bf16 v[74:77], v[156:159], v[196:199], v[74:77]
	v_mfma_f32_16x16x32_bf16 v[70:73], v[164:167], v[196:199], v[70:73]
	v_mfma_f32_16x16x32_bf16 v[122:125], v[160:163], v[176:179], v[122:125]
	v_mfma_f32_16x16x32_bf16 v[118:121], v[168:171], v[176:179], v[118:121]
	v_mfma_f32_16x16x32_bf16 v[106:109], v[160:163], v[184:187], v[106:109]
	v_mfma_f32_16x16x32_bf16 v[102:105], v[168:171], v[184:187], v[102:105]
	v_mfma_f32_16x16x32_bf16 v[90:93], v[160:163], v[192:195], v[90:93]
	v_mfma_f32_16x16x32_bf16 v[86:89], v[168:171], v[192:195], v[86:89]
	v_mfma_f32_16x16x32_bf16 v[74:77], v[160:163], v[200:203], v[74:77]
	v_mfma_f32_16x16x32_bf16 v[70:73], v[168:171], v[200:203], v[70:73]
	s_setprio 0
	s_barrier
	s_add_i32 s28, s30, s38
	v_lshl_add_u64 v[204:205], s[26:27], 0, v[134:135]
	s_mov_b32 m0, s28
	ds_read_b128 v[172:175], v5 offset:49152
	ds_read_b128 v[176:179], v5 offset:50176
	ds_read_b128 v[180:183], v5 offset:51200
	ds_read_b128 v[184:187], v5 offset:52224
	ds_read_b128 v[188:191], v5 offset:53248
	ds_read_b128 v[192:195], v5 offset:54272
	ds_read_b128 v[196:199], v5 offset:55296
	ds_read_b128 v[200:203], v5 offset:56320
	global_load_lds_dwordx4 v[204:205], off
	s_add_i32 m0, s28, 0x2000
	v_lshl_add_u64 v[204:205], s[26:27], 0, v[138:139]
	s_add_u32 s26, s26, 0x100000
	s_addc_u32 s27, s27, 0
	s_add_i32 s28, s31, s38
	global_load_lds_dwordx4 v[204:205], off
	v_lshl_add_u64 v[204:205], s[26:27], 0, v[134:135]
	s_mov_b32 m0, s28
	s_nop 0
	global_load_lds_dwordx4 v[204:205], off
	v_lshl_add_u64 v[204:205], s[26:27], 0, v[138:139]
	s_add_i32 m0, s28, 0x2000
	s_nop 0
	global_load_lds_dwordx4 v[204:205], off
	v_lshl_add_u64 v[204:205], s[24:25], 0, v[2:3]
	s_mov_b32 m0, s49
	s_nop 0
	global_load_lds_dwordx4 v[204:205], off
	v_lshl_add_u64 v[204:205], s[24:25], 0, v[136:137]
	s_mov_b32 m0, s50
	s_nop 0
	global_load_lds_dwordx4 v[204:205], off
	s_waitcnt vmcnt(8)
	s_waitcnt lgkmcnt(0)
	s_barrier
	s_setprio 1
	s_waitcnt lgkmcnt(0)
	v_mfma_f32_16x16x32_bf16 v[66:69], v[140:143], v[172:175], v[66:69]
	v_mfma_f32_16x16x32_bf16 v[62:65], v[148:151], v[172:175], v[62:65]
	v_mfma_f32_16x16x32_bf16 v[50:53], v[140:143], v[180:183], v[50:53]
	v_mfma_f32_16x16x32_bf16 v[46:49], v[148:151], v[180:183], v[46:49]
	v_mfma_f32_16x16x32_bf16 v[34:37], v[140:143], v[188:191], v[34:37]
	v_mfma_f32_16x16x32_bf16 v[30:33], v[148:151], v[188:191], v[30:33]
	v_mfma_f32_16x16x32_bf16 v[18:21], v[140:143], v[196:199], v[18:21]
	v_mfma_f32_16x16x32_bf16 v[14:17], v[148:151], v[196:199], v[14:17]
	v_mfma_f32_16x16x32_bf16 v[66:69], v[144:147], v[176:179], v[66:69]
	v_mfma_f32_16x16x32_bf16 v[62:65], v[152:155], v[176:179], v[62:65]
	v_mfma_f32_16x16x32_bf16 v[50:53], v[144:147], v[184:187], v[50:53]
	v_mfma_f32_16x16x32_bf16 v[46:49], v[152:155], v[184:187], v[46:49]
	v_mfma_f32_16x16x32_bf16 v[34:37], v[144:147], v[192:195], v[34:37]
	v_mfma_f32_16x16x32_bf16 v[30:33], v[152:155], v[192:195], v[30:33]
	v_mfma_f32_16x16x32_bf16 v[18:21], v[144:147], v[200:203], v[18:21]
	v_mfma_f32_16x16x32_bf16 v[14:17], v[152:155], v[200:203], v[14:17]
	v_mfma_f32_16x16x32_bf16 v[58:61], v[156:159], v[172:175], v[58:61]
	v_mfma_f32_16x16x32_bf16 v[54:57], v[164:167], v[172:175], v[54:57]
	v_mfma_f32_16x16x32_bf16 v[42:45], v[156:159], v[180:183], v[42:45]
	v_mfma_f32_16x16x32_bf16 v[38:41], v[164:167], v[180:183], v[38:41]
	v_mfma_f32_16x16x32_bf16 v[26:29], v[156:159], v[188:191], v[26:29]
	v_mfma_f32_16x16x32_bf16 v[22:25], v[164:167], v[188:191], v[22:25]
	v_mfma_f32_16x16x32_bf16 v[10:13], v[156:159], v[196:199], v[10:13]
	v_mfma_f32_16x16x32_bf16 v[6:9], v[164:167], v[196:199], v[6:9]
	v_mfma_f32_16x16x32_bf16 v[58:61], v[160:163], v[176:179], v[58:61]
	v_mfma_f32_16x16x32_bf16 v[54:57], v[168:171], v[176:179], v[54:57]
	v_mfma_f32_16x16x32_bf16 v[42:45], v[160:163], v[184:187], v[42:45]
	v_mfma_f32_16x16x32_bf16 v[38:41], v[168:171], v[184:187], v[38:41]
	v_mfma_f32_16x16x32_bf16 v[26:29], v[160:163], v[192:195], v[26:29]
	v_mfma_f32_16x16x32_bf16 v[22:25], v[168:171], v[192:195], v[22:25]
	v_mfma_f32_16x16x32_bf16 v[10:13], v[160:163], v[200:203], v[10:13]
	v_mfma_f32_16x16x32_bf16 v[6:9], v[168:171], v[200:203], v[6:9]
	s_setprio 0
	s_barrier
	s_add_i32 s53, s53, 2
	s_add_u32 s19, s19, 0x100
	s_addc_u32 s23, s23, 0
	s_add_u32 s33, s33, 0x100
	s_addc_u32 s52, s52, 0
	s_cmp_gt_u32 s53, 61
	s_cbranch_scc0 .LBB0_346
	v_mov_b32_e32 v140, v0
	s_lshl_b32 s1, s0, 8
	s_mov_b64 s[24:25], s[84:85]
	s_add_i32 s1, s1, s47
	v_bfe_u32 v210, v140, 4, 2
	v_and_or_b32 v140, v140, 15, s1
	s_add_u32 s26, s24, s6
	s_addc_u32 s27, s25, s7
	v_ashrrev_i32_e32 v141, 31, v140
	v_lshl_add_u64 v[142:143], v[140:141], 2, s[26:27]
	s_mov_b64 s[26:27], 0x10000
	v_lshl_add_u64 v[154:155], v[142:143], 0, s[26:27]
	v_add_co_u32_e32 v142, vcc, s91, v142
	s_cmp_gt_i32 s22, 3
	s_nop 0
	v_addc_co_u32_e32 v143, vcc, 0, v143, vcc
	global_load_dword v142, v[142:143], off
	s_cselect_b64 s[28:29], -1, 0
	s_cmp_lt_i32 s22, 4
	s_cselect_b64 s[26:27], -1, 0
	global_load_dword v205, v[154:155], off offset:64
	global_load_dword v204, v[154:155], off offset:128
	global_load_dword v203, v[154:155], off offset:192
	global_load_dword v202, v[154:155], off offset:512
	global_load_dword v201, v[154:155], off offset:576
	global_load_dword v200, v[154:155], off offset:640
	global_load_dword v199, v[154:155], off offset:704
	s_waitcnt vmcnt(0)
	v_fmamk_f32 v142, v142, 0x39800000, v246
	v_cmp_gt_f32_e32 vcc, s95, v142
	v_mul_f32_e32 v143, 0x4b800000, v142
	s_nop 0
	v_cndmask_b32_e32 v142, v142, v143, vcc
	v_rsq_f32_e32 v142, v142
	s_nop 0
	v_mul_f32_e32 v143, 0x45800000, v142
	v_cndmask_b32_e32 v142, v142, v143, vcc
	v_pk_mul_f32 v[132:133], v[132:133], v[142:143] op_sel_hi:[1,0]
	v_pk_mul_f32 v[130:131], v[130:131], v[142:143] op_sel_hi:[1,0]
	v_pk_mul_f32 v[128:129], v[128:129], v[142:143] op_sel_hi:[1,0]
	v_pk_mul_f32 v[126:127], v[126:127], v[142:143] op_sel_hi:[1,0]
	v_pk_mul_f32 v[124:125], v[124:125], v[142:143] op_sel_hi:[1,0]
	v_pk_mul_f32 v[122:123], v[122:123], v[142:143] op_sel_hi:[1,0]
	v_pk_mul_f32 v[120:121], v[120:121], v[142:143] op_sel_hi:[1,0]
	v_pk_mul_f32 v[118:119], v[118:119], v[142:143] op_sel_hi:[1,0]
	s_waitcnt vmcnt(0)
	v_fmamk_f32 v142, v205, 0x39800000, v246
	v_cmp_gt_f32_e32 vcc, s95, v142
	v_mul_f32_e32 v143, 0x4b800000, v142
	s_nop 0
	v_cndmask_b32_e32 v142, v142, v143, vcc
	v_rsq_f32_e32 v142, v142
	s_nop 0
	v_mul_f32_e32 v143, 0x45800000, v142
	v_cndmask_b32_e32 v142, v142, v143, vcc
	v_pk_mul_f32 v[116:117], v[116:117], v[142:143] op_sel_hi:[1,0]
	v_pk_mul_f32 v[114:115], v[114:115], v[142:143] op_sel_hi:[1,0]
	v_pk_mul_f32 v[112:113], v[112:113], v[142:143] op_sel_hi:[1,0]
	v_pk_mul_f32 v[110:111], v[110:111], v[142:143] op_sel_hi:[1,0]
	v_pk_mul_f32 v[108:109], v[108:109], v[142:143] op_sel_hi:[1,0]
	v_pk_mul_f32 v[106:107], v[106:107], v[142:143] op_sel_hi:[1,0]
	v_pk_mul_f32 v[104:105], v[104:105], v[142:143] op_sel_hi:[1,0]
	v_pk_mul_f32 v[102:103], v[102:103], v[142:143] op_sel_hi:[1,0]
	s_waitcnt vmcnt(0)
	v_fmamk_f32 v142, v204, 0x39800000, v246
	v_cmp_gt_f32_e32 vcc, s95, v142
	v_mul_f32_e32 v143, 0x4b800000, v142
	s_nop 0
	v_cndmask_b32_e32 v142, v142, v143, vcc
	v_rsq_f32_e32 v142, v142
	s_nop 0
	v_mul_f32_e32 v143, 0x45800000, v142
	v_cndmask_b32_e32 v142, v142, v143, vcc
	v_pk_mul_f32 v[150:151], v[94:95], v[142:143] op_sel_hi:[1,0]
	v_pk_mul_f32 v[152:153], v[98:99], v[142:143] op_sel_hi:[1,0]
	v_pk_mul_f32 v[100:101], v[100:101], v[142:143] op_sel_hi:[1,0]
	v_pk_mul_f32 v[92:93], v[92:93], v[142:143] op_sel_hi:[1,0]
	v_pk_mul_f32 v[90:91], v[90:91], v[142:143] op_sel_hi:[1,0]
	v_pk_mul_f32 v[86:87], v[86:87], v[142:143] op_sel_hi:[1,0]
	v_pk_mul_f32 v[96:97], v[96:97], v[142:143] op_sel_hi:[1,0]
	v_pk_mul_f32 v[88:89], v[88:89], v[142:143] op_sel_hi:[1,0]
	s_waitcnt vmcnt(0)
	v_fmamk_f32 v94, v203, 0x39800000, v246
	v_cmp_gt_f32_e32 vcc, s95, v94
	v_mul_f32_e32 v95, 0x4b800000, v94
	s_nop 0
	v_cndmask_b32_e32 v94, v94, v95, vcc
	v_rsq_f32_e32 v94, v94
	s_nop 0
	v_mul_f32_e32 v95, 0x45800000, v94
	v_cndmask_b32_e32 v94, v94, v95, vcc
	v_pk_mul_f32 v[164:165], v[80:81], v[94:95] op_sel_hi:[1,0]
	v_pk_mul_f32 v[80:81], v[74:75], v[94:95] op_sel_hi:[1,0]
	v_pk_mul_f32 v[166:167], v[84:85], v[94:95] op_sel_hi:[1,0]
	v_pk_mul_f32 v[170:171], v[82:83], v[94:95] op_sel_hi:[1,0]
	v_pk_mul_f32 v[168:169], v[78:79], v[94:95] op_sel_hi:[1,0]
	v_pk_mul_f32 v[78:79], v[76:77], v[94:95] op_sel_hi:[1,0]
	v_pk_mul_f32 v[72:73], v[72:73], v[94:95] op_sel_hi:[1,0]
	v_pk_mul_f32 v[70:71], v[70:71], v[94:95] op_sel_hi:[1,0]
	s_waitcnt vmcnt(0)
	v_fmamk_f32 v74, v202, 0x39800000, v246
	v_cmp_gt_f32_e32 vcc, s95, v74
	v_mul_f32_e32 v75, 0x4b800000, v74
	s_nop 0
	v_cndmask_b32_e32 v74, v74, v75, vcc
	v_rsq_f32_e32 v74, v74
	s_nop 0
	v_mul_f32_e32 v75, 0x45800000, v74
	v_cndmask_b32_e32 v98, v74, v75, vcc
	v_pk_mul_f32 v[76:77], v[68:69], v[98:99] op_sel_hi:[1,0]
	v_pk_mul_f32 v[176:177], v[66:67], v[98:99] op_sel_hi:[1,0]
	v_pk_mul_f32 v[74:75], v[64:65], v[98:99] op_sel_hi:[1,0]
	v_pk_mul_f32 v[174:175], v[62:63], v[98:99] op_sel_hi:[1,0]
	v_pk_mul_f32 v[84:85], v[60:61], v[98:99] op_sel_hi:[1,0]
	v_pk_mul_f32 v[94:95], v[58:59], v[98:99] op_sel_hi:[1,0]
	v_pk_mul_f32 v[82:83], v[56:57], v[98:99] op_sel_hi:[1,0]
	v_pk_mul_f32 v[98:99], v[54:55], v[98:99] op_sel_hi:[1,0]
	s_waitcnt vmcnt(0)
	v_fmamk_f32 v54, v201, 0x39800000, v246
	v_cmp_gt_f32_e32 vcc, s95, v54
	v_mul_f32_e32 v55, 0x4b800000, v54
	s_nop 0
	v_cndmask_b32_e32 v54, v54, v55, vcc
	v_rsq_f32_e32 v54, v54
	s_nop 0
	v_mul_f32_e32 v55, 0x45800000, v54
	v_cndmask_b32_e32 v54, v54, v55, vcc
	v_pk_mul_f32 v[146:147], v[38:39], v[54:55] op_sel_hi:[1,0]
	v_pk_mul_f32 v[180:181], v[52:53], v[54:55] op_sel_hi:[1,0]
	v_pk_mul_f32 v[184:185], v[50:51], v[54:55] op_sel_hi:[1,0]
	v_pk_mul_f32 v[144:145], v[44:45], v[54:55] op_sel_hi:[1,0]
	v_pk_mul_f32 v[148:149], v[42:43], v[54:55] op_sel_hi:[1,0]
	v_pk_mul_f32 v[182:183], v[46:47], v[54:55] op_sel_hi:[1,0]
	v_pk_mul_f32 v[178:179], v[48:49], v[54:55] op_sel_hi:[1,0]
	v_pk_mul_f32 v[142:143], v[40:41], v[54:55] op_sel_hi:[1,0]
	s_waitcnt vmcnt(0)
	v_fmamk_f32 v38, v200, 0x39800000, v246
	v_cmp_gt_f32_e32 vcc, s95, v38
	v_mul_f32_e32 v39, 0x4b800000, v38
	s_nop 0
	v_cndmask_b32_e32 v38, v38, v39, vcc
	v_rsq_f32_e32 v38, v38
	s_nop 0
	v_mul_f32_e32 v39, 0x45800000, v38
	v_cndmask_b32_e32 v38, v38, v39, vcc
	v_pk_mul_f32 v[160:161], v[22:23], v[38:39] op_sel_hi:[1,0]
	v_pk_mul_f32 v[188:189], v[36:37], v[38:39] op_sel_hi:[1,0]
	v_pk_mul_f32 v[192:193], v[34:35], v[38:39] op_sel_hi:[1,0]
	v_pk_mul_f32 v[158:159], v[28:29], v[38:39] op_sel_hi:[1,0]
	v_pk_mul_f32 v[162:163], v[26:27], v[38:39] op_sel_hi:[1,0]
	v_pk_mul_f32 v[186:187], v[32:33], v[38:39] op_sel_hi:[1,0]
	v_pk_mul_f32 v[190:191], v[30:31], v[38:39] op_sel_hi:[1,0]
	v_pk_mul_f32 v[156:157], v[24:25], v[38:39] op_sel_hi:[1,0]
	v_mul_f32_e32 v24, v95, v95
	v_mul_f32_e32 v25, v85, v85
	v_mul_f32_e32 v26, v185, v185
	v_mul_f32_e32 v27, v181, v181
	v_mul_f32_e32 v28, v149, v149
	v_mul_f32_e32 v29, v145, v145
	v_mul_f32_e32 v30, v193, v193
	v_mul_f32_e32 v31, v189, v189
	v_mul_f32_e32 v32, v163, v163
	v_mul_f32_e32 v33, v159, v159
	v_fmac_f32_e32 v24, v94, v94
	v_fmac_f32_e32 v25, v84, v84
	v_fmac_f32_e32 v26, v184, v184
	v_fmac_f32_e32 v27, v180, v180
	v_fmac_f32_e32 v28, v148, v148
	v_fmac_f32_e32 v29, v144, v144
	v_fmac_f32_e32 v30, v192, v192
	v_fmac_f32_e32 v31, v188, v188
	v_fmac_f32_e32 v32, v162, v162
	v_fmac_f32_e32 v33, v158, v158
	v_add_f32_e32 v24, v24, v25
	v_mul_f32_e32 v25, v99, v99
	v_add_f32_e32 v26, v26, v27
	v_mul_f32_e32 v27, v183, v183
	v_add_f32_e32 v28, v28, v29
	v_mul_f32_e32 v29, v147, v147
	v_add_f32_e32 v30, v30, v31
	v_mul_f32_e32 v31, v191, v191
	v_add_f32_e32 v32, v32, v33
	v_mul_f32_e32 v33, v161, v161
	v_fmac_f32_e32 v25, v98, v98
	v_fmac_f32_e32 v27, v182, v182
	v_fmac_f32_e32 v29, v146, v146
	v_fmac_f32_e32 v31, v190, v190
	v_fmac_f32_e32 v33, v160, v160
	v_add_f32_e32 v24, v25, v24
	v_mul_f32_e32 v25, v83, v83
	v_add_f32_e32 v26, v27, v26
	v_mul_f32_e32 v27, v179, v179
	v_add_f32_e32 v28, v29, v28
	v_mul_f32_e32 v29, v143, v143
	v_add_f32_e32 v30, v31, v30
	v_mul_f32_e32 v31, v187, v187
	v_add_f32_e32 v32, v33, v32
	v_mul_f32_e32 v33, v157, v157
	v_fmac_f32_e32 v25, v82, v82
	v_fmac_f32_e32 v27, v178, v178
	v_fmac_f32_e32 v29, v142, v142
	v_fmac_f32_e32 v31, v186, v186
	v_fmac_f32_e32 v33, v156, v156
	v_add_f32_e32 v24, v25, v24
	v_add_f32_e32 v26, v27, v26
	v_add_f32_e32 v28, v29, v28
	v_add_f32_e32 v30, v31, v30
	v_add_f32_e32 v32, v33, v32
	ds_swizzle_b32 v25, v24 offset:swizzle(SWAP,16)
	ds_swizzle_b32 v27, v26 offset:swizzle(SWAP,16)
	ds_swizzle_b32 v29, v28 offset:swizzle(SWAP,16)
	ds_swizzle_b32 v31, v30 offset:swizzle(SWAP,16)
	ds_swizzle_b32 v33, v32 offset:swizzle(SWAP,16)
	s_waitcnt lgkmcnt(4)
	v_add_f32_e32 v24, v24, v25
	s_waitcnt lgkmcnt(3)
	v_add_f32_e32 v26, v26, v27
	s_waitcnt lgkmcnt(2)
	v_add_f32_e32 v28, v28, v29
	s_waitcnt lgkmcnt(1)
	v_add_f32_e32 v30, v30, v31
	s_waitcnt lgkmcnt(0)
	v_add_f32_e32 v32, v32, v33
	v_mov_b32_e32 v25, v24
	v_mov_b32_e32 v27, v26
	v_mov_b32_e32 v29, v28
	v_mov_b32_e32 v31, v30
	v_mov_b32_e32 v33, v32
	v_permlane32_swap_b32_e32 v24, v25
	s_waitcnt vmcnt(0)
	v_fmamk_f32 v22, v199, 0x39800000, v246
	v_cmp_gt_f32_e32 vcc, s95, v22
	v_mul_f32_e32 v23, 0x4b800000, v22
	v_permlane32_swap_b32_e32 v26, v27
	v_cndmask_b32_e32 v22, v22, v23, vcc
	v_rsq_f32_e32 v22, v22
	v_permlane32_swap_b32_e32 v28, v29
	v_permlane32_swap_b32_e32 v30, v31
	v_mul_f32_e32 v23, 0x45800000, v22
	v_cndmask_b32_e32 v22, v22, v23, vcc
	v_pk_mul_f32 v[202:203], v[20:21], v[22:23] op_sel_hi:[1,0]
	v_pk_mul_f32 v[204:205], v[18:19], v[22:23] op_sel_hi:[1,0]
	v_pk_mul_f32 v[194:195], v[12:13], v[22:23] op_sel_hi:[1,0]
	v_pk_mul_f32 v[196:197], v[10:11], v[22:23] op_sel_hi:[1,0]
	v_pk_mul_f32 v[206:207], v[16:17], v[22:23] op_sel_hi:[1,0]
	v_pk_mul_f32 v[208:209], v[14:15], v[22:23] op_sel_hi:[1,0]
	v_pk_mul_f32 v[198:199], v[8:9], v[22:23] op_sel_hi:[1,0]
	v_pk_mul_f32 v[200:201], v[6:7], v[22:23] op_sel_hi:[1,0]
	v_mul_f32_e32 v6, v131, v131
	v_mul_f32_e32 v7, v133, v133
	v_mul_f32_e32 v8, v123, v123
	v_mul_f32_e32 v9, v125, v125
	v_mul_f32_e32 v10, v115, v115
	v_mul_f32_e32 v11, v117, v117
	v_mul_f32_e32 v12, v107, v107
	v_mul_f32_e32 v13, v109, v109
	v_mul_f32_e32 v14, v153, v153
	v_mul_f32_e32 v15, v101, v101
	v_mul_f32_e32 v16, v91, v91
	v_mul_f32_e32 v17, v93, v93
	v_mul_f32_e32 v18, v171, v171
	v_mul_f32_e32 v19, v167, v167
	v_mul_f32_e32 v20, v81, v81
	v_mul_f32_e32 v21, v79, v79
	v_mul_f32_e32 v22, v177, v177
	v_mul_f32_e32 v23, v77, v77
	v_mul_f32_e32 v34, v205, v205
	v_mul_f32_e32 v35, v203, v203
	v_mul_f32_e32 v36, v197, v197
	v_mul_f32_e32 v37, v195, v195
	v_fmac_f32_e32 v6, v130, v130
	v_fmac_f32_e32 v7, v132, v132
	v_fmac_f32_e32 v8, v122, v122
	v_fmac_f32_e32 v9, v124, v124
	v_fmac_f32_e32 v10, v114, v114
	v_fmac_f32_e32 v11, v116, v116
	v_fmac_f32_e32 v12, v106, v106
	v_fmac_f32_e32 v13, v108, v108
	v_fmac_f32_e32 v14, v152, v152
	v_fmac_f32_e32 v15, v100, v100
	v_fmac_f32_e32 v16, v90, v90
	v_fmac_f32_e32 v17, v92, v92
	v_fmac_f32_e32 v18, v170, v170
	v_fmac_f32_e32 v19, v166, v166
	v_fmac_f32_e32 v20, v80, v80
	v_fmac_f32_e32 v21, v78, v78
	v_fmac_f32_e32 v22, v176, v176
	v_fmac_f32_e32 v23, v76, v76
	v_fmac_f32_e32 v34, v204, v204
	v_fmac_f32_e32 v35, v202, v202
	v_fmac_f32_e32 v36, v196, v196
	v_fmac_f32_e32 v37, v194, v194
	v_add_f32_e32 v6, v6, v7
	v_mul_f32_e32 v7, v127, v127
	v_add_f32_e32 v8, v8, v9
	v_mul_f32_e32 v9, v119, v119
	v_add_f32_e32 v10, v10, v11
	v_mul_f32_e32 v11, v111, v111
	v_add_f32_e32 v12, v12, v13
	v_mul_f32_e32 v13, v103, v103
	v_add_f32_e32 v14, v14, v15
	v_mul_f32_e32 v15, v151, v151
	v_add_f32_e32 v16, v16, v17
	v_mul_f32_e32 v17, v87, v87
	v_add_f32_e32 v18, v18, v19
	v_mul_f32_e32 v19, v169, v169
	v_add_f32_e32 v20, v20, v21
	v_mul_f32_e32 v21, v71, v71
	v_add_f32_e32 v22, v22, v23
	v_mul_f32_e32 v23, v175, v175
	v_add_f32_e32 v34, v34, v35
	v_mul_f32_e32 v35, v209, v209
	v_add_f32_e32 v36, v36, v37
	v_mul_f32_e32 v37, v201, v201
	v_fmac_f32_e32 v7, v126, v126
	v_fmac_f32_e32 v9, v118, v118
	v_fmac_f32_e32 v11, v110, v110
	v_fmac_f32_e32 v13, v102, v102
	v_fmac_f32_e32 v15, v150, v150
	v_fmac_f32_e32 v17, v86, v86
	v_fmac_f32_e32 v19, v168, v168
	v_fmac_f32_e32 v21, v70, v70
	v_fmac_f32_e32 v23, v174, v174
	v_fmac_f32_e32 v35, v208, v208
	v_fmac_f32_e32 v37, v200, v200
	v_add_f32_e32 v6, v7, v6
	v_mul_f32_e32 v7, v129, v129
	v_add_f32_e32 v8, v9, v8
	v_mul_f32_e32 v9, v121, v121
	v_add_f32_e32 v10, v11, v10
	v_mul_f32_e32 v11, v113, v113
	v_add_f32_e32 v12, v13, v12
	v_mul_f32_e32 v13, v105, v105
	v_add_f32_e32 v14, v15, v14
	v_mul_f32_e32 v15, v97, v97
	v_add_f32_e32 v16, v17, v16
	v_mul_f32_e32 v17, v89, v89
	v_add_f32_e32 v18, v19, v18
	v_mul_f32_e32 v19, v165, v165
	v_add_f32_e32 v20, v21, v20
	v_mul_f32_e32 v21, v73, v73
	v_add_f32_e32 v22, v23, v22
	v_mul_f32_e32 v23, v75, v75
	v_add_f32_e32 v34, v35, v34
	v_mul_f32_e32 v35, v207, v207
	v_add_f32_e32 v36, v37, v36
	v_mul_f32_e32 v37, v199, v199
	v_fmac_f32_e32 v7, v128, v128
	v_fmac_f32_e32 v9, v120, v120
	v_fmac_f32_e32 v11, v112, v112
	v_fmac_f32_e32 v13, v104, v104
	v_fmac_f32_e32 v15, v96, v96
	v_fmac_f32_e32 v17, v88, v88
	v_fmac_f32_e32 v19, v164, v164
	v_fmac_f32_e32 v21, v72, v72
	v_fmac_f32_e32 v23, v74, v74
	v_fmac_f32_e32 v35, v206, v206
	v_fmac_f32_e32 v37, v198, v198
	v_add_f32_e32 v6, v7, v6
	v_add_f32_e32 v8, v9, v8
	v_add_f32_e32 v10, v11, v10
	v_add_f32_e32 v12, v13, v12
	v_add_f32_e32 v14, v15, v14
	v_add_f32_e32 v16, v17, v16
	v_add_f32_e32 v18, v19, v18
	v_add_f32_e32 v20, v21, v20
	v_add_f32_e32 v22, v23, v22
	v_add_f32_e32 v34, v35, v34
	v_add_f32_e32 v36, v37, v36
	ds_swizzle_b32 v7, v6 offset:swizzle(SWAP,16)
	ds_swizzle_b32 v9, v8 offset:swizzle(SWAP,16)
	ds_swizzle_b32 v11, v10 offset:swizzle(SWAP,16)
	ds_swizzle_b32 v13, v12 offset:swizzle(SWAP,16)
	ds_swizzle_b32 v15, v14 offset:swizzle(SWAP,16)
	ds_swizzle_b32 v17, v16 offset:swizzle(SWAP,16)
	ds_swizzle_b32 v19, v18 offset:swizzle(SWAP,16)
	ds_swizzle_b32 v21, v20 offset:swizzle(SWAP,16)
	ds_swizzle_b32 v23, v22 offset:swizzle(SWAP,16)
	ds_swizzle_b32 v35, v34 offset:swizzle(SWAP,16)
	ds_swizzle_b32 v37, v36 offset:swizzle(SWAP,16)
	s_waitcnt lgkmcnt(10)
	v_add_f32_e32 v6, v6, v7
	s_waitcnt lgkmcnt(9)
	v_add_f32_e32 v8, v8, v9
	s_waitcnt lgkmcnt(8)
	v_add_f32_e32 v10, v10, v11
	s_waitcnt lgkmcnt(7)
	v_add_f32_e32 v12, v12, v13
	s_waitcnt lgkmcnt(6)
	v_add_f32_e32 v14, v14, v15
	s_waitcnt lgkmcnt(5)
	v_add_f32_e32 v16, v16, v17
	s_waitcnt lgkmcnt(4)
	v_add_f32_e32 v18, v18, v19
	s_waitcnt lgkmcnt(3)
	v_add_f32_e32 v20, v20, v21
	s_waitcnt lgkmcnt(2)
	v_add_f32_e32 v22, v22, v23
	s_waitcnt lgkmcnt(1)
	v_add_f32_e32 v34, v34, v35
	s_waitcnt lgkmcnt(0)
	v_add_f32_e32 v36, v36, v37
	v_mov_b32_e32 v7, v6
	v_mov_b32_e32 v9, v8
	v_mov_b32_e32 v11, v10
	v_mov_b32_e32 v13, v12
	v_mov_b32_e32 v15, v14
	v_mov_b32_e32 v17, v16
	v_mov_b32_e32 v19, v18
	v_mov_b32_e32 v21, v20
	v_mov_b32_e32 v23, v22
	v_mov_b32_e32 v35, v34
	v_mov_b32_e32 v37, v36
	v_permlane32_swap_b32_e32 v6, v7
	v_permlane32_swap_b32_e32 v8, v9
	v_permlane32_swap_b32_e32 v10, v11
	v_permlane32_swap_b32_e32 v12, v13
	v_permlane32_swap_b32_e32 v14, v15
	v_permlane32_swap_b32_e32 v16, v17
	v_permlane32_swap_b32_e32 v18, v19
	v_permlane32_swap_b32_e32 v20, v21
	v_permlane32_swap_b32_e32 v22, v23
	v_permlane32_swap_b32_e32 v32, v33
	v_permlane32_swap_b32_e32 v34, v35
	v_permlane32_swap_b32_e32 v36, v37
	v_cmp_eq_u32_e32 vcc, 0, v210
	s_and_saveexec_b64 s[30:31], vcc
	s_cbranch_execz .LBB0_349
	s_and_b64 s[52:53], s[28:29], exec
	s_mov_b32 s1, 0x31000
	s_cselect_b32 s1, s1, 0x20800
	s_add_u32 s1, s24, s1
	s_addc_u32 s2, s25, 0
	s_add_u32 s52, s1, s6
	v_add_f32_e32 v8, v8, v9
	v_add_f32_e32 v9, v6, v7
	s_addc_u32 s53, s2, s7
	v_add_f32_e32 v12, v12, v13
	v_add_f32_e32 v10, v10, v11
	v_lshl_add_u64 v[6:7], v[140:141], 2, s[52:53]
	v_add_f32_e32 v8, v9, v8
	v_add_f32_e32 v16, v16, v17
	v_add_f32_e32 v14, v14, v15
	global_atomic_add_f32 v[6:7], v8, off
	v_add_f32_e32 v8, v10, v12
	v_add_f32_e32 v20, v20, v21
	v_add_f32_e32 v18, v18, v19
	global_atomic_add_f32 v[6:7], v8, off offset:64
	v_add_f32_e32 v8, v14, v16
	v_add_f32_e32 v24, v24, v25
	v_add_f32_e32 v22, v22, v23
	global_atomic_add_f32 v[6:7], v8, off offset:128
	v_add_f32_e32 v8, v18, v20
	v_add_f32_e32 v28, v28, v29
	v_add_f32_e32 v26, v26, v27
	global_atomic_add_f32 v[6:7], v8, off offset:192
	v_add_f32_e32 v8, v22, v24
	v_add_f32_e32 v32, v32, v33
	v_add_f32_e32 v30, v30, v31
	global_atomic_add_f32 v[6:7], v8, off offset:512
	v_add_f32_e32 v8, v26, v28
	v_add_f32_e32 v36, v36, v37
	v_add_f32_e32 v34, v34, v35
	global_atomic_add_f32 v[6:7], v8, off offset:576
	v_add_f32_e32 v8, v30, v32
	global_atomic_add_f32 v[6:7], v8, off offset:640
	v_add_f32_e32 v8, v34, v36
	global_atomic_add_f32 v[6:7], v8, off offset:704

.LBB0_454:
	s_add_u32 s66, s62, 0xffffff80
	s_addc_u32 s67, s63, -1
	s_cmp_eq_u32 s64, 12
	s_cselect_b32 s38, s21, s62
	s_cselect_b32 s39, s3, s63
	s_cselect_b32 s41, s23, s61
	s_cselect_b32 s40, s31, s33
	s_add_u32 s34, s38, 0x80
	s_addc_u32 s35, s39, 0
	s_add_u32 s36, s40, 0x80
	s_addc_u32 s37, s41, 0
	s_add_i32 s65, 0, 0x10000
	s_add_i32 s68, 0, 0x14000
	v_add_u32_e32 v152, s65, v1
	v_add_u32_e32 v168, s68, v1
	ds_read_b128 v[140:143], v152
	ds_read_b128 v[144:147], v152 offset:1024
	ds_read_b128 v[148:151], v152 offset:2048
	ds_read_b128 v[152:155], v152 offset:3072
	ds_read_b128 v[156:159], v168
	ds_read_b128 v[160:163], v168 offset:1024
	ds_read_b128 v[164:167], v168 offset:2048
	ds_read_b128 v[168:171], v168 offset:3072
	s_add_u32 s66, s66, 0x40000
	s_addc_u32 s67, s67, 0
	v_lshl_add_u64 v[204:205], s[66:67], 0, v[2:3]
	s_add_i32 m0, s29, 0xc000
	ds_read_b128 v[172:175], v5
	ds_read_b128 v[176:179], v5 offset:1024
	ds_read_b128 v[180:183], v5 offset:2048
	ds_read_b128 v[184:187], v5 offset:3072
	ds_read_b128 v[188:191], v5 offset:4096
	ds_read_b128 v[192:195], v5 offset:5120
	ds_read_b128 v[196:199], v5 offset:6144
	ds_read_b128 v[200:203], v5 offset:7168
	global_load_lds_dwordx4 v[204:205], off
	v_lshl_add_u64 v[204:205], s[66:67], 0, v[136:137]
	s_add_i32 m0, s29, 0xe000
	s_nop 0
	global_load_lds_dwordx4 v[204:205], off
	s_waitcnt vmcnt(8)
	s_waitcnt lgkmcnt(0)
	s_barrier
	s_setprio 1
	s_waitcnt lgkmcnt(0)
	v_mfma_f32_16x16x32_bf16 v[130:133], v[140:143], v[172:175], v[130:133]
	v_mfma_f32_16x16x32_bf16 v[126:129], v[148:151], v[172:175], v[126:129]
	v_mfma_f32_16x16x32_bf16 v[114:117], v[140:143], v[180:183], v[114:117]
	v_mfma_f32_16x16x32_bf16 v[110:113], v[148:151], v[180:183], v[110:113]
	v_mfma_f32_16x16x32_bf16 v[98:101], v[140:143], v[188:191], v[98:101]
	v_mfma_f32_16x16x32_bf16 v[94:97], v[148:151], v[188:191], v[94:97]
	v_mfma_f32_16x16x32_bf16 v[82:85], v[140:143], v[196:199], v[82:85]
	v_mfma_f32_16x16x32_bf16 v[78:81], v[148:151], v[196:199], v[78:81]
	v_mfma_f32_16x16x32_bf16 v[130:133], v[144:147], v[176:179], v[130:133]
	v_mfma_f32_16x16x32_bf16 v[126:129], v[152:155], v[176:179], v[126:129]
	v_mfma_f32_16x16x32_bf16 v[114:117], v[144:147], v[184:187], v[114:117]
	v_mfma_f32_16x16x32_bf16 v[110:113], v[152:155], v[184:187], v[110:113]
	v_mfma_f32_16x16x32_bf16 v[98:101], v[144:147], v[192:195], v[98:101]
	v_mfma_f32_16x16x32_bf16 v[94:97], v[152:155], v[192:195], v[94:97]
	v_mfma_f32_16x16x32_bf16 v[82:85], v[144:147], v[200:203], v[82:85]
	v_mfma_f32_16x16x32_bf16 v[78:81], v[152:155], v[200:203], v[78:81]
	v_mfma_f32_16x16x32_bf16 v[122:125], v[156:159], v[172:175], v[122:125]
	v_mfma_f32_16x16x32_bf16 v[118:121], v[164:167], v[172:175], v[118:121]
	v_mfma_f32_16x16x32_bf16 v[106:109], v[156:159], v[180:183], v[106:109]
	v_mfma_f32_16x16x32_bf16 v[102:105], v[164:167], v[180:183], v[102:105]
	v_mfma_f32_16x16x32_bf16 v[90:93], v[156:159], v[188:191], v[90:93]
	v_mfma_f32_16x16x32_bf16 v[86:89], v[164:167], v[188:191], v[86:89]
	v_mfma_f32_16x16x32_bf16 v[74:77], v[156:159], v[196:199], v[74:77]
	v_mfma_f32_16x16x32_bf16 v[70:73], v[164:167], v[196:199], v[70:73]
	v_mfma_f32_16x16x32_bf16 v[122:125], v[160:163], v[176:179], v[122:125]
	v_mfma_f32_16x16x32_bf16 v[118:121], v[168:171], v[176:179], v[118:121]
	v_mfma_f32_16x16x32_bf16 v[106:109], v[160:163], v[184:187], v[106:109]
	v_mfma_f32_16x16x32_bf16 v[102:105], v[168:171], v[184:187], v[102:105]
	v_mfma_f32_16x16x32_bf16 v[90:93], v[160:163], v[192:195], v[90:93]
	v_mfma_f32_16x16x32_bf16 v[86:89], v[168:171], v[192:195], v[86:89]
	v_mfma_f32_16x16x32_bf16 v[74:77], v[160:163], v[200:203], v[74:77]
	v_mfma_f32_16x16x32_bf16 v[70:73], v[168:171], v[200:203], v[70:73]
	s_setprio 0
	s_barrier
	s_add_i32 s65, s65, s46
	v_lshl_add_u64 v[204:205], s[40:41], 0, v[134:135]
	s_mov_b32 m0, s65
	ds_read_b128 v[172:175], v5 offset:16384
	ds_read_b128 v[176:179], v5 offset:17408
	ds_read_b128 v[180:183], v5 offset:18432
	ds_read_b128 v[184:187], v5 offset:19456
	ds_read_b128 v[188:191], v5 offset:20480
	ds_read_b128 v[192:195], v5 offset:21504
	ds_read_b128 v[196:199], v5 offset:22528
	ds_read_b128 v[200:203], v5 offset:23552
	global_load_lds_dwordx4 v[204:205], off
	s_add_i32 m0, s65, 0x2000
	v_lshl_add_u64 v[204:205], s[40:41], 0, v[138:139]
	s_add_u32 s40, s40, 0x40000
	s_addc_u32 s41, s41, 0
	s_add_i32 s65, s68, s46
	global_load_lds_dwordx4 v[204:205], off
	v_lshl_add_u64 v[204:205], s[40:41], 0, v[134:135]
	s_mov_b32 m0, s65
	s_nop 0
	global_load_lds_dwordx4 v[204:205], off
	v_lshl_add_u64 v[204:205], s[40:41], 0, v[138:139]
	s_add_i32 m0, s65, 0x2000
	s_nop 0
	global_load_lds_dwordx4 v[204:205], off
	v_lshl_add_u64 v[204:205], s[38:39], 0, v[2:3]
	s_mov_b32 m0, s29
	s_nop 0
	global_load_lds_dwordx4 v[204:205], off
	v_lshl_add_u64 v[204:205], s[38:39], 0, v[136:137]
	s_mov_b32 m0, s51
	s_nop 0
	global_load_lds_dwordx4 v[204:205], off
	s_waitcnt vmcnt(8)
	s_waitcnt lgkmcnt(0)
	s_barrier
	s_setprio 1
	s_waitcnt lgkmcnt(0)
	v_mfma_f32_16x16x32_bf16 v[66:69], v[140:143], v[172:175], v[66:69]
	v_mfma_f32_16x16x32_bf16 v[62:65], v[148:151], v[172:175], v[62:65]
	v_mfma_f32_16x16x32_bf16 v[50:53], v[140:143], v[180:183], v[50:53]
	v_mfma_f32_16x16x32_bf16 v[46:49], v[148:151], v[180:183], v[46:49]
	v_mfma_f32_16x16x32_bf16 v[34:37], v[140:143], v[188:191], v[34:37]
	v_mfma_f32_16x16x32_bf16 v[30:33], v[148:151], v[188:191], v[30:33]
	v_mfma_f32_16x16x32_bf16 v[18:21], v[140:143], v[196:199], v[18:21]
	v_mfma_f32_16x16x32_bf16 v[14:17], v[148:151], v[196:199], v[14:17]
	v_mfma_f32_16x16x32_bf16 v[66:69], v[144:147], v[176:179], v[66:69]
	v_mfma_f32_16x16x32_bf16 v[62:65], v[152:155], v[176:179], v[62:65]
	v_mfma_f32_16x16x32_bf16 v[50:53], v[144:147], v[184:187], v[50:53]
	v_mfma_f32_16x16x32_bf16 v[46:49], v[152:155], v[184:187], v[46:49]
	v_mfma_f32_16x16x32_bf16 v[34:37], v[144:147], v[192:195], v[34:37]
	v_mfma_f32_16x16x32_bf16 v[30:33], v[152:155], v[192:195], v[30:33]
	v_mfma_f32_16x16x32_bf16 v[18:21], v[144:147], v[200:203], v[18:21]
	v_mfma_f32_16x16x32_bf16 v[14:17], v[152:155], v[200:203], v[14:17]
	v_mfma_f32_16x16x32_bf16 v[58:61], v[156:159], v[172:175], v[58:61]
	v_mfma_f32_16x16x32_bf16 v[54:57], v[164:167], v[172:175], v[54:57]
	v_mfma_f32_16x16x32_bf16 v[42:45], v[156:159], v[180:183], v[42:45]
	v_mfma_f32_16x16x32_bf16 v[38:41], v[164:167], v[180:183], v[38:41]
	v_mfma_f32_16x16x32_bf16 v[26:29], v[156:159], v[188:191], v[26:29]
	v_mfma_f32_16x16x32_bf16 v[22:25], v[164:167], v[188:191], v[22:25]
	v_mfma_f32_16x16x32_bf16 v[10:13], v[156:159], v[196:199], v[10:13]
	v_mfma_f32_16x16x32_bf16 v[6:9], v[164:167], v[196:199], v[6:9]
	v_mfma_f32_16x16x32_bf16 v[58:61], v[160:163], v[176:179], v[58:61]
	v_mfma_f32_16x16x32_bf16 v[54:57], v[168:171], v[176:179], v[54:57]
	v_mfma_f32_16x16x32_bf16 v[42:45], v[160:163], v[184:187], v[42:45]
	v_mfma_f32_16x16x32_bf16 v[38:41], v[168:171], v[184:187], v[38:41]
	v_mfma_f32_16x16x32_bf16 v[26:29], v[160:163], v[192:195], v[26:29]
	v_mfma_f32_16x16x32_bf16 v[22:25], v[168:171], v[192:195], v[22:25]
	v_mfma_f32_16x16x32_bf16 v[10:13], v[160:163], v[200:203], v[10:13]
	v_mfma_f32_16x16x32_bf16 v[6:9], v[168:171], v[200:203], v[6:9]
	s_setprio 0
	s_barrier
	s_add_i32 s40, 0, 0x18000
	s_add_i32 s41, 0, 0x1c000
	v_add_u32_e32 v152, s40, v1
	v_add_u32_e32 v168, s41, v1
	ds_read_b128 v[140:143], v152
	ds_read_b128 v[144:147], v152 offset:1024
	ds_read_b128 v[148:151], v152 offset:2048
	ds_read_b128 v[152:155], v152 offset:3072
	ds_read_b128 v[156:159], v168
	ds_read_b128 v[160:163], v168 offset:1024
	ds_read_b128 v[164:167], v168 offset:2048
	ds_read_b128 v[168:171], v168 offset:3072
	s_add_u32 s38, s38, 0x40000
	s_addc_u32 s39, s39, 0
	s_mov_b32 m0, s52
	v_lshl_add_u64 v[204:205], s[38:39], 0, v[2:3]
	ds_read_b128 v[172:175], v5 offset:32768
	ds_read_b128 v[176:179], v5 offset:33792
	ds_read_b128 v[180:183], v5 offset:34816
	ds_read_b128 v[184:187], v5 offset:35840
	ds_read_b128 v[188:191], v5 offset:36864
	ds_read_b128 v[192:195], v5 offset:37888
	ds_read_b128 v[196:199], v5 offset:38912
	ds_read_b128 v[200:203], v5 offset:39936
	global_load_lds_dwordx4 v[204:205], off
	v_lshl_add_u64 v[204:205], s[38:39], 0, v[136:137]
	s_mov_b32 m0, s53
	s_nop 0
	global_load_lds_dwordx4 v[204:205], off
	s_waitcnt vmcnt(8)
	s_waitcnt lgkmcnt(0)
	s_barrier
	s_setprio 1
	s_waitcnt lgkmcnt(0)
	v_mfma_f32_16x16x32_bf16 v[130:133], v[140:143], v[172:175], v[130:133]
	v_mfma_f32_16x16x32_bf16 v[126:129], v[148:151], v[172:175], v[126:129]
	v_mfma_f32_16x16x32_bf16 v[114:117], v[140:143], v[180:183], v[114:117]
	v_mfma_f32_16x16x32_bf16 v[110:113], v[148:151], v[180:183], v[110:113]
	v_mfma_f32_16x16x32_bf16 v[98:101], v[140:143], v[188:191], v[98:101]
	v_mfma_f32_16x16x32_bf16 v[94:97], v[148:151], v[188:191], v[94:97]
	v_mfma_f32_16x16x32_bf16 v[82:85], v[140:143], v[196:199], v[82:85]
	v_mfma_f32_16x16x32_bf16 v[78:81], v[148:151], v[196:199], v[78:81]
	v_mfma_f32_16x16x32_bf16 v[130:133], v[144:147], v[176:179], v[130:133]
	v_mfma_f32_16x16x32_bf16 v[126:129], v[152:155], v[176:179], v[126:129]
	v_mfma_f32_16x16x32_bf16 v[114:117], v[144:147], v[184:187], v[114:117]
	v_mfma_f32_16x16x32_bf16 v[110:113], v[152:155], v[184:187], v[110:113]
	v_mfma_f32_16x16x32_bf16 v[98:101], v[144:147], v[192:195], v[98:101]
	v_mfma_f32_16x16x32_bf16 v[94:97], v[152:155], v[192:195], v[94:97]
	v_mfma_f32_16x16x32_bf16 v[82:85], v[144:147], v[200:203], v[82:85]
	v_mfma_f32_16x16x32_bf16 v[78:81], v[152:155], v[200:203], v[78:81]
	v_mfma_f32_16x16x32_bf16 v[122:125], v[156:159], v[172:175], v[122:125]
	v_mfma_f32_16x16x32_bf16 v[118:121], v[164:167], v[172:175], v[118:121]
	v_mfma_f32_16x16x32_bf16 v[106:109], v[156:159], v[180:183], v[106:109]
	v_mfma_f32_16x16x32_bf16 v[102:105], v[164:167], v[180:183], v[102:105]
	v_mfma_f32_16x16x32_bf16 v[90:93], v[156:159], v[188:191], v[90:93]
	v_mfma_f32_16x16x32_bf16 v[86:89], v[164:167], v[188:191], v[86:89]
	v_mfma_f32_16x16x32_bf16 v[74:77], v[156:159], v[196:199], v[74:77]
	v_mfma_f32_16x16x32_bf16 v[70:73], v[164:167], v[196:199], v[70:73]
	v_mfma_f32_16x16x32_bf16 v[122:125], v[160:163], v[176:179], v[122:125]
	v_mfma_f32_16x16x32_bf16 v[118:121], v[168:171], v[176:179], v[118:121]
	v_mfma_f32_16x16x32_bf16 v[106:109], v[160:163], v[184:187], v[106:109]
	v_mfma_f32_16x16x32_bf16 v[102:105], v[168:171], v[184:187], v[102:105]
	v_mfma_f32_16x16x32_bf16 v[90:93], v[160:163], v[192:195], v[90:93]
	v_mfma_f32_16x16x32_bf16 v[86:89], v[168:171], v[192:195], v[86:89]
	v_mfma_f32_16x16x32_bf16 v[74:77], v[160:163], v[200:203], v[74:77]
	v_mfma_f32_16x16x32_bf16 v[70:73], v[168:171], v[200:203], v[70:73]
	s_setprio 0
	s_barrier
	s_add_i32 s38, s40, s46
	v_lshl_add_u64 v[204:205], s[36:37], 0, v[134:135]
	s_mov_b32 m0, s38
	ds_read_b128 v[172:175], v5 offset:49152
	ds_read_b128 v[176:179], v5 offset:50176
	ds_read_b128 v[180:183], v5 offset:51200
	ds_read_b128 v[184:187], v5 offset:52224
	ds_read_b128 v[188:191], v5 offset:53248
	ds_read_b128 v[192:195], v5 offset:54272
	ds_read_b128 v[196:199], v5 offset:55296
	ds_read_b128 v[200:203], v5 offset:56320
	global_load_lds_dwordx4 v[204:205], off
	s_add_i32 m0, s38, 0x2000
	v_lshl_add_u64 v[204:205], s[36:37], 0, v[138:139]
	s_add_u32 s36, s36, 0x40000
	s_addc_u32 s37, s37, 0
	s_add_i32 s38, s41, s46
	global_load_lds_dwordx4 v[204:205], off
	v_lshl_add_u64 v[204:205], s[36:37], 0, v[134:135]
	s_mov_b32 m0, s38
	s_nop 0
	global_load_lds_dwordx4 v[204:205], off
	v_lshl_add_u64 v[204:205], s[36:37], 0, v[138:139]
	s_add_i32 m0, s38, 0x2000
	s_nop 0
	global_load_lds_dwordx4 v[204:205], off
	v_lshl_add_u64 v[204:205], s[34:35], 0, v[2:3]
	s_mov_b32 m0, s56
	s_nop 0
	global_load_lds_dwordx4 v[204:205], off
	v_lshl_add_u64 v[204:205], s[34:35], 0, v[136:137]
	s_mov_b32 m0, s57
	s_nop 0
	global_load_lds_dwordx4 v[204:205], off
	s_waitcnt vmcnt(8)
	s_waitcnt lgkmcnt(0)
	s_barrier
	s_setprio 1
	s_waitcnt lgkmcnt(0)
	v_mfma_f32_16x16x32_bf16 v[66:69], v[140:143], v[172:175], v[66:69]
	v_mfma_f32_16x16x32_bf16 v[62:65], v[148:151], v[172:175], v[62:65]
	v_mfma_f32_16x16x32_bf16 v[50:53], v[140:143], v[180:183], v[50:53]
	v_mfma_f32_16x16x32_bf16 v[46:49], v[148:151], v[180:183], v[46:49]
	v_mfma_f32_16x16x32_bf16 v[34:37], v[140:143], v[188:191], v[34:37]
	v_mfma_f32_16x16x32_bf16 v[30:33], v[148:151], v[188:191], v[30:33]
	v_mfma_f32_16x16x32_bf16 v[18:21], v[140:143], v[196:199], v[18:21]
	v_mfma_f32_16x16x32_bf16 v[14:17], v[148:151], v[196:199], v[14:17]
	v_mfma_f32_16x16x32_bf16 v[66:69], v[144:147], v[176:179], v[66:69]
	v_mfma_f32_16x16x32_bf16 v[62:65], v[152:155], v[176:179], v[62:65]
	v_mfma_f32_16x16x32_bf16 v[50:53], v[144:147], v[184:187], v[50:53]
	v_mfma_f32_16x16x32_bf16 v[46:49], v[152:155], v[184:187], v[46:49]
	v_mfma_f32_16x16x32_bf16 v[34:37], v[144:147], v[192:195], v[34:37]
	v_mfma_f32_16x16x32_bf16 v[30:33], v[152:155], v[192:195], v[30:33]
	v_mfma_f32_16x16x32_bf16 v[18:21], v[144:147], v[200:203], v[18:21]
	v_mfma_f32_16x16x32_bf16 v[14:17], v[152:155], v[200:203], v[14:17]
	v_mfma_f32_16x16x32_bf16 v[58:61], v[156:159], v[172:175], v[58:61]
	v_mfma_f32_16x16x32_bf16 v[54:57], v[164:167], v[172:175], v[54:57]
	v_mfma_f32_16x16x32_bf16 v[42:45], v[156:159], v[180:183], v[42:45]
	v_mfma_f32_16x16x32_bf16 v[38:41], v[164:167], v[180:183], v[38:41]
	v_mfma_f32_16x16x32_bf16 v[26:29], v[156:159], v[188:191], v[26:29]
	v_mfma_f32_16x16x32_bf16 v[22:25], v[164:167], v[188:191], v[22:25]
	v_mfma_f32_16x16x32_bf16 v[10:13], v[156:159], v[196:199], v[10:13]
	v_mfma_f32_16x16x32_bf16 v[6:9], v[164:167], v[196:199], v[6:9]
	v_mfma_f32_16x16x32_bf16 v[58:61], v[160:163], v[176:179], v[58:61]
	v_mfma_f32_16x16x32_bf16 v[54:57], v[168:171], v[176:179], v[54:57]
	v_mfma_f32_16x16x32_bf16 v[42:45], v[160:163], v[184:187], v[42:45]
	v_mfma_f32_16x16x32_bf16 v[38:41], v[168:171], v[184:187], v[38:41]
	v_mfma_f32_16x16x32_bf16 v[26:29], v[160:163], v[192:195], v[26:29]
	v_mfma_f32_16x16x32_bf16 v[22:25], v[168:171], v[192:195], v[22:25]
	v_mfma_f32_16x16x32_bf16 v[10:13], v[160:163], v[200:203], v[10:13]
	v_mfma_f32_16x16x32_bf16 v[6:9], v[168:171], v[200:203], v[6:9]
	s_setprio 0
	s_barrier
	s_add_i32 s64, s64, 2
	s_add_u32 s33, s33, 0x100
	s_addc_u32 s61, s61, 0
	s_add_u32 s62, s62, 0x100
	s_addc_u32 s63, s63, 0
	s_cmp_gt_u32 s64, 13
	s_cbranch_scc0 .LBB0_454
	s_and_b64 vcc, exec, s[8:9]
	s_cbranch_vccz .LBB0_457
	s_barrier

.LBB0_480:
	s_add_u32 s58, s54, 0xffffff80
	s_addc_u32 s59, s55, -1
	s_cmp_eq_u32 s56, 4
	s_cselect_b32 s30, s25, s54
	s_cselect_b32 s31, s15, s55
	s_cselect_b32 s35, s17, s53
	s_cselect_b32 s34, s33, s52
	s_add_u32 s26, s30, 0x80
	s_addc_u32 s27, s31, 0
	s_add_u32 s28, s34, 0x80
	s_addc_u32 s29, s35, 0
	s_add_i32 s57, 0, 0x10000
	s_add_i32 s60, 0, 0x14000
	v_add_u32_e32 v152, s57, v1
	v_add_u32_e32 v168, s60, v1
	ds_read_b128 v[140:143], v152
	ds_read_b128 v[144:147], v152 offset:1024
	ds_read_b128 v[148:151], v152 offset:2048
	ds_read_b128 v[152:155], v152 offset:3072
	ds_read_b128 v[156:159], v168
	ds_read_b128 v[160:163], v168 offset:1024
	ds_read_b128 v[164:167], v168 offset:2048
	ds_read_b128 v[168:171], v168 offset:3072
	s_add_u32 s58, s58, 0x20000
	s_addc_u32 s59, s59, 0
	v_lshl_add_u64 v[204:205], s[58:59], 0, v[2:3]
	s_add_i32 m0, s43, 0xc000
	ds_read_b128 v[172:175], v5
	ds_read_b128 v[176:179], v5 offset:1024
	ds_read_b128 v[180:183], v5 offset:2048
	ds_read_b128 v[184:187], v5 offset:3072
	ds_read_b128 v[188:191], v5 offset:4096
	ds_read_b128 v[192:195], v5 offset:5120
	ds_read_b128 v[196:199], v5 offset:6144
	ds_read_b128 v[200:203], v5 offset:7168
	global_load_lds_dwordx4 v[204:205], off
	v_lshl_add_u64 v[204:205], s[58:59], 0, v[136:137]
	s_add_i32 m0, s43, 0xe000
	s_nop 0
	global_load_lds_dwordx4 v[204:205], off
	s_waitcnt vmcnt(8)
	s_waitcnt lgkmcnt(0)
	s_barrier
	s_setprio 1
	s_waitcnt lgkmcnt(0)
	v_mfma_f32_16x16x32_bf16 v[130:133], v[140:143], v[172:175], v[130:133]
	v_mfma_f32_16x16x32_bf16 v[126:129], v[148:151], v[172:175], v[126:129]
	v_mfma_f32_16x16x32_bf16 v[114:117], v[140:143], v[180:183], v[114:117]
	v_mfma_f32_16x16x32_bf16 v[110:113], v[148:151], v[180:183], v[110:113]
	v_mfma_f32_16x16x32_bf16 v[98:101], v[140:143], v[188:191], v[98:101]
	v_mfma_f32_16x16x32_bf16 v[94:97], v[148:151], v[188:191], v[94:97]
	v_mfma_f32_16x16x32_bf16 v[82:85], v[140:143], v[196:199], v[82:85]
	v_mfma_f32_16x16x32_bf16 v[78:81], v[148:151], v[196:199], v[78:81]
	v_mfma_f32_16x16x32_bf16 v[130:133], v[144:147], v[176:179], v[130:133]
	v_mfma_f32_16x16x32_bf16 v[126:129], v[152:155], v[176:179], v[126:129]
	v_mfma_f32_16x16x32_bf16 v[114:117], v[144:147], v[184:187], v[114:117]
	v_mfma_f32_16x16x32_bf16 v[110:113], v[152:155], v[184:187], v[110:113]
	v_mfma_f32_16x16x32_bf16 v[98:101], v[144:147], v[192:195], v[98:101]
	v_mfma_f32_16x16x32_bf16 v[94:97], v[152:155], v[192:195], v[94:97]
	v_mfma_f32_16x16x32_bf16 v[82:85], v[144:147], v[200:203], v[82:85]
	v_mfma_f32_16x16x32_bf16 v[78:81], v[152:155], v[200:203], v[78:81]
	v_mfma_f32_16x16x32_bf16 v[122:125], v[156:159], v[172:175], v[122:125]
	v_mfma_f32_16x16x32_bf16 v[118:121], v[164:167], v[172:175], v[118:121]
	v_mfma_f32_16x16x32_bf16 v[106:109], v[156:159], v[180:183], v[106:109]
	v_mfma_f32_16x16x32_bf16 v[102:105], v[164:167], v[180:183], v[102:105]
	v_mfma_f32_16x16x32_bf16 v[90:93], v[156:159], v[188:191], v[90:93]
	v_mfma_f32_16x16x32_bf16 v[86:89], v[164:167], v[188:191], v[86:89]
	v_mfma_f32_16x16x32_bf16 v[74:77], v[156:159], v[196:199], v[74:77]
	v_mfma_f32_16x16x32_bf16 v[70:73], v[164:167], v[196:199], v[70:73]
	v_mfma_f32_16x16x32_bf16 v[122:125], v[160:163], v[176:179], v[122:125]
	v_mfma_f32_16x16x32_bf16 v[118:121], v[168:171], v[176:179], v[118:121]
	v_mfma_f32_16x16x32_bf16 v[106:109], v[160:163], v[184:187], v[106:109]
	v_mfma_f32_16x16x32_bf16 v[102:105], v[168:171], v[184:187], v[102:105]
	v_mfma_f32_16x16x32_bf16 v[90:93], v[160:163], v[192:195], v[90:93]
	v_mfma_f32_16x16x32_bf16 v[86:89], v[168:171], v[192:195], v[86:89]
	v_mfma_f32_16x16x32_bf16 v[74:77], v[160:163], v[200:203], v[74:77]
	v_mfma_f32_16x16x32_bf16 v[70:73], v[168:171], v[200:203], v[70:73]
	s_setprio 0
	s_barrier
	s_add_i32 s57, s57, s42
	v_lshl_add_u64 v[204:205], s[34:35], 0, v[134:135]
	s_mov_b32 m0, s57
	ds_read_b128 v[172:175], v5 offset:16384
	ds_read_b128 v[176:179], v5 offset:17408
	ds_read_b128 v[180:183], v5 offset:18432
	ds_read_b128 v[184:187], v5 offset:19456
	ds_read_b128 v[188:191], v5 offset:20480
	ds_read_b128 v[192:195], v5 offset:21504
	ds_read_b128 v[196:199], v5 offset:22528
	ds_read_b128 v[200:203], v5 offset:23552
	global_load_lds_dwordx4 v[204:205], off
	s_add_i32 m0, s57, 0x2000
	v_lshl_add_u64 v[204:205], s[34:35], 0, v[138:139]
	s_add_u32 s34, s34, 0x20000
	s_addc_u32 s35, s35, 0
	s_add_i32 s57, s60, s42
	global_load_lds_dwordx4 v[204:205], off
	v_lshl_add_u64 v[204:205], s[34:35], 0, v[134:135]
	s_mov_b32 m0, s57
	s_nop 0
	global_load_lds_dwordx4 v[204:205], off
	v_lshl_add_u64 v[204:205], s[34:35], 0, v[138:139]
	s_add_i32 m0, s57, 0x2000
	s_nop 0
	global_load_lds_dwordx4 v[204:205], off
	v_lshl_add_u64 v[204:205], s[30:31], 0, v[2:3]
	s_mov_b32 m0, s43
	s_nop 0
	global_load_lds_dwordx4 v[204:205], off
	v_lshl_add_u64 v[204:205], s[30:31], 0, v[136:137]
	s_mov_b32 m0, s44
	s_nop 0
	global_load_lds_dwordx4 v[204:205], off
	s_waitcnt vmcnt(8)
	s_waitcnt lgkmcnt(0)
	s_barrier
	s_setprio 1
	s_waitcnt lgkmcnt(0)
	v_mfma_f32_16x16x32_bf16 v[66:69], v[140:143], v[172:175], v[66:69]
	v_mfma_f32_16x16x32_bf16 v[62:65], v[148:151], v[172:175], v[62:65]
	v_mfma_f32_16x16x32_bf16 v[50:53], v[140:143], v[180:183], v[50:53]
	v_mfma_f32_16x16x32_bf16 v[46:49], v[148:151], v[180:183], v[46:49]
	v_mfma_f32_16x16x32_bf16 v[34:37], v[140:143], v[188:191], v[34:37]
	v_mfma_f32_16x16x32_bf16 v[30:33], v[148:151], v[188:191], v[30:33]
	v_mfma_f32_16x16x32_bf16 v[18:21], v[140:143], v[196:199], v[18:21]
	v_mfma_f32_16x16x32_bf16 v[14:17], v[148:151], v[196:199], v[14:17]
	v_mfma_f32_16x16x32_bf16 v[66:69], v[144:147], v[176:179], v[66:69]
	v_mfma_f32_16x16x32_bf16 v[62:65], v[152:155], v[176:179], v[62:65]
	v_mfma_f32_16x16x32_bf16 v[50:53], v[144:147], v[184:187], v[50:53]
	v_mfma_f32_16x16x32_bf16 v[46:49], v[152:155], v[184:187], v[46:49]
	v_mfma_f32_16x16x32_bf16 v[34:37], v[144:147], v[192:195], v[34:37]
	v_mfma_f32_16x16x32_bf16 v[30:33], v[152:155], v[192:195], v[30:33]
	v_mfma_f32_16x16x32_bf16 v[18:21], v[144:147], v[200:203], v[18:21]
	v_mfma_f32_16x16x32_bf16 v[14:17], v[152:155], v[200:203], v[14:17]
	v_mfma_f32_16x16x32_bf16 v[58:61], v[156:159], v[172:175], v[58:61]
	v_mfma_f32_16x16x32_bf16 v[54:57], v[164:167], v[172:175], v[54:57]
	v_mfma_f32_16x16x32_bf16 v[42:45], v[156:159], v[180:183], v[42:45]
	v_mfma_f32_16x16x32_bf16 v[38:41], v[164:167], v[180:183], v[38:41]
	v_mfma_f32_16x16x32_bf16 v[26:29], v[156:159], v[188:191], v[26:29]
	v_mfma_f32_16x16x32_bf16 v[22:25], v[164:167], v[188:191], v[22:25]
	v_mfma_f32_16x16x32_bf16 v[10:13], v[156:159], v[196:199], v[10:13]
	v_mfma_f32_16x16x32_bf16 v[6:9], v[164:167], v[196:199], v[6:9]
	v_mfma_f32_16x16x32_bf16 v[58:61], v[160:163], v[176:179], v[58:61]
	v_mfma_f32_16x16x32_bf16 v[54:57], v[168:171], v[176:179], v[54:57]
	v_mfma_f32_16x16x32_bf16 v[42:45], v[160:163], v[184:187], v[42:45]
	v_mfma_f32_16x16x32_bf16 v[38:41], v[168:171], v[184:187], v[38:41]
	v_mfma_f32_16x16x32_bf16 v[26:29], v[160:163], v[192:195], v[26:29]
	v_mfma_f32_16x16x32_bf16 v[22:25], v[168:171], v[192:195], v[22:25]
	v_mfma_f32_16x16x32_bf16 v[10:13], v[160:163], v[200:203], v[10:13]
	v_mfma_f32_16x16x32_bf16 v[6:9], v[168:171], v[200:203], v[6:9]
	s_setprio 0
	s_barrier
	s_add_i32 s34, 0, 0x18000
	s_add_i32 s35, 0, 0x1c000
	v_add_u32_e32 v152, s34, v1
	v_add_u32_e32 v168, s35, v1
	ds_read_b128 v[140:143], v152
	ds_read_b128 v[144:147], v152 offset:1024
	ds_read_b128 v[148:151], v152 offset:2048
	ds_read_b128 v[152:155], v152 offset:3072
	ds_read_b128 v[156:159], v168
	ds_read_b128 v[160:163], v168 offset:1024
	ds_read_b128 v[164:167], v168 offset:2048
	ds_read_b128 v[168:171], v168 offset:3072
	s_add_u32 s30, s30, 0x20000
	s_addc_u32 s31, s31, 0
	s_mov_b32 m0, s45
	v_lshl_add_u64 v[204:205], s[30:31], 0, v[2:3]
	ds_read_b128 v[172:175], v5 offset:32768
	ds_read_b128 v[176:179], v5 offset:33792
	ds_read_b128 v[180:183], v5 offset:34816
	ds_read_b128 v[184:187], v5 offset:35840
	ds_read_b128 v[188:191], v5 offset:36864
	ds_read_b128 v[192:195], v5 offset:37888
	ds_read_b128 v[196:199], v5 offset:38912
	ds_read_b128 v[200:203], v5 offset:39936
	global_load_lds_dwordx4 v[204:205], off
	v_lshl_add_u64 v[204:205], s[30:31], 0, v[136:137]
	s_mov_b32 m0, s46
	s_nop 0
	global_load_lds_dwordx4 v[204:205], off
	s_waitcnt vmcnt(8)
	s_waitcnt lgkmcnt(0)
	s_barrier
	s_setprio 1
	s_waitcnt lgkmcnt(0)
	v_mfma_f32_16x16x32_bf16 v[130:133], v[140:143], v[172:175], v[130:133]
	v_mfma_f32_16x16x32_bf16 v[126:129], v[148:151], v[172:175], v[126:129]
	v_mfma_f32_16x16x32_bf16 v[114:117], v[140:143], v[180:183], v[114:117]
	v_mfma_f32_16x16x32_bf16 v[110:113], v[148:151], v[180:183], v[110:113]
	v_mfma_f32_16x16x32_bf16 v[98:101], v[140:143], v[188:191], v[98:101]
	v_mfma_f32_16x16x32_bf16 v[94:97], v[148:151], v[188:191], v[94:97]
	v_mfma_f32_16x16x32_bf16 v[82:85], v[140:143], v[196:199], v[82:85]
	v_mfma_f32_16x16x32_bf16 v[78:81], v[148:151], v[196:199], v[78:81]
	v_mfma_f32_16x16x32_bf16 v[130:133], v[144:147], v[176:179], v[130:133]
	v_mfma_f32_16x16x32_bf16 v[126:129], v[152:155], v[176:179], v[126:129]
	v_mfma_f32_16x16x32_bf16 v[114:117], v[144:147], v[184:187], v[114:117]
	v_mfma_f32_16x16x32_bf16 v[110:113], v[152:155], v[184:187], v[110:113]
	v_mfma_f32_16x16x32_bf16 v[98:101], v[144:147], v[192:195], v[98:101]
	v_mfma_f32_16x16x32_bf16 v[94:97], v[152:155], v[192:195], v[94:97]
	v_mfma_f32_16x16x32_bf16 v[82:85], v[144:147], v[200:203], v[82:85]
	v_mfma_f32_16x16x32_bf16 v[78:81], v[152:155], v[200:203], v[78:81]
	v_mfma_f32_16x16x32_bf16 v[122:125], v[156:159], v[172:175], v[122:125]
	v_mfma_f32_16x16x32_bf16 v[118:121], v[164:167], v[172:175], v[118:121]
	v_mfma_f32_16x16x32_bf16 v[106:109], v[156:159], v[180:183], v[106:109]
	v_mfma_f32_16x16x32_bf16 v[102:105], v[164:167], v[180:183], v[102:105]
	v_mfma_f32_16x16x32_bf16 v[90:93], v[156:159], v[188:191], v[90:93]
	v_mfma_f32_16x16x32_bf16 v[86:89], v[164:167], v[188:191], v[86:89]
	v_mfma_f32_16x16x32_bf16 v[74:77], v[156:159], v[196:199], v[74:77]
	v_mfma_f32_16x16x32_bf16 v[70:73], v[164:167], v[196:199], v[70:73]
	v_mfma_f32_16x16x32_bf16 v[122:125], v[160:163], v[176:179], v[122:125]
	v_mfma_f32_16x16x32_bf16 v[118:121], v[168:171], v[176:179], v[118:121]
	v_mfma_f32_16x16x32_bf16 v[106:109], v[160:163], v[184:187], v[106:109]
	v_mfma_f32_16x16x32_bf16 v[102:105], v[168:171], v[184:187], v[102:105]
	v_mfma_f32_16x16x32_bf16 v[90:93], v[160:163], v[192:195], v[90:93]
	v_mfma_f32_16x16x32_bf16 v[86:89], v[168:171], v[192:195], v[86:89]
	v_mfma_f32_16x16x32_bf16 v[74:77], v[160:163], v[200:203], v[74:77]
	v_mfma_f32_16x16x32_bf16 v[70:73], v[168:171], v[200:203], v[70:73]
	s_setprio 0
	s_barrier
	s_add_i32 s30, s34, s42
	v_lshl_add_u64 v[204:205], s[28:29], 0, v[134:135]
	s_mov_b32 m0, s30
	ds_read_b128 v[172:175], v5 offset:49152
	ds_read_b128 v[176:179], v5 offset:50176
	ds_read_b128 v[180:183], v5 offset:51200
	ds_read_b128 v[184:187], v5 offset:52224
	ds_read_b128 v[188:191], v5 offset:53248
	ds_read_b128 v[192:195], v5 offset:54272
	ds_read_b128 v[196:199], v5 offset:55296
	ds_read_b128 v[200:203], v5 offset:56320
	global_load_lds_dwordx4 v[204:205], off
	s_add_i32 m0, s30, 0x2000
	v_lshl_add_u64 v[204:205], s[28:29], 0, v[138:139]
	s_add_u32 s28, s28, 0x20000
	s_addc_u32 s29, s29, 0
	s_add_i32 s30, s35, s42
	global_load_lds_dwordx4 v[204:205], off
	v_lshl_add_u64 v[204:205], s[28:29], 0, v[134:135]
	s_mov_b32 m0, s30
	s_nop 0
	global_load_lds_dwordx4 v[204:205], off
	v_lshl_add_u64 v[204:205], s[28:29], 0, v[138:139]
	s_add_i32 m0, s30, 0x2000
	s_nop 0
	global_load_lds_dwordx4 v[204:205], off
	v_lshl_add_u64 v[204:205], s[26:27], 0, v[2:3]
	s_mov_b32 m0, s49
	s_nop 0
	global_load_lds_dwordx4 v[204:205], off
	v_lshl_add_u64 v[204:205], s[26:27], 0, v[136:137]
	s_mov_b32 m0, s50
	s_nop 0
	global_load_lds_dwordx4 v[204:205], off
	s_waitcnt vmcnt(8)
	s_waitcnt lgkmcnt(0)
	s_barrier
	s_setprio 1
	s_waitcnt lgkmcnt(0)
	v_mfma_f32_16x16x32_bf16 v[66:69], v[140:143], v[172:175], v[66:69]
	v_mfma_f32_16x16x32_bf16 v[62:65], v[148:151], v[172:175], v[62:65]
	v_mfma_f32_16x16x32_bf16 v[50:53], v[140:143], v[180:183], v[50:53]
	v_mfma_f32_16x16x32_bf16 v[46:49], v[148:151], v[180:183], v[46:49]
	v_mfma_f32_16x16x32_bf16 v[34:37], v[140:143], v[188:191], v[34:37]
	v_mfma_f32_16x16x32_bf16 v[30:33], v[148:151], v[188:191], v[30:33]
	v_mfma_f32_16x16x32_bf16 v[18:21], v[140:143], v[196:199], v[18:21]
	v_mfma_f32_16x16x32_bf16 v[14:17], v[148:151], v[196:199], v[14:17]
	v_mfma_f32_16x16x32_bf16 v[66:69], v[144:147], v[176:179], v[66:69]
	v_mfma_f32_16x16x32_bf16 v[62:65], v[152:155], v[176:179], v[62:65]
	v_mfma_f32_16x16x32_bf16 v[50:53], v[144:147], v[184:187], v[50:53]
	v_mfma_f32_16x16x32_bf16 v[46:49], v[152:155], v[184:187], v[46:49]
	v_mfma_f32_16x16x32_bf16 v[34:37], v[144:147], v[192:195], v[34:37]
	v_mfma_f32_16x16x32_bf16 v[30:33], v[152:155], v[192:195], v[30:33]
	v_mfma_f32_16x16x32_bf16 v[18:21], v[144:147], v[200:203], v[18:21]
	v_mfma_f32_16x16x32_bf16 v[14:17], v[152:155], v[200:203], v[14:17]
	v_mfma_f32_16x16x32_bf16 v[58:61], v[156:159], v[172:175], v[58:61]
	v_mfma_f32_16x16x32_bf16 v[54:57], v[164:167], v[172:175], v[54:57]
	v_mfma_f32_16x16x32_bf16 v[42:45], v[156:159], v[180:183], v[42:45]
	v_mfma_f32_16x16x32_bf16 v[38:41], v[164:167], v[180:183], v[38:41]
	v_mfma_f32_16x16x32_bf16 v[26:29], v[156:159], v[188:191], v[26:29]
	v_mfma_f32_16x16x32_bf16 v[22:25], v[164:167], v[188:191], v[22:25]
	v_mfma_f32_16x16x32_bf16 v[10:13], v[156:159], v[196:199], v[10:13]
	v_mfma_f32_16x16x32_bf16 v[6:9], v[164:167], v[196:199], v[6:9]
	v_mfma_f32_16x16x32_bf16 v[58:61], v[160:163], v[176:179], v[58:61]
	v_mfma_f32_16x16x32_bf16 v[54:57], v[168:171], v[176:179], v[54:57]
	v_mfma_f32_16x16x32_bf16 v[42:45], v[160:163], v[184:187], v[42:45]
	v_mfma_f32_16x16x32_bf16 v[38:41], v[168:171], v[184:187], v[38:41]
	v_mfma_f32_16x16x32_bf16 v[26:29], v[160:163], v[192:195], v[26:29]
	v_mfma_f32_16x16x32_bf16 v[22:25], v[168:171], v[192:195], v[22:25]
	v_mfma_f32_16x16x32_bf16 v[10:13], v[160:163], v[200:203], v[10:13]
	v_mfma_f32_16x16x32_bf16 v[6:9], v[168:171], v[200:203], v[6:9]
	s_setprio 0
	s_barrier
	s_add_i32 s56, s56, 2
	s_add_u32 s52, s52, 0x100
	s_addc_u32 s53, s53, 0
	s_add_u32 s54, s54, 0x100
	s_addc_u32 s55, s55, 0
	s_cmp_gt_u32 s56, 5
	s_cbranch_scc0 .LBB0_480
	s_and_b64 vcc, exec, s[8:9]
	s_cbranch_vccz .LBB0_483
	s_barrier

.LBB0_536:
	s_add_u32 s48, s45, 0xffffff80
	s_addc_u32 s49, s46, -1
	s_cmp_eq_u32 s47, 4
	s_cselect_b32 s22, s41, s45
	s_cselect_b32 s23, s7, s46
	s_cselect_b32 s25, s9, s44
	s_cselect_b32 s24, s42, s43
	s_add_u32 s18, s22, 0x80
	s_addc_u32 s19, s23, 0
	s_add_u32 s20, s24, 0x80
	s_addc_u32 s21, s25, 0
	s_add_i32 s50, 0, 0x10000
	s_add_i32 s51, 0, 0x14000
	v_add_u32_e32 v152, s50, v1
	v_add_u32_e32 v168, s51, v1
	ds_read_b128 v[140:143], v152
	ds_read_b128 v[144:147], v152 offset:1024
	ds_read_b128 v[148:151], v152 offset:2048
	ds_read_b128 v[152:155], v152 offset:3072
	ds_read_b128 v[156:159], v168
	ds_read_b128 v[160:163], v168 offset:1024
	ds_read_b128 v[164:167], v168 offset:2048
	ds_read_b128 v[168:171], v168 offset:3072
	s_add_u32 s48, s48, 0x20000
	s_addc_u32 s49, s49, 0
	v_lshl_add_u64 v[204:205], s[48:49], 0, v[2:3]
	s_add_i32 m0, s15, 0xc000
	ds_read_b128 v[172:175], v5
	ds_read_b128 v[176:179], v5 offset:1024
	ds_read_b128 v[180:183], v5 offset:2048
	ds_read_b128 v[184:187], v5 offset:3072
	ds_read_b128 v[188:191], v5 offset:4096
	ds_read_b128 v[192:195], v5 offset:5120
	ds_read_b128 v[196:199], v5 offset:6144
	ds_read_b128 v[200:203], v5 offset:7168
	global_load_lds_dwordx4 v[204:205], off
	v_lshl_add_u64 v[204:205], s[48:49], 0, v[136:137]
	s_add_i32 m0, s15, 0xe000
	s_nop 0
	global_load_lds_dwordx4 v[204:205], off
	s_waitcnt vmcnt(8)
	s_waitcnt lgkmcnt(0)
	s_barrier
	s_setprio 1
	s_waitcnt lgkmcnt(0)
	v_mfma_f32_16x16x32_bf16 v[130:133], v[140:143], v[172:175], v[130:133]
	v_mfma_f32_16x16x32_bf16 v[126:129], v[148:151], v[172:175], v[126:129]
	v_mfma_f32_16x16x32_bf16 v[122:125], v[140:143], v[180:183], v[122:125]
	v_mfma_f32_16x16x32_bf16 v[114:117], v[148:151], v[180:183], v[114:117]
	v_mfma_f32_16x16x32_bf16 v[106:109], v[140:143], v[188:191], v[106:109]
	v_mfma_f32_16x16x32_bf16 v[98:101], v[148:151], v[188:191], v[98:101]
	v_mfma_f32_16x16x32_bf16 v[90:93], v[140:143], v[196:199], v[90:93]
	v_mfma_f32_16x16x32_bf16 v[82:85], v[148:151], v[196:199], v[82:85]
	v_mfma_f32_16x16x32_bf16 v[130:133], v[144:147], v[176:179], v[130:133]
	v_mfma_f32_16x16x32_bf16 v[126:129], v[152:155], v[176:179], v[126:129]
	v_mfma_f32_16x16x32_bf16 v[122:125], v[144:147], v[184:187], v[122:125]
	v_mfma_f32_16x16x32_bf16 v[114:117], v[152:155], v[184:187], v[114:117]
	v_mfma_f32_16x16x32_bf16 v[106:109], v[144:147], v[192:195], v[106:109]
	v_mfma_f32_16x16x32_bf16 v[98:101], v[152:155], v[192:195], v[98:101]
	v_mfma_f32_16x16x32_bf16 v[90:93], v[144:147], v[200:203], v[90:93]
	v_mfma_f32_16x16x32_bf16 v[82:85], v[152:155], v[200:203], v[82:85]
	v_mfma_f32_16x16x32_bf16 v[118:121], v[156:159], v[172:175], v[118:121]
	v_mfma_f32_16x16x32_bf16 v[110:113], v[164:167], v[172:175], v[110:113]
	v_mfma_f32_16x16x32_bf16 v[102:105], v[156:159], v[180:183], v[102:105]
	v_mfma_f32_16x16x32_bf16 v[94:97], v[164:167], v[180:183], v[94:97]
	v_mfma_f32_16x16x32_bf16 v[86:89], v[156:159], v[188:191], v[86:89]
	v_mfma_f32_16x16x32_bf16 v[78:81], v[164:167], v[188:191], v[78:81]
	v_mfma_f32_16x16x32_bf16 v[74:77], v[156:159], v[196:199], v[74:77]
	v_mfma_f32_16x16x32_bf16 v[70:73], v[164:167], v[196:199], v[70:73]
	v_mfma_f32_16x16x32_bf16 v[118:121], v[160:163], v[176:179], v[118:121]
	v_mfma_f32_16x16x32_bf16 v[110:113], v[168:171], v[176:179], v[110:113]
	v_mfma_f32_16x16x32_bf16 v[102:105], v[160:163], v[184:187], v[102:105]
	v_mfma_f32_16x16x32_bf16 v[94:97], v[168:171], v[184:187], v[94:97]
	v_mfma_f32_16x16x32_bf16 v[86:89], v[160:163], v[192:195], v[86:89]
	v_mfma_f32_16x16x32_bf16 v[78:81], v[168:171], v[192:195], v[78:81]
	v_mfma_f32_16x16x32_bf16 v[74:77], v[160:163], v[200:203], v[74:77]
	v_mfma_f32_16x16x32_bf16 v[70:73], v[168:171], v[200:203], v[70:73]
	s_setprio 0
	s_barrier
	s_add_i32 s48, s50, s29
	v_lshl_add_u64 v[204:205], s[24:25], 0, v[134:135]
	s_mov_b32 m0, s48
	ds_read_b128 v[172:175], v5 offset:16384
	ds_read_b128 v[176:179], v5 offset:17408
	ds_read_b128 v[180:183], v5 offset:18432
	ds_read_b128 v[184:187], v5 offset:19456
	ds_read_b128 v[188:191], v5 offset:20480
	ds_read_b128 v[192:195], v5 offset:21504
	ds_read_b128 v[196:199], v5 offset:22528
	ds_read_b128 v[200:203], v5 offset:23552
	global_load_lds_dwordx4 v[204:205], off
	s_add_i32 m0, s48, 0x2000
	v_lshl_add_u64 v[204:205], s[24:25], 0, v[138:139]
	s_add_u32 s24, s24, 0x20000
	s_addc_u32 s25, s25, 0
	s_add_i32 s48, s51, s29
	global_load_lds_dwordx4 v[204:205], off
	v_lshl_add_u64 v[204:205], s[24:25], 0, v[134:135]
	s_mov_b32 m0, s48
	s_nop 0
	global_load_lds_dwordx4 v[204:205], off
	v_lshl_add_u64 v[204:205], s[24:25], 0, v[138:139]
	s_add_i32 m0, s48, 0x2000
	s_nop 0
	global_load_lds_dwordx4 v[204:205], off
	v_lshl_add_u64 v[204:205], s[22:23], 0, v[2:3]
	s_mov_b32 m0, s15
	s_nop 0
	global_load_lds_dwordx4 v[204:205], off
	v_lshl_add_u64 v[204:205], s[22:23], 0, v[136:137]
	s_mov_b32 m0, s17
	s_nop 0
	global_load_lds_dwordx4 v[204:205], off
	s_waitcnt vmcnt(8)
	s_waitcnt lgkmcnt(0)
	s_barrier
	s_setprio 1
	s_waitcnt lgkmcnt(0)
	v_mfma_f32_16x16x32_bf16 v[66:69], v[140:143], v[172:175], v[66:69]
	v_mfma_f32_16x16x32_bf16 v[62:65], v[148:151], v[172:175], v[62:65]
	v_mfma_f32_16x16x32_bf16 v[58:61], v[140:143], v[180:183], v[58:61]
	v_mfma_f32_16x16x32_bf16 v[50:53], v[148:151], v[180:183], v[50:53]
	v_mfma_f32_16x16x32_bf16 v[42:45], v[140:143], v[188:191], v[42:45]
	v_mfma_f32_16x16x32_bf16 v[34:37], v[148:151], v[188:191], v[34:37]
	v_mfma_f32_16x16x32_bf16 v[26:29], v[140:143], v[196:199], v[26:29]
	v_mfma_f32_16x16x32_bf16 v[18:21], v[148:151], v[196:199], v[18:21]
	v_mfma_f32_16x16x32_bf16 v[66:69], v[144:147], v[176:179], v[66:69]
	v_mfma_f32_16x16x32_bf16 v[62:65], v[152:155], v[176:179], v[62:65]
	v_mfma_f32_16x16x32_bf16 v[58:61], v[144:147], v[184:187], v[58:61]
	v_mfma_f32_16x16x32_bf16 v[50:53], v[152:155], v[184:187], v[50:53]
	v_mfma_f32_16x16x32_bf16 v[42:45], v[144:147], v[192:195], v[42:45]
	v_mfma_f32_16x16x32_bf16 v[34:37], v[152:155], v[192:195], v[34:37]
	v_mfma_f32_16x16x32_bf16 v[26:29], v[144:147], v[200:203], v[26:29]
	v_mfma_f32_16x16x32_bf16 v[18:21], v[152:155], v[200:203], v[18:21]
	v_mfma_f32_16x16x32_bf16 v[54:57], v[156:159], v[172:175], v[54:57]
	v_mfma_f32_16x16x32_bf16 v[46:49], v[164:167], v[172:175], v[46:49]
	v_mfma_f32_16x16x32_bf16 v[38:41], v[156:159], v[180:183], v[38:41]
	v_mfma_f32_16x16x32_bf16 v[30:33], v[164:167], v[180:183], v[30:33]
	v_mfma_f32_16x16x32_bf16 v[22:25], v[156:159], v[188:191], v[22:25]
	v_mfma_f32_16x16x32_bf16 v[14:17], v[164:167], v[188:191], v[14:17]
	v_mfma_f32_16x16x32_bf16 v[10:13], v[156:159], v[196:199], v[10:13]
	v_mfma_f32_16x16x32_bf16 v[6:9], v[164:167], v[196:199], v[6:9]
	v_mfma_f32_16x16x32_bf16 v[54:57], v[160:163], v[176:179], v[54:57]
	v_mfma_f32_16x16x32_bf16 v[46:49], v[168:171], v[176:179], v[46:49]
	v_mfma_f32_16x16x32_bf16 v[38:41], v[160:163], v[184:187], v[38:41]
	v_mfma_f32_16x16x32_bf16 v[30:33], v[168:171], v[184:187], v[30:33]
	v_mfma_f32_16x16x32_bf16 v[22:25], v[160:163], v[192:195], v[22:25]
	v_mfma_f32_16x16x32_bf16 v[14:17], v[168:171], v[192:195], v[14:17]
	v_mfma_f32_16x16x32_bf16 v[10:13], v[160:163], v[200:203], v[10:13]
	v_mfma_f32_16x16x32_bf16 v[6:9], v[168:171], v[200:203], v[6:9]
	s_setprio 0
	s_barrier
	s_add_i32 s24, 0, 0x18000
	s_add_i32 s25, 0, 0x1c000
	v_add_u32_e32 v152, s24, v1
	v_add_u32_e32 v168, s25, v1
	ds_read_b128 v[140:143], v152
	ds_read_b128 v[144:147], v152 offset:1024
	ds_read_b128 v[148:151], v152 offset:2048
	ds_read_b128 v[152:155], v152 offset:3072
	ds_read_b128 v[156:159], v168
	ds_read_b128 v[160:163], v168 offset:1024
	ds_read_b128 v[164:167], v168 offset:2048
	ds_read_b128 v[168:171], v168 offset:3072
	s_add_u32 s22, s22, 0x20000
	s_addc_u32 s23, s23, 0
	s_mov_b32 m0, s31
	v_lshl_add_u64 v[204:205], s[22:23], 0, v[2:3]
	ds_read_b128 v[172:175], v5 offset:32768
	ds_read_b128 v[176:179], v5 offset:33792
	ds_read_b128 v[180:183], v5 offset:34816
	ds_read_b128 v[184:187], v5 offset:35840
	ds_read_b128 v[188:191], v5 offset:36864
	ds_read_b128 v[192:195], v5 offset:37888
	ds_read_b128 v[196:199], v5 offset:38912
	ds_read_b128 v[200:203], v5 offset:39936
	global_load_lds_dwordx4 v[204:205], off
	v_lshl_add_u64 v[204:205], s[22:23], 0, v[136:137]
	s_mov_b32 m0, s33
	s_nop 0
	global_load_lds_dwordx4 v[204:205], off
	s_waitcnt vmcnt(8)
	s_waitcnt lgkmcnt(0)
	s_barrier
	s_setprio 1
	s_waitcnt lgkmcnt(0)
	v_mfma_f32_16x16x32_bf16 v[130:133], v[140:143], v[172:175], v[130:133]
	v_mfma_f32_16x16x32_bf16 v[126:129], v[148:151], v[172:175], v[126:129]
	v_mfma_f32_16x16x32_bf16 v[122:125], v[140:143], v[180:183], v[122:125]
	v_mfma_f32_16x16x32_bf16 v[114:117], v[148:151], v[180:183], v[114:117]
	v_mfma_f32_16x16x32_bf16 v[106:109], v[140:143], v[188:191], v[106:109]
	v_mfma_f32_16x16x32_bf16 v[98:101], v[148:151], v[188:191], v[98:101]
	v_mfma_f32_16x16x32_bf16 v[90:93], v[140:143], v[196:199], v[90:93]
	v_mfma_f32_16x16x32_bf16 v[82:85], v[148:151], v[196:199], v[82:85]
	v_mfma_f32_16x16x32_bf16 v[130:133], v[144:147], v[176:179], v[130:133]
	v_mfma_f32_16x16x32_bf16 v[126:129], v[152:155], v[176:179], v[126:129]
	v_mfma_f32_16x16x32_bf16 v[122:125], v[144:147], v[184:187], v[122:125]
	v_mfma_f32_16x16x32_bf16 v[114:117], v[152:155], v[184:187], v[114:117]
	v_mfma_f32_16x16x32_bf16 v[106:109], v[144:147], v[192:195], v[106:109]
	v_mfma_f32_16x16x32_bf16 v[98:101], v[152:155], v[192:195], v[98:101]
	v_mfma_f32_16x16x32_bf16 v[90:93], v[144:147], v[200:203], v[90:93]
	v_mfma_f32_16x16x32_bf16 v[82:85], v[152:155], v[200:203], v[82:85]
	v_mfma_f32_16x16x32_bf16 v[118:121], v[156:159], v[172:175], v[118:121]
	v_mfma_f32_16x16x32_bf16 v[110:113], v[164:167], v[172:175], v[110:113]
	v_mfma_f32_16x16x32_bf16 v[102:105], v[156:159], v[180:183], v[102:105]
	v_mfma_f32_16x16x32_bf16 v[94:97], v[164:167], v[180:183], v[94:97]
	v_mfma_f32_16x16x32_bf16 v[86:89], v[156:159], v[188:191], v[86:89]
	v_mfma_f32_16x16x32_bf16 v[78:81], v[164:167], v[188:191], v[78:81]
	v_mfma_f32_16x16x32_bf16 v[74:77], v[156:159], v[196:199], v[74:77]
	v_mfma_f32_16x16x32_bf16 v[70:73], v[164:167], v[196:199], v[70:73]
	v_mfma_f32_16x16x32_bf16 v[118:121], v[160:163], v[176:179], v[118:121]
	v_mfma_f32_16x16x32_bf16 v[110:113], v[168:171], v[176:179], v[110:113]
	v_mfma_f32_16x16x32_bf16 v[102:105], v[160:163], v[184:187], v[102:105]
	v_mfma_f32_16x16x32_bf16 v[94:97], v[168:171], v[184:187], v[94:97]
	v_mfma_f32_16x16x32_bf16 v[86:89], v[160:163], v[192:195], v[86:89]
	v_mfma_f32_16x16x32_bf16 v[78:81], v[168:171], v[192:195], v[78:81]
	v_mfma_f32_16x16x32_bf16 v[74:77], v[160:163], v[200:203], v[74:77]
	v_mfma_f32_16x16x32_bf16 v[70:73], v[168:171], v[200:203], v[70:73]
	s_setprio 0
	s_barrier
	s_add_i32 s22, s24, s29
	v_lshl_add_u64 v[204:205], s[20:21], 0, v[134:135]
	s_mov_b32 m0, s22
	ds_read_b128 v[172:175], v5 offset:49152
	ds_read_b128 v[176:179], v5 offset:50176
	ds_read_b128 v[180:183], v5 offset:51200
	ds_read_b128 v[184:187], v5 offset:52224
	ds_read_b128 v[188:191], v5 offset:53248
	ds_read_b128 v[192:195], v5 offset:54272
	ds_read_b128 v[196:199], v5 offset:55296
	ds_read_b128 v[200:203], v5 offset:56320
	global_load_lds_dwordx4 v[204:205], off
	s_add_i32 m0, s22, 0x2000
	v_lshl_add_u64 v[204:205], s[20:21], 0, v[138:139]
	s_add_u32 s20, s20, 0x20000
	s_addc_u32 s21, s21, 0
	s_add_i32 s22, s25, s29
	global_load_lds_dwordx4 v[204:205], off
	v_lshl_add_u64 v[204:205], s[20:21], 0, v[134:135]
	s_mov_b32 m0, s22
	s_nop 0
	global_load_lds_dwordx4 v[204:205], off
	v_lshl_add_u64 v[204:205], s[20:21], 0, v[138:139]
	s_add_i32 m0, s22, 0x2000
	s_nop 0
	global_load_lds_dwordx4 v[204:205], off
	v_lshl_add_u64 v[204:205], s[18:19], 0, v[2:3]
	s_mov_b32 m0, s38
	s_nop 0
	global_load_lds_dwordx4 v[204:205], off
	v_lshl_add_u64 v[204:205], s[18:19], 0, v[136:137]
	s_mov_b32 m0, s39
	s_nop 0
	global_load_lds_dwordx4 v[204:205], off
	s_waitcnt vmcnt(8)
	s_waitcnt lgkmcnt(0)
	s_barrier
	s_setprio 1
	s_waitcnt lgkmcnt(0)
	v_mfma_f32_16x16x32_bf16 v[66:69], v[140:143], v[172:175], v[66:69]
	v_mfma_f32_16x16x32_bf16 v[62:65], v[148:151], v[172:175], v[62:65]
	v_mfma_f32_16x16x32_bf16 v[58:61], v[140:143], v[180:183], v[58:61]
	v_mfma_f32_16x16x32_bf16 v[50:53], v[148:151], v[180:183], v[50:53]
	v_mfma_f32_16x16x32_bf16 v[42:45], v[140:143], v[188:191], v[42:45]
	v_mfma_f32_16x16x32_bf16 v[34:37], v[148:151], v[188:191], v[34:37]
	v_mfma_f32_16x16x32_bf16 v[26:29], v[140:143], v[196:199], v[26:29]
	v_mfma_f32_16x16x32_bf16 v[18:21], v[148:151], v[196:199], v[18:21]
	v_mfma_f32_16x16x32_bf16 v[66:69], v[144:147], v[176:179], v[66:69]
	v_mfma_f32_16x16x32_bf16 v[62:65], v[152:155], v[176:179], v[62:65]
	v_mfma_f32_16x16x32_bf16 v[58:61], v[144:147], v[184:187], v[58:61]
	v_mfma_f32_16x16x32_bf16 v[50:53], v[152:155], v[184:187], v[50:53]
	v_mfma_f32_16x16x32_bf16 v[42:45], v[144:147], v[192:195], v[42:45]
	v_mfma_f32_16x16x32_bf16 v[34:37], v[152:155], v[192:195], v[34:37]
	v_mfma_f32_16x16x32_bf16 v[26:29], v[144:147], v[200:203], v[26:29]
	v_mfma_f32_16x16x32_bf16 v[18:21], v[152:155], v[200:203], v[18:21]
	v_mfma_f32_16x16x32_bf16 v[54:57], v[156:159], v[172:175], v[54:57]
	v_mfma_f32_16x16x32_bf16 v[46:49], v[164:167], v[172:175], v[46:49]
	v_mfma_f32_16x16x32_bf16 v[38:41], v[156:159], v[180:183], v[38:41]
	v_mfma_f32_16x16x32_bf16 v[30:33], v[164:167], v[180:183], v[30:33]
	v_mfma_f32_16x16x32_bf16 v[22:25], v[156:159], v[188:191], v[22:25]
	v_mfma_f32_16x16x32_bf16 v[14:17], v[164:167], v[188:191], v[14:17]
	v_mfma_f32_16x16x32_bf16 v[10:13], v[156:159], v[196:199], v[10:13]
	v_mfma_f32_16x16x32_bf16 v[6:9], v[164:167], v[196:199], v[6:9]
	v_mfma_f32_16x16x32_bf16 v[54:57], v[160:163], v[176:179], v[54:57]
	v_mfma_f32_16x16x32_bf16 v[46:49], v[168:171], v[176:179], v[46:49]
	v_mfma_f32_16x16x32_bf16 v[38:41], v[160:163], v[184:187], v[38:41]
	v_mfma_f32_16x16x32_bf16 v[30:33], v[168:171], v[184:187], v[30:33]
	v_mfma_f32_16x16x32_bf16 v[22:25], v[160:163], v[192:195], v[22:25]
	v_mfma_f32_16x16x32_bf16 v[14:17], v[168:171], v[192:195], v[14:17]
	v_mfma_f32_16x16x32_bf16 v[10:13], v[160:163], v[200:203], v[10:13]
	v_mfma_f32_16x16x32_bf16 v[6:9], v[168:171], v[200:203], v[6:9]
	s_setprio 0
	s_barrier
	s_add_i32 s47, s47, 2
	s_add_u32 s43, s43, 0x100
	s_addc_u32 s44, s44, 0
	s_add_u32 s45, s45, 0x100
	s_addc_u32 s46, s46, 0
	s_cmp_gt_u32 s47, 5
	s_cbranch_scc0 .LBB0_536
	s_lshl_b32 s20, s16, 8
	v_mov_b32_e32 v140, v0
	s_mov_b64 s[18:19], s[84:85]
	s_lshl_b32 s7, s14, 8
	s_ashr_i32 s21, s20, 31
	s_add_i32 s7, s7, s34
	s_lshl_b64 s[20:21], s[20:21], 1
	v_and_b32_e32 v142, 15, v140
	s_add_u32 s18, s18, s20
	v_or_b32_e32 v146, s7, v142
	v_lshrrev_b32_e32 v140, 1, v140
	s_addc_u32 s19, s19, s21
	s_ashr_i32 s9, s7, 11
	v_mov_b32_e32 v143, s7
	s_movk_i32 s7, 0x7cf
	v_and_or_b32 v140, v140, 24, s35
	s_mulk_i32 s9, 0x810
	v_bitop3_b32 v142, v142, s7, v143 bitop3:0xc8
	v_lshlrev_b32_e32 v140, 1, v140
	v_mov_b32_e32 v141, v4
	v_add_u32_e32 v142, s9, v142
	v_lshl_add_u64 v[140:141], s[18:19], 0, v[140:141]
	s_mov_b64 s[18:19], 0x2c900000
	v_ashrrev_i32_e32 v143, 31, v142
	v_lshl_add_u64 v[140:141], v[140:141], 0, s[18:19]
	v_lshlrev_b64 v[144:145], 13, v[142:143]
	v_lshl_add_u64 v[144:145], v[140:141], 0, v[144:145]
	v_cvt_pk_bf16_f32 v130, v130, v131
	v_cvt_pk_bf16_f32 v131, v132, v133
	v_cvt_pk_bf16_f32 v132, v126, v127
	v_cvt_pk_bf16_f32 v133, v128, v129
	global_store_dwordx4 v[144:145], v[130:133], off nt
	v_cvt_pk_bf16_f32 v118, v118, v119
	v_cvt_pk_bf16_f32 v119, v120, v121
	v_cvt_pk_bf16_f32 v120, v110, v111
	v_add_u32_e32 v110, 16, v142
	v_ashrrev_i32_e32 v111, 31, v110
	v_lshlrev_b64 v[110:111], 13, v[110:111]
	v_cvt_pk_bf16_f32 v121, v112, v113
	global_store_dwordx4 v[144:145], v[118:121], off offset:256 nt
	s_movk_i32 s7, 0x810
	s_and_b64 vcc, exec, s[0:1]
	v_lshl_add_u64 v[118:119], v[140:141], 0, v[110:111]
	v_cvt_pk_bf16_f32 v110, v122, v123
	v_cvt_pk_bf16_f32 v111, v124, v125
	v_cvt_pk_bf16_f32 v112, v114, v115
	v_cvt_pk_bf16_f32 v113, v116, v117
	global_store_dwordx4 v[118:119], v[110:113], off nt
	v_cvt_pk_bf16_f32 v102, v102, v103
	v_cvt_pk_bf16_f32 v103, v104, v105
	v_cvt_pk_bf16_f32 v104, v94, v95
	v_add_u32_e32 v94, 32, v142
	v_ashrrev_i32_e32 v95, 31, v94
	v_lshlrev_b64 v[94:95], 13, v[94:95]
	v_cvt_pk_bf16_f32 v105, v96, v97
	global_store_dwordx4 v[118:119], v[102:105], off offset:256 nt
	s_mov_b32 s16, s8
	s_mov_b32 s14, s6
	v_lshl_add_u64 v[102:103], v[140:141], 0, v[94:95]
	v_cvt_pk_bf16_f32 v94, v106, v107
	v_cvt_pk_bf16_f32 v95, v108, v109
	v_cvt_pk_bf16_f32 v96, v98, v99
	v_cvt_pk_bf16_f32 v97, v100, v101
	global_store_dwordx4 v[102:103], v[94:97], off nt
	v_cvt_pk_bf16_f32 v86, v86, v87
	v_cvt_pk_bf16_f32 v87, v88, v89
	v_cvt_pk_bf16_f32 v88, v78, v79
	v_add_u32_e32 v78, 48, v142
	v_ashrrev_i32_e32 v79, 31, v78
	v_lshlrev_b64 v[78:79], 13, v[78:79]
	v_cvt_pk_bf16_f32 v89, v80, v81
	global_store_dwordx4 v[102:103], v[86:89], off offset:256 nt
	s_mov_b64 s[20:21], s[10:11]
	s_mov_b64 s[18:19], s[12:13]
	v_lshl_add_u64 v[86:87], v[140:141], 0, v[78:79]
	v_cvt_pk_bf16_f32 v78, v90, v91
	v_cvt_pk_bf16_f32 v79, v92, v93
	v_cvt_pk_bf16_f32 v80, v82, v83
	v_cvt_pk_bf16_f32 v81, v84, v85
	global_store_dwordx4 v[86:87], v[78:81], off nt
	v_cvt_pk_bf16_f32 v74, v74, v75
	v_cvt_pk_bf16_f32 v75, v76, v77
	v_cvt_pk_bf16_f32 v76, v70, v71
	v_add_u32_e32 v70, 0x80, v146
	v_ashrrev_i32_e32 v71, 11, v70
	v_and_b32_e32 v70, 0x7cf, v70
	v_mad_i32_i24 v70, v71, s7, v70
	v_ashrrev_i32_e32 v71, 31, v70
	v_cvt_pk_bf16_f32 v77, v72, v73
	v_lshlrev_b64 v[72:73], 13, v[70:71]
	global_store_dwordx4 v[86:87], v[74:77], off offset:256 nt
	v_lshl_add_u64 v[72:73], v[140:141], 0, v[72:73]
	v_cvt_pk_bf16_f32 v66, v66, v67
	v_cvt_pk_bf16_f32 v67, v68, v69
	v_cvt_pk_bf16_f32 v68, v62, v63
	v_cvt_pk_bf16_f32 v69, v64, v65
	global_store_dwordx4 v[72:73], v[66:69], off nt
	v_cvt_pk_bf16_f32 v54, v54, v55
	v_cvt_pk_bf16_f32 v55, v56, v57
	v_cvt_pk_bf16_f32 v56, v46, v47
	v_add_u32_e32 v46, 16, v70
	v_ashrrev_i32_e32 v47, 31, v46
	v_lshlrev_b64 v[46:47], 13, v[46:47]
	v_cvt_pk_bf16_f32 v57, v48, v49
	global_store_dwordx4 v[72:73], v[54:57], off offset:256 nt
	s_mov_b32 s51, 0x40c000
	s_mov_b32 s47, 0x120000
	v_lshl_add_u64 v[54:55], v[140:141], 0, v[46:47]
	v_cvt_pk_bf16_f32 v46, v58, v59
	v_cvt_pk_bf16_f32 v47, v60, v61
	v_cvt_pk_bf16_f32 v48, v50, v51
	v_cvt_pk_bf16_f32 v49, v52, v53
	global_store_dwordx4 v[54:55], v[46:49], off nt
	v_cvt_pk_bf16_f32 v38, v38, v39
	v_cvt_pk_bf16_f32 v39, v40, v41
	v_cvt_pk_bf16_f32 v40, v30, v31
	v_add_u32_e32 v30, 32, v70
	v_ashrrev_i32_e32 v31, 31, v30
	v_lshlrev_b64 v[30:31], 13, v[30:31]
	v_cvt_pk_bf16_f32 v41, v32, v33
	global_store_dwordx4 v[54:55], v[38:41], off offset:256 nt
	s_mov_b64 s[48:49], 0x7ffff
	s_nop 0
	v_lshl_add_u64 v[38:39], v[140:141], 0, v[30:31]
	v_cvt_pk_bf16_f32 v30, v42, v43
	v_cvt_pk_bf16_f32 v31, v44, v45
	v_cvt_pk_bf16_f32 v32, v34, v35
	v_cvt_pk_bf16_f32 v33, v36, v37
	global_store_dwordx4 v[38:39], v[30:33], off nt
	v_cvt_pk_bf16_f32 v22, v22, v23
	v_cvt_pk_bf16_f32 v23, v24, v25
	v_cvt_pk_bf16_f32 v24, v14, v15
	v_add_u32_e32 v14, 48, v70
	v_ashrrev_i32_e32 v15, 31, v14
	v_lshlrev_b64 v[14:15], 13, v[14:15]
	v_cvt_pk_bf16_f32 v25, v16, v17
	global_store_dwordx4 v[38:39], v[22:25], off offset:256 nt
	s_nop 1
	v_lshl_add_u64 v[22:23], v[140:141], 0, v[14:15]
	v_cvt_pk_bf16_f32 v14, v26, v27
	v_cvt_pk_bf16_f32 v15, v28, v29
	v_cvt_pk_bf16_f32 v16, v18, v19
	v_cvt_pk_bf16_f32 v17, v20, v21
	global_store_dwordx4 v[22:23], v[14:17], off nt
	v_cvt_pk_bf16_f32 v10, v10, v11
	v_cvt_pk_bf16_f32 v11, v12, v13
	v_cvt_pk_bf16_f32 v12, v6, v7
	v_cvt_pk_bf16_f32 v13, v8, v9
	global_store_dwordx4 v[22:23], v[10:13], off offset:256 nt
	s_cbranch_vccz .LBB0_529
	s_waitcnt vmcnt(0)
	s_cmpk_gt_u32 s28, 0xff
	s_cbranch_scc1 .LBB0_540
	s_barrier

.LBB0_924:
	s_add_u32 s48, s45, 0xffffff80
	s_addc_u32 s49, s46, -1
	s_cmp_eq_u32 s47, 60
	s_cselect_b32 s22, s9, s45
	s_cselect_b32 s23, s7, s46
	s_cselect_b32 s25, s11, s44
	s_cselect_b32 s24, s13, s33
	s_add_u32 s18, s22, 0x80
	s_addc_u32 s19, s23, 0
	s_add_u32 s20, s24, 0x80
	s_addc_u32 s21, s25, 0
	s_add_i32 s50, 0, 0x10000
	s_add_i32 s51, 0, 0x14000
	v_add_u32_e32 v90, s50, v1
	v_add_u32_e32 v162, s51, v1
	ds_read_b128 v[78:81], v90
	ds_read_b128 v[82:85], v90 offset:1024
	ds_read_b128 v[86:89], v90 offset:2048
	ds_read_b128 v[90:93], v90 offset:3072
	ds_read_b128 v[142:145], v162
	ds_read_b128 v[146:149], v162 offset:1024
	ds_read_b128 v[158:161], v162 offset:2048
	ds_read_b128 v[162:165], v162 offset:3072
	s_add_u32 s48, s48, 0x100000
	s_addc_u32 s49, s49, 0
	v_lshl_add_u64 v[198:199], s[48:49], 0, v[2:3]
	s_add_i32 m0, s35, 0xc000
	ds_read_b128 v[166:169], v5
	ds_read_b128 v[170:173], v5 offset:1024
	ds_read_b128 v[174:177], v5 offset:2048
	ds_read_b128 v[178:181], v5 offset:3072
	ds_read_b128 v[182:185], v5 offset:4096
	ds_read_b128 v[186:189], v5 offset:5120
	ds_read_b128 v[190:193], v5 offset:6144
	ds_read_b128 v[194:197], v5 offset:7168
	global_load_lds_dwordx4 v[198:199], off
	v_lshl_add_u64 v[198:199], s[48:49], 0, v[218:219]
	s_add_i32 m0, s35, 0xe000
	s_nop 0
	global_load_lds_dwordx4 v[198:199], off
	s_waitcnt vmcnt(8)
	s_waitcnt lgkmcnt(0)
	s_barrier
	s_setprio 1
	s_waitcnt lgkmcnt(0)
	v_mfma_f32_16x16x32_bf16 v[154:157], v[78:81], v[166:169], v[154:157]
	v_mfma_f32_16x16x32_bf16 v[150:153], v[86:89], v[166:169], v[150:153]
	v_mfma_f32_16x16x32_bf16 v[134:137], v[78:81], v[174:177], v[134:137]
	v_mfma_f32_16x16x32_bf16 v[126:129], v[86:89], v[174:177], v[126:129]
	v_mfma_f32_16x16x32_bf16 v[118:121], v[78:81], v[182:185], v[118:121]
	v_mfma_f32_16x16x32_bf16 v[110:113], v[86:89], v[182:185], v[110:113]
	v_mfma_f32_16x16x32_bf16 v[102:105], v[78:81], v[190:193], v[102:105]
	v_mfma_f32_16x16x32_bf16 v[94:97], v[86:89], v[190:193], v[94:97]
	v_mfma_f32_16x16x32_bf16 v[154:157], v[82:85], v[170:173], v[154:157]
	v_mfma_f32_16x16x32_bf16 v[150:153], v[90:93], v[170:173], v[150:153]
	v_mfma_f32_16x16x32_bf16 v[134:137], v[82:85], v[178:181], v[134:137]
	v_mfma_f32_16x16x32_bf16 v[126:129], v[90:93], v[178:181], v[126:129]
	v_mfma_f32_16x16x32_bf16 v[118:121], v[82:85], v[186:189], v[118:121]
	v_mfma_f32_16x16x32_bf16 v[110:113], v[90:93], v[186:189], v[110:113]
	v_mfma_f32_16x16x32_bf16 v[102:105], v[82:85], v[194:197], v[102:105]
	v_mfma_f32_16x16x32_bf16 v[94:97], v[90:93], v[194:197], v[94:97]
	v_mfma_f32_16x16x32_bf16 v[138:141], v[142:145], v[166:169], v[138:141]
	v_mfma_f32_16x16x32_bf16 v[130:133], v[158:161], v[166:169], v[130:133]
	v_mfma_f32_16x16x32_bf16 v[122:125], v[142:145], v[174:177], v[122:125]
	v_mfma_f32_16x16x32_bf16 v[114:117], v[158:161], v[174:177], v[114:117]
	v_mfma_f32_16x16x32_bf16 v[106:109], v[142:145], v[182:185], v[106:109]
	v_mfma_f32_16x16x32_bf16 v[98:101], v[158:161], v[182:185], v[98:101]
	v_mfma_f32_16x16x32_bf16 v[74:77], v[142:145], v[190:193], v[74:77]
	v_mfma_f32_16x16x32_bf16 v[70:73], v[158:161], v[190:193], v[70:73]
	v_mfma_f32_16x16x32_bf16 v[138:141], v[146:149], v[170:173], v[138:141]
	v_mfma_f32_16x16x32_bf16 v[130:133], v[162:165], v[170:173], v[130:133]
	v_mfma_f32_16x16x32_bf16 v[122:125], v[146:149], v[178:181], v[122:125]
	v_mfma_f32_16x16x32_bf16 v[114:117], v[162:165], v[178:181], v[114:117]
	v_mfma_f32_16x16x32_bf16 v[106:109], v[146:149], v[186:189], v[106:109]
	v_mfma_f32_16x16x32_bf16 v[98:101], v[162:165], v[186:189], v[98:101]
	v_mfma_f32_16x16x32_bf16 v[74:77], v[146:149], v[194:197], v[74:77]
	v_mfma_f32_16x16x32_bf16 v[70:73], v[162:165], v[194:197], v[70:73]
	s_setprio 0
	s_barrier
	s_add_i32 s48, s50, s29
	v_lshl_add_u64 v[198:199], s[24:25], 0, v[216:217]
	s_mov_b32 m0, s48
	ds_read_b128 v[166:169], v5 offset:16384
	ds_read_b128 v[170:173], v5 offset:17408
	ds_read_b128 v[174:177], v5 offset:18432
	ds_read_b128 v[178:181], v5 offset:19456
	ds_read_b128 v[182:185], v5 offset:20480
	ds_read_b128 v[186:189], v5 offset:21504
	ds_read_b128 v[190:193], v5 offset:22528
	ds_read_b128 v[194:197], v5 offset:23552
	global_load_lds_dwordx4 v[198:199], off
	s_add_i32 m0, s48, 0x2000
	v_lshl_add_u64 v[198:199], s[24:25], 0, v[220:221]
	s_add_u32 s24, s24, 0x100000
	s_addc_u32 s25, s25, 0
	s_add_i32 s48, s51, s29
	global_load_lds_dwordx4 v[198:199], off
	v_lshl_add_u64 v[198:199], s[24:25], 0, v[216:217]
	s_mov_b32 m0, s48
	s_nop 0
	global_load_lds_dwordx4 v[198:199], off
	v_lshl_add_u64 v[198:199], s[24:25], 0, v[220:221]
	s_add_i32 m0, s48, 0x2000
	s_nop 0
	global_load_lds_dwordx4 v[198:199], off
	v_lshl_add_u64 v[198:199], s[22:23], 0, v[2:3]
	s_mov_b32 m0, s35
	s_nop 0
	global_load_lds_dwordx4 v[198:199], off
	v_lshl_add_u64 v[198:199], s[22:23], 0, v[218:219]
	s_mov_b32 m0, s36
	s_nop 0
	global_load_lds_dwordx4 v[198:199], off
	s_waitcnt vmcnt(8)
	s_waitcnt lgkmcnt(0)
	s_barrier
	s_setprio 1
	s_waitcnt lgkmcnt(0)
	v_mfma_f32_16x16x32_bf16 v[66:69], v[78:81], v[166:169], v[66:69]
	v_mfma_f32_16x16x32_bf16 v[62:65], v[86:89], v[166:169], v[62:65]
	v_mfma_f32_16x16x32_bf16 v[54:57], v[78:81], v[174:177], v[54:57]
	v_mfma_f32_16x16x32_bf16 v[46:49], v[86:89], v[174:177], v[46:49]
	v_mfma_f32_16x16x32_bf16 v[38:41], v[78:81], v[182:185], v[38:41]
	v_mfma_f32_16x16x32_bf16 v[30:33], v[86:89], v[182:185], v[30:33]
	v_mfma_f32_16x16x32_bf16 v[22:25], v[78:81], v[190:193], v[22:25]
	v_mfma_f32_16x16x32_bf16 v[14:17], v[86:89], v[190:193], v[14:17]
	v_mfma_f32_16x16x32_bf16 v[66:69], v[82:85], v[170:173], v[66:69]
	v_mfma_f32_16x16x32_bf16 v[62:65], v[90:93], v[170:173], v[62:65]
	v_mfma_f32_16x16x32_bf16 v[54:57], v[82:85], v[178:181], v[54:57]
	v_mfma_f32_16x16x32_bf16 v[46:49], v[90:93], v[178:181], v[46:49]
	v_mfma_f32_16x16x32_bf16 v[38:41], v[82:85], v[186:189], v[38:41]
	v_mfma_f32_16x16x32_bf16 v[30:33], v[90:93], v[186:189], v[30:33]
	v_mfma_f32_16x16x32_bf16 v[22:25], v[82:85], v[194:197], v[22:25]
	v_mfma_f32_16x16x32_bf16 v[14:17], v[90:93], v[194:197], v[14:17]
	v_mfma_f32_16x16x32_bf16 v[58:61], v[142:145], v[166:169], v[58:61]
	v_mfma_f32_16x16x32_bf16 v[50:53], v[158:161], v[166:169], v[50:53]
	v_mfma_f32_16x16x32_bf16 v[42:45], v[142:145], v[174:177], v[42:45]
	v_mfma_f32_16x16x32_bf16 v[34:37], v[158:161], v[174:177], v[34:37]
	v_mfma_f32_16x16x32_bf16 v[26:29], v[142:145], v[182:185], v[26:29]
	v_mfma_f32_16x16x32_bf16 v[18:21], v[158:161], v[182:185], v[18:21]
	v_mfma_f32_16x16x32_bf16 v[10:13], v[142:145], v[190:193], v[10:13]
	v_mfma_f32_16x16x32_bf16 v[6:9], v[158:161], v[190:193], v[6:9]
	v_mfma_f32_16x16x32_bf16 v[58:61], v[146:149], v[170:173], v[58:61]
	v_mfma_f32_16x16x32_bf16 v[50:53], v[162:165], v[170:173], v[50:53]
	v_mfma_f32_16x16x32_bf16 v[42:45], v[146:149], v[178:181], v[42:45]
	v_mfma_f32_16x16x32_bf16 v[34:37], v[162:165], v[178:181], v[34:37]
	v_mfma_f32_16x16x32_bf16 v[26:29], v[146:149], v[186:189], v[26:29]
	v_mfma_f32_16x16x32_bf16 v[18:21], v[162:165], v[186:189], v[18:21]
	v_mfma_f32_16x16x32_bf16 v[10:13], v[146:149], v[194:197], v[10:13]
	v_mfma_f32_16x16x32_bf16 v[6:9], v[162:165], v[194:197], v[6:9]
	s_setprio 0
	s_barrier
	s_add_i32 s24, 0, 0x18000
	s_add_i32 s25, 0, 0x1c000
	v_add_u32_e32 v90, s24, v1
	v_add_u32_e32 v162, s25, v1
	ds_read_b128 v[78:81], v90
	ds_read_b128 v[82:85], v90 offset:1024
	ds_read_b128 v[86:89], v90 offset:2048
	ds_read_b128 v[90:93], v90 offset:3072
	ds_read_b128 v[142:145], v162
	ds_read_b128 v[146:149], v162 offset:1024
	ds_read_b128 v[158:161], v162 offset:2048
	ds_read_b128 v[162:165], v162 offset:3072
	s_add_u32 s22, s22, 0x100000
	s_addc_u32 s23, s23, 0
	s_mov_b32 m0, s37
	v_lshl_add_u64 v[198:199], s[22:23], 0, v[2:3]
	ds_read_b128 v[166:169], v5 offset:32768
	ds_read_b128 v[170:173], v5 offset:33792
	ds_read_b128 v[174:177], v5 offset:34816
	ds_read_b128 v[178:181], v5 offset:35840
	ds_read_b128 v[182:185], v5 offset:36864
	ds_read_b128 v[186:189], v5 offset:37888
	ds_read_b128 v[190:193], v5 offset:38912
	ds_read_b128 v[194:197], v5 offset:39936
	global_load_lds_dwordx4 v[198:199], off
	v_lshl_add_u64 v[198:199], s[22:23], 0, v[218:219]
	s_mov_b32 m0, s38
	s_nop 0
	global_load_lds_dwordx4 v[198:199], off
	s_waitcnt vmcnt(8)
	s_waitcnt lgkmcnt(0)
	s_barrier
	s_setprio 1
	s_waitcnt lgkmcnt(0)
	v_mfma_f32_16x16x32_bf16 v[154:157], v[78:81], v[166:169], v[154:157]
	v_mfma_f32_16x16x32_bf16 v[150:153], v[86:89], v[166:169], v[150:153]
	v_mfma_f32_16x16x32_bf16 v[134:137], v[78:81], v[174:177], v[134:137]
	v_mfma_f32_16x16x32_bf16 v[126:129], v[86:89], v[174:177], v[126:129]
	v_mfma_f32_16x16x32_bf16 v[118:121], v[78:81], v[182:185], v[118:121]
	v_mfma_f32_16x16x32_bf16 v[110:113], v[86:89], v[182:185], v[110:113]
	v_mfma_f32_16x16x32_bf16 v[102:105], v[78:81], v[190:193], v[102:105]
	v_mfma_f32_16x16x32_bf16 v[94:97], v[86:89], v[190:193], v[94:97]
	v_mfma_f32_16x16x32_bf16 v[154:157], v[82:85], v[170:173], v[154:157]
	v_mfma_f32_16x16x32_bf16 v[150:153], v[90:93], v[170:173], v[150:153]
	v_mfma_f32_16x16x32_bf16 v[134:137], v[82:85], v[178:181], v[134:137]
	v_mfma_f32_16x16x32_bf16 v[126:129], v[90:93], v[178:181], v[126:129]
	v_mfma_f32_16x16x32_bf16 v[118:121], v[82:85], v[186:189], v[118:121]
	v_mfma_f32_16x16x32_bf16 v[110:113], v[90:93], v[186:189], v[110:113]
	v_mfma_f32_16x16x32_bf16 v[102:105], v[82:85], v[194:197], v[102:105]
	v_mfma_f32_16x16x32_bf16 v[94:97], v[90:93], v[194:197], v[94:97]
	v_mfma_f32_16x16x32_bf16 v[138:141], v[142:145], v[166:169], v[138:141]
	v_mfma_f32_16x16x32_bf16 v[130:133], v[158:161], v[166:169], v[130:133]
	v_mfma_f32_16x16x32_bf16 v[122:125], v[142:145], v[174:177], v[122:125]
	v_mfma_f32_16x16x32_bf16 v[114:117], v[158:161], v[174:177], v[114:117]
	v_mfma_f32_16x16x32_bf16 v[106:109], v[142:145], v[182:185], v[106:109]
	v_mfma_f32_16x16x32_bf16 v[98:101], v[158:161], v[182:185], v[98:101]
	v_mfma_f32_16x16x32_bf16 v[74:77], v[142:145], v[190:193], v[74:77]
	v_mfma_f32_16x16x32_bf16 v[70:73], v[158:161], v[190:193], v[70:73]
	v_mfma_f32_16x16x32_bf16 v[138:141], v[146:149], v[170:173], v[138:141]
	v_mfma_f32_16x16x32_bf16 v[130:133], v[162:165], v[170:173], v[130:133]
	v_mfma_f32_16x16x32_bf16 v[122:125], v[146:149], v[178:181], v[122:125]
	v_mfma_f32_16x16x32_bf16 v[114:117], v[162:165], v[178:181], v[114:117]
	v_mfma_f32_16x16x32_bf16 v[106:109], v[146:149], v[186:189], v[106:109]
	v_mfma_f32_16x16x32_bf16 v[98:101], v[162:165], v[186:189], v[98:101]
	v_mfma_f32_16x16x32_bf16 v[74:77], v[146:149], v[194:197], v[74:77]
	v_mfma_f32_16x16x32_bf16 v[70:73], v[162:165], v[194:197], v[70:73]
	s_setprio 0
	s_barrier
	s_add_i32 s22, s24, s29
	v_lshl_add_u64 v[198:199], s[20:21], 0, v[216:217]
	s_mov_b32 m0, s22
	ds_read_b128 v[166:169], v5 offset:49152
	ds_read_b128 v[170:173], v5 offset:50176
	ds_read_b128 v[174:177], v5 offset:51200
	ds_read_b128 v[178:181], v5 offset:52224
	ds_read_b128 v[182:185], v5 offset:53248
	ds_read_b128 v[186:189], v5 offset:54272
	ds_read_b128 v[190:193], v5 offset:55296
	ds_read_b128 v[194:197], v5 offset:56320
	global_load_lds_dwordx4 v[198:199], off
	s_add_i32 m0, s22, 0x2000
	v_lshl_add_u64 v[198:199], s[20:21], 0, v[220:221]
	s_add_u32 s20, s20, 0x100000
	s_addc_u32 s21, s21, 0
	s_add_i32 s22, s25, s29
	global_load_lds_dwordx4 v[198:199], off
	v_lshl_add_u64 v[198:199], s[20:21], 0, v[216:217]
	s_mov_b32 m0, s22
	s_nop 0
	global_load_lds_dwordx4 v[198:199], off
	v_lshl_add_u64 v[198:199], s[20:21], 0, v[220:221]
	s_add_i32 m0, s22, 0x2000
	s_nop 0
	global_load_lds_dwordx4 v[198:199], off
	v_lshl_add_u64 v[198:199], s[18:19], 0, v[2:3]
	s_mov_b32 m0, s41
	s_nop 0
	global_load_lds_dwordx4 v[198:199], off
	v_lshl_add_u64 v[198:199], s[18:19], 0, v[218:219]
	s_mov_b32 m0, s42
	s_nop 0
	global_load_lds_dwordx4 v[198:199], off
	s_waitcnt vmcnt(8)
	s_waitcnt lgkmcnt(0)
	s_barrier
	s_setprio 1
	s_waitcnt lgkmcnt(0)
	v_mfma_f32_16x16x32_bf16 v[66:69], v[78:81], v[166:169], v[66:69]
	v_mfma_f32_16x16x32_bf16 v[62:65], v[86:89], v[166:169], v[62:65]
	v_mfma_f32_16x16x32_bf16 v[54:57], v[78:81], v[174:177], v[54:57]
	v_mfma_f32_16x16x32_bf16 v[46:49], v[86:89], v[174:177], v[46:49]
	v_mfma_f32_16x16x32_bf16 v[38:41], v[78:81], v[182:185], v[38:41]
	v_mfma_f32_16x16x32_bf16 v[30:33], v[86:89], v[182:185], v[30:33]
	v_mfma_f32_16x16x32_bf16 v[22:25], v[78:81], v[190:193], v[22:25]
	v_mfma_f32_16x16x32_bf16 v[14:17], v[86:89], v[190:193], v[14:17]
	v_mfma_f32_16x16x32_bf16 v[66:69], v[82:85], v[170:173], v[66:69]
	v_mfma_f32_16x16x32_bf16 v[62:65], v[90:93], v[170:173], v[62:65]
	v_mfma_f32_16x16x32_bf16 v[54:57], v[82:85], v[178:181], v[54:57]
	v_mfma_f32_16x16x32_bf16 v[46:49], v[90:93], v[178:181], v[46:49]
	v_mfma_f32_16x16x32_bf16 v[38:41], v[82:85], v[186:189], v[38:41]
	v_mfma_f32_16x16x32_bf16 v[30:33], v[90:93], v[186:189], v[30:33]
	v_mfma_f32_16x16x32_bf16 v[22:25], v[82:85], v[194:197], v[22:25]
	v_mfma_f32_16x16x32_bf16 v[14:17], v[90:93], v[194:197], v[14:17]
	v_mfma_f32_16x16x32_bf16 v[58:61], v[142:145], v[166:169], v[58:61]
	v_mfma_f32_16x16x32_bf16 v[50:53], v[158:161], v[166:169], v[50:53]
	v_mfma_f32_16x16x32_bf16 v[42:45], v[142:145], v[174:177], v[42:45]
	v_mfma_f32_16x16x32_bf16 v[34:37], v[158:161], v[174:177], v[34:37]
	v_mfma_f32_16x16x32_bf16 v[26:29], v[142:145], v[182:185], v[26:29]
	v_mfma_f32_16x16x32_bf16 v[18:21], v[158:161], v[182:185], v[18:21]
	v_mfma_f32_16x16x32_bf16 v[10:13], v[142:145], v[190:193], v[10:13]
	v_mfma_f32_16x16x32_bf16 v[6:9], v[158:161], v[190:193], v[6:9]
	v_mfma_f32_16x16x32_bf16 v[58:61], v[146:149], v[170:173], v[58:61]
	v_mfma_f32_16x16x32_bf16 v[50:53], v[162:165], v[170:173], v[50:53]
	v_mfma_f32_16x16x32_bf16 v[42:45], v[146:149], v[178:181], v[42:45]
	v_mfma_f32_16x16x32_bf16 v[34:37], v[162:165], v[178:181], v[34:37]
	v_mfma_f32_16x16x32_bf16 v[26:29], v[146:149], v[186:189], v[26:29]
	v_mfma_f32_16x16x32_bf16 v[18:21], v[162:165], v[186:189], v[18:21]
	v_mfma_f32_16x16x32_bf16 v[10:13], v[146:149], v[194:197], v[10:13]
	v_mfma_f32_16x16x32_bf16 v[6:9], v[162:165], v[194:197], v[6:9]
	s_setprio 0
	s_barrier
	s_add_i32 s47, s47, 2
	s_add_u32 s33, s33, 0x100
	s_addc_u32 s44, s44, 0
	s_add_u32 s45, s45, 0x100
	s_addc_u32 s46, s46, 0
	s_cmp_gt_u32 s47, 61
	s_cbranch_scc0 .LBB0_924
	v_mov_b32_e32 v142, v0
	s_mov_b64 s[20:21], s[84:85]
	s_add_u32 s7, s20, 0x4179c000
	v_readlane_b32 s18, v254, 26
	s_addc_u32 s9, s21, 0
	v_readlane_b32 s19, v254, 27
	v_readlane_b32 s44, v253, 35
	s_and_b64 s[18:19], s[18:19], exec
	v_readlane_b32 s45, v253, 36
	v_bfe_u32 v144, v142, 4, 2
	s_cselect_b32 s23, s9, s45
	s_cselect_b32 s22, s7, s44
	s_cselect_b32 s19, s83, s9
	s_cselect_b32 s18, s82, s7
	s_lshl_b32 s7, s8, 8
	s_lshl_b32 s6, s6, 8
	v_lshl_or_b32 v78, v144, 3, s7
	s_add_i32 s6, s6, s39
	v_or_b32_e32 v226, s40, v78
	v_ashrrev_i32_e32 v227, 31, v226
	v_readlane_b32 s8, v254, 9
	v_and_or_b32 v230, v142, 15, s6
	v_lshlrev_b64 v[244:245], 2, v[226:227]
	v_readlane_b32 s9, v254, 10
	v_lshl_add_u64 v[142:143], v[226:227], 1, s[20:21]
	s_mov_b64 s[6:7], 0x10f80000
	v_ashrrev_i32_e32 v231, 31, v230
	v_or_b32_e32 v240, 16, v230
	v_lshl_add_u64 v[82:83], s[8:9], 0, v[244:245]
	v_lshl_add_u64 v[228:229], s[22:23], 0, v[244:245]
	v_lshl_add_u64 v[224:225], v[142:143], 0, s[6:7]
	v_lshl_add_u64 v[142:143], v[230:231], 2, s[20:21]
	s_mov_b64 s[8:9], 0x18400
	v_lshlrev_b64 v[248:249], 14, v[230:231]
	v_ashrrev_i32_e32 v241, 31, v240
	v_or_b32_e32 v236, 32, v230
	v_or_b32_e32 v232, 48, v230
	v_lshl_add_u64 v[222:223], v[142:143], 0, s[8:9]
	v_lshl_add_u64 v[142:143], v[228:229], 0, v[248:249]
	v_lshlrev_b64 v[242:243], 14, v[240:241]
	v_ashrrev_i32_e32 v237, 31, v236
	v_ashrrev_i32_e32 v233, 31, v232
	global_load_dwordx4 v[86:89], v[82:83], off offset:16
	global_load_dwordx4 v[90:93], v[82:83], off
	global_load_dwordx4 v[78:81], v[82:83], off offset:528
	s_nop 0
	global_load_dwordx4 v[82:85], v[82:83], off offset:512
	s_nop 0
	global_load_dwordx4 v[206:209], v[142:143], off offset:16
	global_load_dwordx4 v[210:213], v[142:143], off
	global_load_dwordx4 v[198:201], v[142:143], off offset:528
	global_load_dwordx4 v[202:205], v[142:143], off offset:512
	v_lshl_add_u64 v[142:143], v[228:229], 0, v[242:243]
	v_lshlrev_b64 v[238:239], 14, v[236:237]
	v_lshlrev_b64 v[234:235], 14, v[232:233]
	global_load_dwordx4 v[190:193], v[142:143], off offset:16
	global_load_dwordx4 v[194:197], v[142:143], off
	global_load_dwordx4 v[182:185], v[142:143], off offset:528
	global_load_dwordx4 v[186:189], v[142:143], off offset:512
	v_lshl_add_u64 v[142:143], v[228:229], 0, v[238:239]
	v_lshl_add_u64 v[146:147], v[228:229], 0, v[234:235]
	v_cmp_eq_u32_e64 s[6:7], 0, v144
	global_load_dwordx4 v[174:177], v[142:143], off offset:16
	global_load_dwordx4 v[178:181], v[142:143], off
	global_load_dwordx4 v[166:169], v[142:143], off offset:528
	global_load_dwordx4 v[170:173], v[142:143], off offset:512
	global_load_dwordx4 v[158:161], v[146:147], off offset:16
	global_load_dwordx4 v[162:165], v[146:147], off
	s_nop 0
	global_load_dwordx4 v[142:145], v[146:147], off offset:528
	s_nop 0
	global_load_dwordx4 v[146:149], v[146:147], off offset:512
	v_lshl_add_u64 v[248:249], s[18:19], 0, v[248:249]
	v_lshl_add_u64 v[244:245], v[248:249], 0, v[244:245]
	s_mov_b64 s[20:21], -1
	s_andn2_b64 vcc, exec, s[60:61]
	v_readlane_b32 s46, v253, 37
	v_readlane_b32 s47, v253, 38
	v_readlane_b32 s48, v253, 39
	v_readlane_b32 s49, v253, 40
	v_readlane_b32 s50, v253, 41
	v_readlane_b32 s51, v253, 42
	v_readlane_b32 s52, v253, 43
	v_readlane_b32 s53, v253, 44
	v_readlane_b32 s54, v253, 45
	v_readlane_b32 s55, v253, 46
	v_readlane_b32 s56, v253, 47
	v_readlane_b32 s57, v253, 48
	v_readlane_b32 s58, v253, 49
	v_readlane_b32 s59, v253, 50
	s_waitcnt vmcnt(0)
	v_pk_add_f32 v[206:207], v[150:151], v[206:207]
	v_cndmask_b32_e64 v150, 0, 1, s[60:61]
	v_pk_add_f32 v[212:213], v[156:157], v[212:213]
	v_pk_add_f32 v[210:211], v[154:155], v[210:211]
	v_pk_add_f32 v[208:209], v[152:153], v[208:209]
	v_cmp_ne_u32_e64 s[8:9], 1, v150
	v_pk_add_f32 v[150:151], v[138:139], v[202:203]
	v_pk_add_f32 v[154:155], v[130:131], v[198:199]
	global_store_dwordx4 v[244:245], v[210:213], off
	global_store_dwordx4 v[244:245], v[206:209], off offset:16
	s_cbranch_vccnz .LBB0_929
	v_mul_f32_e32 v138, v211, v211
	v_mul_f32_e32 v139, v213, v213
	v_fmac_f32_e32 v138, v210, v210
	v_fmac_f32_e32 v139, v212, v212
	v_add_f32_e32 v138, v138, v139
	v_mul_f32_e32 v139, v207, v207
	v_fmac_f32_e32 v139, v206, v206
	v_add_f32_e32 v138, v138, v139
	v_mul_f32_e32 v139, v209, v209
	v_lshlrev_b64 v[130:131], 12, v[230:231]
	v_fmac_f32_e32 v139, v208, v208
	v_pk_mul_f32 v[152:153], v[90:91], v[210:211]
	v_pk_mul_f32 v[156:157], v[88:89], v[208:209]
	v_lshl_add_u64 v[130:131], v[130:131], 1, v[224:225]
	v_add_f32_e32 v231, v139, v138
	v_pk_mul_f32 v[138:139], v[92:93], v[212:213]
	v_pk_mul_f32 v[198:199], v[86:87], v[206:207]
	v_cvt_pk_bf16_f32 v206, v152, v153
	v_cvt_pk_bf16_f32 v207, v138, v139
	v_pk_add_f32 v[152:153], v[140:141], v[204:205]
	v_cvt_pk_bf16_f32 v208, v198, v199
	v_cvt_pk_bf16_f32 v209, v156, v157
	v_pk_add_f32 v[156:157], v[132:133], v[200:201]
	global_store_dwordx4 v[130:131], v[206:209], off
	global_store_dwordx4 v[244:245], v[150:153], off offset:512
	global_store_dwordx4 v[244:245], v[154:157], off offset:528
	v_pk_mul_f32 v[202:203], v[80:81], v[156:157]
	v_pk_mul_f32 v[138:139], v[84:85], v[152:153]
	v_mul_f32_e32 v157, v157, v157
	v_fmac_f32_e32 v157, v156, v156
	v_mul_f32_e32 v156, v151, v151
	v_mul_f32_e32 v153, v153, v153
	v_fmac_f32_e32 v156, v150, v150
	v_fmac_f32_e32 v153, v152, v152
	v_add_f32_e32 v152, v156, v153
	v_mul_f32_e32 v153, v155, v155
	v_fmac_f32_e32 v153, v154, v154
	v_add_f32_e32 v152, v152, v153
	v_add_f32_e32 v152, v157, v152
	v_add_f32_e32 v152, v231, v152
	ds_swizzle_b32 v153, v152 offset:swizzle(SWAP,16)
	v_pk_mul_f32 v[208:209], v[78:79], v[154:155]
	v_pk_mul_f32 v[198:199], v[82:83], v[150:151]
	s_nop 0
	v_cvt_pk_bf16_f32 v206, v198, v199
	v_cvt_pk_bf16_f32 v207, v138, v139
	v_cvt_pk_bf16_f32 v208, v208, v209
	v_cvt_pk_bf16_f32 v209, v202, v203
	global_store_dwordx4 v[130:131], v[206:209], off offset:256
	s_waitcnt lgkmcnt(0)
	v_add_f32_e32 v130, v152, v153
	v_mov_b32_e32 v131, v130
	s_nop 1
	v_permlane32_swap_b32_e32 v130, v131
	s_and_saveexec_b64 s[20:21], s[6:7]
	s_cbranch_execz .LBB0_928
	v_add_f32_e32 v130, v130, v131
	global_atomic_add_f32 v[222:223], v130, off
